# stack_i + setprio 0 delayed until after the ds_read block of each load segment
# speedup vs baseline: 1.0033x; 1.0033x over previous
;     __host__ __device__ bool next(int i, Unit& u) const { const int t = i / 3, b = i - 3 * t; Unit v; if (!StaticOrder::next(t, v)) return false; u.pm = v.pm; u.pn = 8 * b + v.pn; return true; }
; #define PG8_STAGE(bufoff, gbase, voff) do { const int so_ = (int)(unsigned)((const char*)(gbase) - base_##voff); _Pragma("unroll") for (int _i = 0; _i < 2; ++_i) \
;         __builtin_amdgcn_raw_ptr_buffer_load_lds(rs_##voff, (PG8_LAS unsigned*)(lds + (bufoff) + ldsw + _i * 8192), 16, (int)(voff)[_i], so_, 0, 0); } while (0)
; #define PG8_LDA(dst, b, h) do { _Pragma("unroll") for (int m = 0; m < 4; ++m) _Pragma("unroll") for (int k = 0; k < 2; ++k) dst[m][k] = *(const PG8_LAS bf16x8*)(lds + PG8_SA(b, h) + aoff + m * 2048 + k * 1024); } while (0)
; #define PG8_WAIT_V(n) asm volatile("s_waitcnt vmcnt(" #n ")" ::: "memory")
; #define PG8_WAIT_L(n) asm volatile("s_waitcnt lgkmcnt(" #n ")" ::: "memory")
; #define PG8_BAR __builtin_amdgcn_s_barrier()
; template <class Epi, class Sched, bool ALIGN_EPI = false, bool SP2 = false>
; __device__ __forceinline__ void gemm_phase(PG8_LAS unsigned char* lds, const Gemm g, const Sched& S, const Epi& E, int tid_in) {
;     ...
;         const bool has_next = S.next(ui + 1, nxt);
;         const char* nA = has_next ? (const char*)g.A + (size_t)nxt.pm * tstepA + (g.grp ? (size_t)(nxt.pn / g.grp) * g.agrp : (size_t)0) : cA; const char* nB = has_next ? (const char*)g.Bt + (size_t)nxt.pn * tstepB : cB;
;         for (int t = 0; t < nt; t += 2) {
;             const bool last = (t == nt - 2);
;             const char* a1 = cA + (size_t)(t + 1) * kstep;
;             const char* a2 = last ? nA : cA + (size_t)(t + 2) * kstep; const char* b2 = last ? nB : cB + (size_t)(t + 2) * kstep;
;             const char* a3 = a2 + kstep; const char* b3 = b2 + kstep;
;             if (last && has_next) S.a_ready(nxt);
;             if constexpr (SP2) {
;             PG8_LDB(B0, 0, 0); PG8_LDB(B1, 0, 1); PG8_SCHED; PG8_LDA(At, 0, 0); PG8_STAGE(PG8_SA(1, 1), a1 + hstepA, voffA);
;             PG8_WAIT_V(8); PG8_WAIT_L(0); PG8_BAR; PG8_MMA(0, 0, At, B0); PG8_MMA(0, 1, At, B1); PG8_BAR; PG8_SCHED;
;             PG8_LDA(At, 0, 1); PG8_STAGE(PG8_SB(0, 0), b2, voffB); PG8_STAGE(PG8_SB(0, 1), b2 + hstepB, voffB); PG8_STAGE(PG8_SA(0, 0), a2, voffA);
;             PG8_WAIT_V(8); PG8_WAIT_L(0); PG8_BAR; PG8_MMA(1, 0, At, B0); PG8_MMA(1, 1, At, B1); PG8_BAR; PG8_SCHED;
.LBB0_311:
	s_ashr_i32 s23, s22, 31
	s_lshl_b64 s[10:11], s[22:23], 20
	s_add_u32 s24, s4, s10
	s_addc_u32 s25, s26, s11
	s_and_b64 s[10:11], s[34:35], exec
	s_cselect_b32 s19, s24, s12
	s_ashr_i32 s15, s14, 31
	s_lshl_b64 s[10:11], s[14:15], 20
	s_add_u32 s10, s40, s10
	s_addc_u32 s11, s60, s11
	s_and_b64 s[20:21], s[34:35], exec
	s_cselect_b32 s15, s10, s16
	s_add_u32 s20, s16, 0x100
	v_mov_b32_e32 v2, 0
	s_addc_u32 s21, s17, 0
	s_mov_b32 s23, -2
	v_add_u32_e32 v0, 0x10000, v237
	ds_read_b128 v[130:133], v0
	ds_read_b128 v[134:137], v0 offset:1024
	ds_read_b128 v[138:141], v0 offset:2048
	ds_read_b128 v[142:145], v0 offset:3072
	v_add_u32_e32 v0, 0x14000, v237
	ds_read_b128 v[146:149], v0
	ds_read_b128 v[150:153], v0 offset:1024
	ds_read_b128 v[154:157], v0 offset:2048
	ds_read_b128 v[158:161], v0 offset:3072
	s_add_u32 s16, s12, 0x100
	s_addc_u32 s17, s13, 0
	s_sub_i32 s12, s12, s4
	s_add_i32 s12, s12, 0x80080
	s_sub_i32 s36, s12, 0x80000
	s_cmp_eq_u32 s23, 28
	s_cselect_b32 s13, s19, s16
	s_mov_b32 m0, s69
	ds_read_b128 v[162:165], v238
	ds_read_b128 v[166:169], v238 offset:1024
	ds_read_b128 v[170:173], v238 offset:2048
	ds_read_b128 v[174:177], v238 offset:3072
	ds_read_b128 v[178:181], v238 offset:4096
	ds_read_b128 v[182:185], v238 offset:5120
	ds_read_b128 v[186:189], v238 offset:6144
	ds_read_b128 v[190:193], v238 offset:7168
	s_mov_b32 m0, s78
	s_nop 0
	buffer_load_dwordx4 v211, s[4:7], s36 offen lds
	s_mov_b32 m0, s69
	s_nop 0
	buffer_load_dwordx4 v195, s[4:7], s12 offen lds
	s_mov_b32 m0, s67
	s_nop 0
	buffer_load_dwordx4 v211, s[4:7], s12 offen lds
	s_waitcnt vmcnt(8)
	s_waitcnt lgkmcnt(0)
	s_setprio 1
	s_barrier
	v_mfma_f32_16x16x32_bf16 v[126:129], v[130:133], v[162:165], 0
	v_mfma_f32_16x16x32_bf16 v[122:125], v[138:141], v[162:165], 0
	v_mfma_f32_16x16x32_bf16 v[106:109], v[138:141], v[170:173], 0
	v_mfma_f32_16x16x32_bf16 v[110:113], v[130:133], v[170:173], 0
	v_mfma_f32_16x16x32_bf16 v[94:97], v[130:133], v[178:181], 0
	v_mfma_f32_16x16x32_bf16 v[90:93], v[138:141], v[178:181], 0
	v_mfma_f32_16x16x32_bf16 v[74:77], v[138:141], v[186:189], 0
	v_mfma_f32_16x16x32_bf16 v[78:81], v[130:133], v[186:189], 0
	v_mfma_f32_16x16x32_bf16 v[126:129], v[134:137], v[166:169], v[126:129]
	v_mfma_f32_16x16x32_bf16 v[122:125], v[142:145], v[166:169], v[122:125]
	v_mfma_f32_16x16x32_bf16 v[106:109], v[142:145], v[174:177], v[106:109]
	v_mfma_f32_16x16x32_bf16 v[110:113], v[134:137], v[174:177], v[110:113]
	v_mfma_f32_16x16x32_bf16 v[94:97], v[134:137], v[182:185], v[94:97]
	v_mfma_f32_16x16x32_bf16 v[90:93], v[142:145], v[182:185], v[90:93]
	v_mfma_f32_16x16x32_bf16 v[74:77], v[142:145], v[190:193], v[74:77]
	v_mfma_f32_16x16x32_bf16 v[78:81], v[134:137], v[190:193], v[78:81]
	v_mfma_f32_16x16x32_bf16 v[118:121], v[146:149], v[162:165], 0
	v_mfma_f32_16x16x32_bf16 v[114:117], v[154:157], v[162:165], 0
	v_mfma_f32_16x16x32_bf16 v[98:101], v[154:157], v[170:173], 0
	v_mfma_f32_16x16x32_bf16 v[102:105], v[146:149], v[170:173], 0
	v_mfma_f32_16x16x32_bf16 v[86:89], v[146:149], v[178:181], 0
	v_mfma_f32_16x16x32_bf16 v[82:85], v[154:157], v[178:181], 0
	v_mfma_f32_16x16x32_bf16 v[66:69], v[154:157], v[186:189], 0
	v_mfma_f32_16x16x32_bf16 v[70:73], v[146:149], v[186:189], 0
	v_mfma_f32_16x16x32_bf16 v[118:121], v[150:153], v[166:169], v[118:121]
	v_mfma_f32_16x16x32_bf16 v[114:117], v[158:161], v[166:169], v[114:117]
	v_mfma_f32_16x16x32_bf16 v[98:101], v[158:161], v[174:177], v[98:101]
	v_mfma_f32_16x16x32_bf16 v[102:105], v[150:153], v[174:177], v[102:105]
	v_mfma_f32_16x16x32_bf16 v[86:89], v[150:153], v[182:185], v[86:89]
	v_mfma_f32_16x16x32_bf16 v[82:85], v[158:161], v[182:185], v[82:85]
	v_mfma_f32_16x16x32_bf16 v[66:69], v[158:161], v[190:193], v[66:69]
	v_mfma_f32_16x16x32_bf16 v[70:73], v[150:153], v[190:193], v[70:73]
	s_barrier
	s_cselect_b32 s12, s15, s20
	s_mov_b32 m0, s61
	s_mov_b32 s42, s6
	s_mov_b32 s43, s7
	s_sub_i32 s12, s12, s40
	ds_read_b128 v[162:165], v238 offset:16384
	ds_read_b128 v[166:169], v238 offset:17408
	ds_read_b128 v[170:173], v238 offset:18432
	ds_read_b128 v[174:177], v238 offset:19456
	ds_read_b128 v[178:181], v238 offset:20480
	ds_read_b128 v[182:185], v238 offset:21504
	ds_read_b128 v[186:189], v238 offset:22528
	ds_read_b128 v[190:193], v238 offset:23552
	s_setprio 0
	buffer_load_dwordx4 v207, s[40:43], s12 offen lds
	s_mov_b32 m0, s62
	s_add_i32 s36, s12, 0x80000
	buffer_load_dwordx4 v224, s[40:43], s12 offen lds
	s_mov_b32 m0, s63
	s_sub_i32 s13, s13, s4
	buffer_load_dwordx4 v207, s[40:43], s36 offen lds
	s_mov_b32 m0, s71
	s_nop 0
	buffer_load_dwordx4 v224, s[40:43], s36 offen lds
	s_mov_b32 m0, s53
	s_nop 0
	buffer_load_dwordx4 v195, s[4:7], s13 offen lds
	s_waitcnt vmcnt(7)
	s_waitcnt lgkmcnt(0)
	s_setprio 1
	s_barrier
; #define PG8_STAGE(bufoff, gbase, voff) do { const int so_ = (int)(unsigned)((const char*)(gbase) - base_##voff); _Pragma("unroll") for (int _i = 0; _i < 2; ++_i) \
;         __builtin_amdgcn_raw_ptr_buffer_load_lds(rs_##voff, (PG8_LAS unsigned*)(lds + (bufoff) + ldsw + _i * 8192), 16, (int)(voff)[_i], so_, 0, 0); } while (0)
; #define PG8_LDA(dst, b, h) do { _Pragma("unroll") for (int m = 0; m < 4; ++m) _Pragma("unroll") for (int k = 0; k < 2; ++k) dst[m][k] = *(const PG8_LAS bf16x8*)(lds + PG8_SA(b, h) + aoff + m * 2048 + k * 1024); } while (0)
; #define PG8_LDB(dst, b, h) do { _Pragma("unroll") for (int n = 0; n < 2; ++n) _Pragma("unroll") for (int k = 0; k < 2; ++k) dst[n][k] = *(const PG8_LAS bf16x8*)(lds + PG8_SB(b, h) + boff + n * 2048 + k * 1024); } while (0)
; #define PG8_MMA(ai, bj, At, Bt) do { __builtin_amdgcn_s_setprio(1); _Pragma("unroll") for (int m = 0; m < 4; ++m) _Pragma("unroll") for (int n = 0; n < 2; ++n) _Pragma("unroll") for (int k = 0; k < 2; ++k) \
;         acc[ai][bj][m][n] = __builtin_amdgcn_mfma_f32_16x16x32_bf16(Bt[n][k], At[m][k], acc[ai][bj][m][n], 0, 0, 0); __builtin_amdgcn_s_setprio(0); } while (0)
; #define PG8_WAIT_V(n) asm volatile("s_waitcnt vmcnt(" #n ")" ::: "memory")
; #define PG8_WAIT_L(n) asm volatile("s_waitcnt lgkmcnt(" #n ")" ::: "memory")
; #define PG8_BAR __builtin_amdgcn_s_barrier()
; #define PG8_SCHED __builtin_amdgcn_sched_barrier(0)
; template <class Epi, class Sched, bool ALIGN_EPI = false, bool SP2 = false>
; __device__ __forceinline__ void gemm_phase(PG8_LAS unsigned char* lds, const Gemm g, const Sched& S, const Epi& E, int tid_in) {
;     ...
;             PG8_LDA(At, 0, 1); PG8_STAGE(PG8_SB(0, 0), b2, voffB); PG8_STAGE(PG8_SB(0, 1), b2 + hstepB, voffB); PG8_STAGE(PG8_SA(0, 0), a2, voffA);
;             PG8_WAIT_V(8); PG8_WAIT_L(0); PG8_BAR; PG8_MMA(1, 0, At, B0); PG8_MMA(1, 1, At, B1); PG8_BAR; PG8_SCHED;
;             PG8_LDB(B0, 1, 0); PG8_LDB(B1, 1, 1); PG8_SCHED; PG8_LDA(At, 1, 0); PG8_STAGE(PG8_SA(0, 1), a2 + hstepA, voffA);
;             PG8_WAIT_V(8); PG8_WAIT_L(0); PG8_BAR; PG8_MMA(0, 0, At, B0); PG8_MMA(0, 1, At, B1); PG8_BAR; PG8_SCHED;
	v_mfma_f32_16x16x32_bf16 v[62:65], v[130:133], v[162:165], 0
	v_mfma_f32_16x16x32_bf16 v[58:61], v[138:141], v[162:165], 0
	v_mfma_f32_16x16x32_bf16 v[42:45], v[138:141], v[170:173], 0
	v_mfma_f32_16x16x32_bf16 v[46:49], v[130:133], v[170:173], 0
	v_mfma_f32_16x16x32_bf16 v[30:33], v[130:133], v[178:181], 0
	v_mfma_f32_16x16x32_bf16 v[26:29], v[138:141], v[178:181], 0
	v_mfma_f32_16x16x32_bf16 v[10:13], v[138:141], v[186:189], 0
	v_mfma_f32_16x16x32_bf16 v[14:17], v[130:133], v[186:189], 0
	v_mfma_f32_16x16x32_bf16 v[62:65], v[134:137], v[166:169], v[62:65]
	v_mfma_f32_16x16x32_bf16 v[58:61], v[142:145], v[166:169], v[58:61]
	v_mfma_f32_16x16x32_bf16 v[42:45], v[142:145], v[174:177], v[42:45]
	v_mfma_f32_16x16x32_bf16 v[46:49], v[134:137], v[174:177], v[46:49]
	v_mfma_f32_16x16x32_bf16 v[30:33], v[134:137], v[182:185], v[30:33]
	v_mfma_f32_16x16x32_bf16 v[26:29], v[142:145], v[182:185], v[26:29]
	v_mfma_f32_16x16x32_bf16 v[10:13], v[142:145], v[190:193], v[10:13]
	v_mfma_f32_16x16x32_bf16 v[14:17], v[134:137], v[190:193], v[14:17]
	v_mfma_f32_16x16x32_bf16 v[54:57], v[146:149], v[162:165], 0
	v_mfma_f32_16x16x32_bf16 v[50:53], v[154:157], v[162:165], 0
	v_mfma_f32_16x16x32_bf16 v[34:37], v[154:157], v[170:173], 0
	v_mfma_f32_16x16x32_bf16 v[38:41], v[146:149], v[170:173], 0
	v_mfma_f32_16x16x32_bf16 v[22:25], v[146:149], v[178:181], 0
	v_mfma_f32_16x16x32_bf16 v[18:21], v[154:157], v[178:181], 0
	v_mfma_f32_16x16x32_bf16 v[2:5], v[154:157], v[186:189], 0
	v_mfma_f32_16x16x32_bf16 v[6:9], v[146:149], v[186:189], 0
	v_mfma_f32_16x16x32_bf16 v[54:57], v[150:153], v[166:169], v[54:57]
	v_mfma_f32_16x16x32_bf16 v[50:53], v[158:161], v[166:169], v[50:53]
	v_mfma_f32_16x16x32_bf16 v[34:37], v[158:161], v[174:177], v[34:37]
	v_mfma_f32_16x16x32_bf16 v[38:41], v[150:153], v[174:177], v[38:41]
	v_mfma_f32_16x16x32_bf16 v[22:25], v[150:153], v[182:185], v[22:25]
	v_mfma_f32_16x16x32_bf16 v[18:21], v[158:161], v[182:185], v[18:21]
	v_mfma_f32_16x16x32_bf16 v[2:5], v[158:161], v[190:193], v[2:5]
	v_mfma_f32_16x16x32_bf16 v[6:9], v[150:153], v[190:193], v[6:9]
	s_barrier
	v_add_u32_e32 v0, 0x18000, v237
	ds_read_b128 v[130:133], v0
	ds_read_b128 v[134:137], v0 offset:1024
	ds_read_b128 v[138:141], v0 offset:2048
	ds_read_b128 v[142:145], v0 offset:3072
	v_add_u32_e32 v0, 0x1c000, v237
	ds_read_b128 v[146:149], v0
	ds_read_b128 v[150:153], v0 offset:1024
	ds_read_b128 v[154:157], v0 offset:2048
	ds_read_b128 v[158:161], v0 offset:3072
	s_add_i32 s36, s13, 0x80000
	s_mov_b32 m0, s73
	ds_read_b128 v[162:165], v238 offset:32768
	ds_read_b128 v[166:169], v238 offset:33792
	ds_read_b128 v[170:173], v238 offset:34816
	ds_read_b128 v[174:177], v238 offset:35840
	ds_read_b128 v[178:181], v238 offset:36864
	ds_read_b128 v[182:185], v238 offset:37888
	ds_read_b128 v[186:189], v238 offset:38912
	ds_read_b128 v[190:193], v238 offset:39936
	s_setprio 0
	s_mov_b32 m0, s72
	s_nop 0
	buffer_load_dwordx4 v211, s[4:7], s13 offen lds
	s_mov_b32 m0, s73
	s_nop 0
	buffer_load_dwordx4 v195, s[4:7], s36 offen lds
	s_mov_b32 m0, s74
	s_nop 0
	buffer_load_dwordx4 v211, s[4:7], s36 offen lds
	s_waitcnt vmcnt(8)
	s_waitcnt lgkmcnt(0)
	s_setprio 1
	s_barrier
	v_mfma_f32_16x16x32_bf16 v[126:129], v[130:133], v[162:165], v[126:129]
	v_mfma_f32_16x16x32_bf16 v[122:125], v[138:141], v[162:165], v[122:125]
	v_mfma_f32_16x16x32_bf16 v[106:109], v[138:141], v[170:173], v[106:109]
	v_mfma_f32_16x16x32_bf16 v[110:113], v[130:133], v[170:173], v[110:113]
	v_mfma_f32_16x16x32_bf16 v[94:97], v[130:133], v[178:181], v[94:97]
	v_mfma_f32_16x16x32_bf16 v[90:93], v[138:141], v[178:181], v[90:93]
	v_mfma_f32_16x16x32_bf16 v[74:77], v[138:141], v[186:189], v[74:77]
	v_mfma_f32_16x16x32_bf16 v[78:81], v[130:133], v[186:189], v[78:81]
	v_mfma_f32_16x16x32_bf16 v[126:129], v[134:137], v[166:169], v[126:129]
	v_mfma_f32_16x16x32_bf16 v[122:125], v[142:145], v[166:169], v[122:125]
	v_mfma_f32_16x16x32_bf16 v[106:109], v[142:145], v[174:177], v[106:109]
	v_mfma_f32_16x16x32_bf16 v[110:113], v[134:137], v[174:177], v[110:113]
	v_mfma_f32_16x16x32_bf16 v[94:97], v[134:137], v[182:185], v[94:97]
	v_mfma_f32_16x16x32_bf16 v[90:93], v[142:145], v[182:185], v[90:93]
	v_mfma_f32_16x16x32_bf16 v[74:77], v[142:145], v[190:193], v[74:77]
	v_mfma_f32_16x16x32_bf16 v[78:81], v[134:137], v[190:193], v[78:81]
	v_mfma_f32_16x16x32_bf16 v[118:121], v[146:149], v[162:165], v[118:121]
	v_mfma_f32_16x16x32_bf16 v[114:117], v[154:157], v[162:165], v[114:117]
	v_mfma_f32_16x16x32_bf16 v[98:101], v[154:157], v[170:173], v[98:101]
	v_mfma_f32_16x16x32_bf16 v[102:105], v[146:149], v[170:173], v[102:105]
	v_mfma_f32_16x16x32_bf16 v[86:89], v[146:149], v[178:181], v[86:89]
	v_mfma_f32_16x16x32_bf16 v[82:85], v[154:157], v[178:181], v[82:85]
	v_mfma_f32_16x16x32_bf16 v[66:69], v[154:157], v[186:189], v[66:69]
	v_mfma_f32_16x16x32_bf16 v[70:73], v[146:149], v[186:189], v[70:73]
	v_mfma_f32_16x16x32_bf16 v[118:121], v[150:153], v[166:169], v[118:121]
	v_mfma_f32_16x16x32_bf16 v[114:117], v[158:161], v[166:169], v[114:117]
	v_mfma_f32_16x16x32_bf16 v[98:101], v[158:161], v[174:177], v[98:101]
	v_mfma_f32_16x16x32_bf16 v[102:105], v[150:153], v[174:177], v[102:105]
	v_mfma_f32_16x16x32_bf16 v[86:89], v[150:153], v[182:185], v[86:89]
	v_mfma_f32_16x16x32_bf16 v[82:85], v[158:161], v[182:185], v[82:85]
	v_mfma_f32_16x16x32_bf16 v[66:69], v[158:161], v[190:193], v[66:69]
	v_mfma_f32_16x16x32_bf16 v[70:73], v[150:153], v[190:193], v[70:73]
	s_barrier
; #define PG8_STAGE(bufoff, gbase, voff) do { const int so_ = (int)(unsigned)((const char*)(gbase) - base_##voff); _Pragma("unroll") for (int _i = 0; _i < 2; ++_i) \
;         __builtin_amdgcn_raw_ptr_buffer_load_lds(rs_##voff, (PG8_LAS unsigned*)(lds + (bufoff) + ldsw + _i * 8192), 16, (int)(voff)[_i], so_, 0, 0); } while (0)
; #define PG8_LDA(dst, b, h) do { _Pragma("unroll") for (int m = 0; m < 4; ++m) _Pragma("unroll") for (int k = 0; k < 2; ++k) dst[m][k] = *(const PG8_LAS bf16x8*)(lds + PG8_SA(b, h) + aoff + m * 2048 + k * 1024); } while (0)
; #define PG8_LDB(dst, b, h) do { _Pragma("unroll") for (int n = 0; n < 2; ++n) _Pragma("unroll") for (int k = 0; k < 2; ++k) dst[n][k] = *(const PG8_LAS bf16x8*)(lds + PG8_SB(b, h) + boff + n * 2048 + k * 1024); } while (0)
; #define PG8_MMA(ai, bj, At, Bt) do { __builtin_amdgcn_s_setprio(1); _Pragma("unroll") for (int m = 0; m < 4; ++m) _Pragma("unroll") for (int n = 0; n < 2; ++n) _Pragma("unroll") for (int k = 0; k < 2; ++k) \
;         acc[ai][bj][m][n] = __builtin_amdgcn_mfma_f32_16x16x32_bf16(Bt[n][k], At[m][k], acc[ai][bj][m][n], 0, 0, 0); __builtin_amdgcn_s_setprio(0); } while (0)
; template <class Epi, class Sched, bool ALIGN_EPI = false, bool SP2 = false>
; __device__ __forceinline__ void gemm_phase(PG8_LAS unsigned char* lds, const Gemm g, const Sched& S, const Epi& E, int tid_in) {
;     ...
;             PG8_LDB(B0, 0, 0); PG8_LDB(B1, 0, 1); PG8_SCHED; PG8_LDA(At, 0, 0); PG8_STAGE(PG8_SA(1, 1), a1 + hstepA, voffA);
;             PG8_WAIT_V(8); PG8_WAIT_L(0); PG8_BAR; PG8_MMA(0, 0, At, B0); PG8_MMA(0, 1, At, B1); PG8_BAR; PG8_SCHED;
;             PG8_LDA(At, 0, 1); PG8_STAGE(PG8_SB(0, 0), b2, voffB); PG8_STAGE(PG8_SB(0, 1), b2 + hstepB, voffB); PG8_STAGE(PG8_SA(0, 0), a2, voffA);
;             PG8_WAIT_V(8); PG8_WAIT_L(0); PG8_BAR; PG8_MMA(1, 0, At, B0); PG8_MMA(1, 1, At, B1); PG8_BAR; PG8_SCHED;
;             PG8_LDB(B0, 1, 0); PG8_LDB(B1, 1, 1); PG8_SCHED; PG8_LDA(At, 1, 0); PG8_STAGE(PG8_SA(0, 1), a2 + hstepA, voffA);
;             PG8_WAIT_V(8); PG8_WAIT_L(0); PG8_BAR; PG8_MMA(0, 0, At, B0); PG8_MMA(0, 1, At, B1); PG8_BAR; PG8_SCHED;
;             PG8_LDA(At, 1, 1); PG8_STAGE(PG8_SB(1, 0), b3, voffB); PG8_STAGE(PG8_SB(1, 1), b3 + hstepB, voffB); PG8_STAGE(PG8_SA(1, 0), a3, voffA);
;             PG8_WAIT_V(8); PG8_WAIT_L(0); PG8_BAR; PG8_MMA(1, 0, At, B0); PG8_MMA(1, 1, At, B1); PG8_BAR; PG8_SCHED;
	s_mov_b32 m0, s75
	s_add_i32 s36, s12, 0x80
	ds_read_b128 v[162:165], v238 offset:49152
	ds_read_b128 v[166:169], v238 offset:50176
	ds_read_b128 v[170:173], v238 offset:51200
	ds_read_b128 v[174:177], v238 offset:52224
	ds_read_b128 v[178:181], v238 offset:53248
	ds_read_b128 v[182:185], v238 offset:54272
	ds_read_b128 v[186:189], v238 offset:55296
	ds_read_b128 v[190:193], v238 offset:56320
	s_setprio 0
	buffer_load_dwordx4 v207, s[40:43], s36 offen lds
	s_mov_b32 m0, s76
	s_add_i32 s12, s12, 0x80080
	buffer_load_dwordx4 v224, s[40:43], s36 offen lds
	s_mov_b32 m0, s79
	s_addk_i32 s13, 0x80
	buffer_load_dwordx4 v207, s[40:43], s12 offen lds
	s_mov_b32 m0, s68
	s_nop 0
	buffer_load_dwordx4 v224, s[40:43], s12 offen lds
	s_mov_b32 m0, s77
	s_nop 0
	buffer_load_dwordx4 v195, s[4:7], s13 offen lds
	s_waitcnt vmcnt(7)
	s_waitcnt lgkmcnt(0)
	s_setprio 1
	s_barrier
	v_mfma_f32_16x16x32_bf16 v[62:65], v[130:133], v[162:165], v[62:65]
	v_mfma_f32_16x16x32_bf16 v[58:61], v[138:141], v[162:165], v[58:61]
	v_mfma_f32_16x16x32_bf16 v[42:45], v[138:141], v[170:173], v[42:45]
	v_mfma_f32_16x16x32_bf16 v[46:49], v[130:133], v[170:173], v[46:49]
	v_mfma_f32_16x16x32_bf16 v[30:33], v[130:133], v[178:181], v[30:33]
	v_mfma_f32_16x16x32_bf16 v[26:29], v[138:141], v[178:181], v[26:29]
	v_mfma_f32_16x16x32_bf16 v[10:13], v[138:141], v[186:189], v[10:13]
	v_mfma_f32_16x16x32_bf16 v[14:17], v[130:133], v[186:189], v[14:17]
	v_mfma_f32_16x16x32_bf16 v[62:65], v[134:137], v[166:169], v[62:65]
	v_mfma_f32_16x16x32_bf16 v[58:61], v[142:145], v[166:169], v[58:61]
	v_mfma_f32_16x16x32_bf16 v[42:45], v[142:145], v[174:177], v[42:45]
	v_mfma_f32_16x16x32_bf16 v[46:49], v[134:137], v[174:177], v[46:49]
	v_mfma_f32_16x16x32_bf16 v[30:33], v[134:137], v[182:185], v[30:33]
	v_mfma_f32_16x16x32_bf16 v[26:29], v[142:145], v[182:185], v[26:29]
	v_mfma_f32_16x16x32_bf16 v[10:13], v[142:145], v[190:193], v[10:13]
	v_mfma_f32_16x16x32_bf16 v[14:17], v[134:137], v[190:193], v[14:17]
	v_mfma_f32_16x16x32_bf16 v[54:57], v[146:149], v[162:165], v[54:57]
	v_mfma_f32_16x16x32_bf16 v[50:53], v[154:157], v[162:165], v[50:53]
	v_mfma_f32_16x16x32_bf16 v[34:37], v[154:157], v[170:173], v[34:37]
	v_mfma_f32_16x16x32_bf16 v[38:41], v[146:149], v[170:173], v[38:41]
	v_mfma_f32_16x16x32_bf16 v[22:25], v[146:149], v[178:181], v[22:25]
	v_mfma_f32_16x16x32_bf16 v[18:21], v[154:157], v[178:181], v[18:21]
	v_mfma_f32_16x16x32_bf16 v[2:5], v[154:157], v[186:189], v[2:5]
	v_mfma_f32_16x16x32_bf16 v[6:9], v[146:149], v[186:189], v[6:9]
	v_mfma_f32_16x16x32_bf16 v[54:57], v[150:153], v[166:169], v[54:57]
	v_mfma_f32_16x16x32_bf16 v[50:53], v[158:161], v[166:169], v[50:53]
	v_mfma_f32_16x16x32_bf16 v[34:37], v[158:161], v[174:177], v[34:37]
	v_mfma_f32_16x16x32_bf16 v[38:41], v[150:153], v[174:177], v[38:41]
	v_mfma_f32_16x16x32_bf16 v[22:25], v[150:153], v[182:185], v[22:25]
	v_mfma_f32_16x16x32_bf16 v[18:21], v[158:161], v[182:185], v[18:21]
	v_mfma_f32_16x16x32_bf16 v[2:5], v[158:161], v[190:193], v[2:5]
	v_mfma_f32_16x16x32_bf16 v[6:9], v[150:153], v[190:193], v[6:9]
	s_barrier
	s_setprio 0
	s_add_i32 s23, s23, 2
	s_add_u32 s20, s20, 0x100
	s_addc_u32 s21, s21, 0
	s_cmp_gt_u32 s23, 29
	s_mov_b64 s[12:13], s[16:17]
.LBB0_312:
	v_add_u32_e32 v0, 0x10000, v237
	ds_read_b128 v[130:133], v0
	ds_read_b128 v[134:137], v0 offset:1024
	ds_read_b128 v[138:141], v0 offset:2048
	ds_read_b128 v[142:145], v0 offset:3072
	v_add_u32_e32 v0, 0x14000, v237
	ds_read_b128 v[146:149], v0
	ds_read_b128 v[150:153], v0 offset:1024
	ds_read_b128 v[154:157], v0 offset:2048
	ds_read_b128 v[158:161], v0 offset:3072
	s_add_u32 s16, s12, 0x100
	s_addc_u32 s17, s13, 0
	s_sub_i32 s12, s12, s4
	s_add_i32 s12, s12, 0x80080
	s_sub_i32 s36, s12, 0x80000
	s_cmp_eq_u32 s23, 28
	s_cselect_b32 s13, s19, s16
	s_mov_b32 m0, s69
	ds_read_b128 v[162:165], v238
	ds_read_b128 v[166:169], v238 offset:1024
	ds_read_b128 v[170:173], v238 offset:2048
	ds_read_b128 v[174:177], v238 offset:3072
	ds_read_b128 v[178:181], v238 offset:4096
	ds_read_b128 v[182:185], v238 offset:5120
	ds_read_b128 v[186:189], v238 offset:6144
	ds_read_b128 v[190:193], v238 offset:7168
	s_mov_b32 m0, s78
	s_nop 0
	buffer_load_dwordx4 v211, s[4:7], s36 offen lds
	s_mov_b32 m0, s69
	s_nop 0
	buffer_load_dwordx4 v195, s[4:7], s12 offen lds
	s_mov_b32 m0, s67
	s_nop 0
	buffer_load_dwordx4 v211, s[4:7], s12 offen lds
	s_waitcnt vmcnt(8)
	s_waitcnt lgkmcnt(0)
	s_setprio 1
	s_barrier
	v_mfma_f32_16x16x32_bf16 v[126:129], v[130:133], v[162:165], v[126:129]
	v_mfma_f32_16x16x32_bf16 v[122:125], v[138:141], v[162:165], v[122:125]
	v_mfma_f32_16x16x32_bf16 v[106:109], v[138:141], v[170:173], v[106:109]
	v_mfma_f32_16x16x32_bf16 v[110:113], v[130:133], v[170:173], v[110:113]
	v_mfma_f32_16x16x32_bf16 v[94:97], v[130:133], v[178:181], v[94:97]
	v_mfma_f32_16x16x32_bf16 v[90:93], v[138:141], v[178:181], v[90:93]
	v_mfma_f32_16x16x32_bf16 v[74:77], v[138:141], v[186:189], v[74:77]
	v_mfma_f32_16x16x32_bf16 v[78:81], v[130:133], v[186:189], v[78:81]
	v_mfma_f32_16x16x32_bf16 v[126:129], v[134:137], v[166:169], v[126:129]
	v_mfma_f32_16x16x32_bf16 v[122:125], v[142:145], v[166:169], v[122:125]
	v_mfma_f32_16x16x32_bf16 v[106:109], v[142:145], v[174:177], v[106:109]
	v_mfma_f32_16x16x32_bf16 v[110:113], v[134:137], v[174:177], v[110:113]
	v_mfma_f32_16x16x32_bf16 v[94:97], v[134:137], v[182:185], v[94:97]
	v_mfma_f32_16x16x32_bf16 v[90:93], v[142:145], v[182:185], v[90:93]
	v_mfma_f32_16x16x32_bf16 v[74:77], v[142:145], v[190:193], v[74:77]
	v_mfma_f32_16x16x32_bf16 v[78:81], v[134:137], v[190:193], v[78:81]
	v_mfma_f32_16x16x32_bf16 v[118:121], v[146:149], v[162:165], v[118:121]
	v_mfma_f32_16x16x32_bf16 v[114:117], v[154:157], v[162:165], v[114:117]
	v_mfma_f32_16x16x32_bf16 v[98:101], v[154:157], v[170:173], v[98:101]
	v_mfma_f32_16x16x32_bf16 v[102:105], v[146:149], v[170:173], v[102:105]
	v_mfma_f32_16x16x32_bf16 v[86:89], v[146:149], v[178:181], v[86:89]
	v_mfma_f32_16x16x32_bf16 v[82:85], v[154:157], v[178:181], v[82:85]
	v_mfma_f32_16x16x32_bf16 v[66:69], v[154:157], v[186:189], v[66:69]
	v_mfma_f32_16x16x32_bf16 v[70:73], v[146:149], v[186:189], v[70:73]
	v_mfma_f32_16x16x32_bf16 v[118:121], v[150:153], v[166:169], v[118:121]
	v_mfma_f32_16x16x32_bf16 v[114:117], v[158:161], v[166:169], v[114:117]
	v_mfma_f32_16x16x32_bf16 v[98:101], v[158:161], v[174:177], v[98:101]
	v_mfma_f32_16x16x32_bf16 v[102:105], v[150:153], v[174:177], v[102:105]
	v_mfma_f32_16x16x32_bf16 v[86:89], v[150:153], v[182:185], v[86:89]
	v_mfma_f32_16x16x32_bf16 v[82:85], v[158:161], v[182:185], v[82:85]
	v_mfma_f32_16x16x32_bf16 v[66:69], v[158:161], v[190:193], v[66:69]
	v_mfma_f32_16x16x32_bf16 v[70:73], v[150:153], v[190:193], v[70:73]
	s_barrier
; #define PG8_STAGE(bufoff, gbase, voff) do { const int so_ = (int)(unsigned)((const char*)(gbase) - base_##voff); _Pragma("unroll") for (int _i = 0; _i < 2; ++_i) \
;         __builtin_amdgcn_raw_ptr_buffer_load_lds(rs_##voff, (PG8_LAS unsigned*)(lds + (bufoff) + ldsw + _i * 8192), 16, (int)(voff)[_i], so_, 0, 0); } while (0)
; #define PG8_LDA(dst, b, h) do { _Pragma("unroll") for (int m = 0; m < 4; ++m) _Pragma("unroll") for (int k = 0; k < 2; ++k) dst[m][k] = *(const PG8_LAS bf16x8*)(lds + PG8_SA(b, h) + aoff + m * 2048 + k * 1024); } while (0)
; #define PG8_LDB(dst, b, h) do { _Pragma("unroll") for (int n = 0; n < 2; ++n) _Pragma("unroll") for (int k = 0; k < 2; ++k) dst[n][k] = *(const PG8_LAS bf16x8*)(lds + PG8_SB(b, h) + boff + n * 2048 + k * 1024); } while (0)
; #define PG8_MMA(ai, bj, At, Bt) do { __builtin_amdgcn_s_setprio(1); _Pragma("unroll") for (int m = 0; m < 4; ++m) _Pragma("unroll") for (int n = 0; n < 2; ++n) _Pragma("unroll") for (int k = 0; k < 2; ++k) \
;         acc[ai][bj][m][n] = __builtin_amdgcn_mfma_f32_16x16x32_bf16(Bt[n][k], At[m][k], acc[ai][bj][m][n], 0, 0, 0); __builtin_amdgcn_s_setprio(0); } while (0)
; #define PG8_WAIT_V(n) asm volatile("s_waitcnt vmcnt(" #n ")" ::: "memory")
; #define PG8_WAIT_L(n) asm volatile("s_waitcnt lgkmcnt(" #n ")" ::: "memory")
; #define PG8_BAR __builtin_amdgcn_s_barrier()
; #define PG8_SCHED __builtin_amdgcn_sched_barrier(0)
; template <class Epi, class Sched, bool ALIGN_EPI = false, bool SP2 = false>
; __device__ __forceinline__ void gemm_phase(PG8_LAS unsigned char* lds, const Gemm g, const Sched& S, const Epi& E, int tid_in) {
;     ...
;             PG8_WAIT_V(8); PG8_WAIT_L(0); PG8_BAR; PG8_MMA(0, 0, At, B0); PG8_MMA(0, 1, At, B1); PG8_BAR; PG8_SCHED;
;             PG8_LDA(At, 0, 1); PG8_STAGE(PG8_SB(0, 0), b2, voffB); PG8_STAGE(PG8_SB(0, 1), b2 + hstepB, voffB); PG8_STAGE(PG8_SA(0, 0), a2, voffA);
;             PG8_WAIT_V(8); PG8_WAIT_L(0); PG8_BAR; PG8_MMA(1, 0, At, B0); PG8_MMA(1, 1, At, B1); PG8_BAR; PG8_SCHED;
;             PG8_LDB(B0, 1, 0); PG8_LDB(B1, 1, 1); PG8_SCHED; PG8_LDA(At, 1, 0); PG8_STAGE(PG8_SA(0, 1), a2 + hstepA, voffA);
;             PG8_WAIT_V(8); PG8_WAIT_L(0); PG8_BAR; PG8_MMA(0, 0, At, B0); PG8_MMA(0, 1, At, B1); PG8_BAR; PG8_SCHED;
	s_cselect_b32 s12, s15, s20
	s_mov_b32 m0, s61
	s_mov_b32 s42, s6
	s_mov_b32 s43, s7
	s_sub_i32 s12, s12, s40
	ds_read_b128 v[162:165], v238 offset:16384
	ds_read_b128 v[166:169], v238 offset:17408
	ds_read_b128 v[170:173], v238 offset:18432
	ds_read_b128 v[174:177], v238 offset:19456
	ds_read_b128 v[178:181], v238 offset:20480
	ds_read_b128 v[182:185], v238 offset:21504
	ds_read_b128 v[186:189], v238 offset:22528
	ds_read_b128 v[190:193], v238 offset:23552
	s_setprio 0
	buffer_load_dwordx4 v207, s[40:43], s12 offen lds
	s_mov_b32 m0, s62
	s_add_i32 s36, s12, 0x80000
	buffer_load_dwordx4 v224, s[40:43], s12 offen lds
	s_mov_b32 m0, s63
	s_sub_i32 s13, s13, s4
	buffer_load_dwordx4 v207, s[40:43], s36 offen lds
	s_mov_b32 m0, s71
	s_nop 0
	buffer_load_dwordx4 v224, s[40:43], s36 offen lds
	s_mov_b32 m0, s53
	s_nop 0
	buffer_load_dwordx4 v195, s[4:7], s13 offen lds
	s_waitcnt vmcnt(7)
	s_waitcnt lgkmcnt(0)
	s_setprio 1
	s_barrier
	v_mfma_f32_16x16x32_bf16 v[62:65], v[130:133], v[162:165], v[62:65]
	v_mfma_f32_16x16x32_bf16 v[58:61], v[138:141], v[162:165], v[58:61]
	v_mfma_f32_16x16x32_bf16 v[42:45], v[138:141], v[170:173], v[42:45]
	v_mfma_f32_16x16x32_bf16 v[46:49], v[130:133], v[170:173], v[46:49]
	v_mfma_f32_16x16x32_bf16 v[30:33], v[130:133], v[178:181], v[30:33]
	v_mfma_f32_16x16x32_bf16 v[26:29], v[138:141], v[178:181], v[26:29]
	v_mfma_f32_16x16x32_bf16 v[10:13], v[138:141], v[186:189], v[10:13]
	v_mfma_f32_16x16x32_bf16 v[14:17], v[130:133], v[186:189], v[14:17]
	v_mfma_f32_16x16x32_bf16 v[62:65], v[134:137], v[166:169], v[62:65]
	v_mfma_f32_16x16x32_bf16 v[58:61], v[142:145], v[166:169], v[58:61]
	v_mfma_f32_16x16x32_bf16 v[42:45], v[142:145], v[174:177], v[42:45]
	v_mfma_f32_16x16x32_bf16 v[46:49], v[134:137], v[174:177], v[46:49]
	v_mfma_f32_16x16x32_bf16 v[30:33], v[134:137], v[182:185], v[30:33]
	v_mfma_f32_16x16x32_bf16 v[26:29], v[142:145], v[182:185], v[26:29]
	v_mfma_f32_16x16x32_bf16 v[10:13], v[142:145], v[190:193], v[10:13]
	v_mfma_f32_16x16x32_bf16 v[14:17], v[134:137], v[190:193], v[14:17]
	v_mfma_f32_16x16x32_bf16 v[54:57], v[146:149], v[162:165], v[54:57]
	v_mfma_f32_16x16x32_bf16 v[50:53], v[154:157], v[162:165], v[50:53]
	v_mfma_f32_16x16x32_bf16 v[34:37], v[154:157], v[170:173], v[34:37]
	v_mfma_f32_16x16x32_bf16 v[38:41], v[146:149], v[170:173], v[38:41]
	v_mfma_f32_16x16x32_bf16 v[22:25], v[146:149], v[178:181], v[22:25]
	v_mfma_f32_16x16x32_bf16 v[18:21], v[154:157], v[178:181], v[18:21]
	v_mfma_f32_16x16x32_bf16 v[2:5], v[154:157], v[186:189], v[2:5]
	v_mfma_f32_16x16x32_bf16 v[6:9], v[146:149], v[186:189], v[6:9]
	v_mfma_f32_16x16x32_bf16 v[54:57], v[150:153], v[166:169], v[54:57]
	v_mfma_f32_16x16x32_bf16 v[50:53], v[158:161], v[166:169], v[50:53]
	v_mfma_f32_16x16x32_bf16 v[34:37], v[158:161], v[174:177], v[34:37]
	v_mfma_f32_16x16x32_bf16 v[38:41], v[150:153], v[174:177], v[38:41]
	v_mfma_f32_16x16x32_bf16 v[22:25], v[150:153], v[182:185], v[22:25]
	v_mfma_f32_16x16x32_bf16 v[18:21], v[158:161], v[182:185], v[18:21]
	v_mfma_f32_16x16x32_bf16 v[2:5], v[158:161], v[190:193], v[2:5]
	v_mfma_f32_16x16x32_bf16 v[6:9], v[150:153], v[190:193], v[6:9]
	s_barrier
	v_add_u32_e32 v0, 0x18000, v237
	ds_read_b128 v[130:133], v0
	ds_read_b128 v[134:137], v0 offset:1024
	ds_read_b128 v[138:141], v0 offset:2048
	ds_read_b128 v[142:145], v0 offset:3072
	v_add_u32_e32 v0, 0x1c000, v237
	ds_read_b128 v[146:149], v0
	ds_read_b128 v[150:153], v0 offset:1024
	ds_read_b128 v[154:157], v0 offset:2048
	ds_read_b128 v[158:161], v0 offset:3072
	s_add_i32 s36, s13, 0x80000
	s_mov_b32 m0, s73
	ds_read_b128 v[162:165], v238 offset:32768
	ds_read_b128 v[166:169], v238 offset:33792
	ds_read_b128 v[170:173], v238 offset:34816
	ds_read_b128 v[174:177], v238 offset:35840
	ds_read_b128 v[178:181], v238 offset:36864
	ds_read_b128 v[182:185], v238 offset:37888
	ds_read_b128 v[186:189], v238 offset:38912
	ds_read_b128 v[190:193], v238 offset:39936
	s_setprio 0
	s_mov_b32 m0, s72
	s_nop 0
	buffer_load_dwordx4 v211, s[4:7], s13 offen lds
	s_mov_b32 m0, s73
	s_nop 0
	buffer_load_dwordx4 v195, s[4:7], s36 offen lds
	s_mov_b32 m0, s74
	s_nop 0
	buffer_load_dwordx4 v211, s[4:7], s36 offen lds
	s_waitcnt vmcnt(8)
	s_waitcnt lgkmcnt(0)
	s_setprio 1
	s_barrier
; #define PG8_STAGE(bufoff, gbase, voff) do { const int so_ = (int)(unsigned)((const char*)(gbase) - base_##voff); _Pragma("unroll") for (int _i = 0; _i < 2; ++_i) \
;         __builtin_amdgcn_raw_ptr_buffer_load_lds(rs_##voff, (PG8_LAS unsigned*)(lds + (bufoff) + ldsw + _i * 8192), 16, (int)(voff)[_i], so_, 0, 0); } while (0)
; #define PG8_LDA(dst, b, h) do { _Pragma("unroll") for (int m = 0; m < 4; ++m) _Pragma("unroll") for (int k = 0; k < 2; ++k) dst[m][k] = *(const PG8_LAS bf16x8*)(lds + PG8_SA(b, h) + aoff + m * 2048 + k * 1024); } while (0)
; #define PG8_MMA(ai, bj, At, Bt) do { __builtin_amdgcn_s_setprio(1); _Pragma("unroll") for (int m = 0; m < 4; ++m) _Pragma("unroll") for (int n = 0; n < 2; ++n) _Pragma("unroll") for (int k = 0; k < 2; ++k) \
;         acc[ai][bj][m][n] = __builtin_amdgcn_mfma_f32_16x16x32_bf16(Bt[n][k], At[m][k], acc[ai][bj][m][n], 0, 0, 0); __builtin_amdgcn_s_setprio(0); } while (0)
; #define PG8_WAIT_V(n) asm volatile("s_waitcnt vmcnt(" #n ")" ::: "memory")
; #define PG8_WAIT_L(n) asm volatile("s_waitcnt lgkmcnt(" #n ")" ::: "memory")
; #define PG8_BAR __builtin_amdgcn_s_barrier()
; #define PG8_SCHED __builtin_amdgcn_sched_barrier(0)
; template <class Epi, class Sched, bool ALIGN_EPI = false, bool SP2 = false>
; __device__ __forceinline__ void gemm_phase(PG8_LAS unsigned char* lds, const Gemm g, const Sched& S, const Epi& E, int tid_in) {
;     ...
;             PG8_WAIT_V(8); PG8_WAIT_L(0); PG8_BAR; PG8_MMA(0, 0, At, B0); PG8_MMA(0, 1, At, B1); PG8_BAR; PG8_SCHED;
;             PG8_LDA(At, 1, 1); PG8_STAGE(PG8_SB(1, 0), b3, voffB); PG8_STAGE(PG8_SB(1, 1), b3 + hstepB, voffB); PG8_STAGE(PG8_SA(1, 0), a3, voffA);
;             PG8_WAIT_V(8); PG8_WAIT_L(0); PG8_BAR; PG8_MMA(1, 0, At, B0); PG8_MMA(1, 1, At, B1); PG8_BAR; PG8_SCHED;
;     ...
;         if constexpr (ALIGN_EPI) { if (wr == 0) PG8_BAR; }
	v_mfma_f32_16x16x32_bf16 v[126:129], v[130:133], v[162:165], v[126:129]
	v_mfma_f32_16x16x32_bf16 v[122:125], v[138:141], v[162:165], v[122:125]
	v_mfma_f32_16x16x32_bf16 v[106:109], v[138:141], v[170:173], v[106:109]
	v_mfma_f32_16x16x32_bf16 v[110:113], v[130:133], v[170:173], v[110:113]
	v_mfma_f32_16x16x32_bf16 v[94:97], v[130:133], v[178:181], v[94:97]
	v_mfma_f32_16x16x32_bf16 v[90:93], v[138:141], v[178:181], v[90:93]
	v_mfma_f32_16x16x32_bf16 v[74:77], v[138:141], v[186:189], v[74:77]
	v_mfma_f32_16x16x32_bf16 v[78:81], v[130:133], v[186:189], v[78:81]
	v_mfma_f32_16x16x32_bf16 v[126:129], v[134:137], v[166:169], v[126:129]
	v_mfma_f32_16x16x32_bf16 v[122:125], v[142:145], v[166:169], v[122:125]
	v_mfma_f32_16x16x32_bf16 v[106:109], v[142:145], v[174:177], v[106:109]
	v_mfma_f32_16x16x32_bf16 v[110:113], v[134:137], v[174:177], v[110:113]
	v_mfma_f32_16x16x32_bf16 v[94:97], v[134:137], v[182:185], v[94:97]
	v_mfma_f32_16x16x32_bf16 v[90:93], v[142:145], v[182:185], v[90:93]
	v_mfma_f32_16x16x32_bf16 v[74:77], v[142:145], v[190:193], v[74:77]
	v_mfma_f32_16x16x32_bf16 v[78:81], v[134:137], v[190:193], v[78:81]
	v_mfma_f32_16x16x32_bf16 v[118:121], v[146:149], v[162:165], v[118:121]
	v_mfma_f32_16x16x32_bf16 v[114:117], v[154:157], v[162:165], v[114:117]
	v_mfma_f32_16x16x32_bf16 v[98:101], v[154:157], v[170:173], v[98:101]
	v_mfma_f32_16x16x32_bf16 v[102:105], v[146:149], v[170:173], v[102:105]
	v_mfma_f32_16x16x32_bf16 v[86:89], v[146:149], v[178:181], v[86:89]
	v_mfma_f32_16x16x32_bf16 v[82:85], v[154:157], v[178:181], v[82:85]
	v_mfma_f32_16x16x32_bf16 v[66:69], v[154:157], v[186:189], v[66:69]
	v_mfma_f32_16x16x32_bf16 v[70:73], v[146:149], v[186:189], v[70:73]
	v_mfma_f32_16x16x32_bf16 v[118:121], v[150:153], v[166:169], v[118:121]
	v_mfma_f32_16x16x32_bf16 v[114:117], v[158:161], v[166:169], v[114:117]
	v_mfma_f32_16x16x32_bf16 v[98:101], v[158:161], v[174:177], v[98:101]
	v_mfma_f32_16x16x32_bf16 v[102:105], v[150:153], v[174:177], v[102:105]
	v_mfma_f32_16x16x32_bf16 v[86:89], v[150:153], v[182:185], v[86:89]
	v_mfma_f32_16x16x32_bf16 v[82:85], v[158:161], v[182:185], v[82:85]
	v_mfma_f32_16x16x32_bf16 v[66:69], v[158:161], v[190:193], v[66:69]
	v_mfma_f32_16x16x32_bf16 v[70:73], v[150:153], v[190:193], v[70:73]
	s_barrier
	s_mov_b32 m0, s75
	s_add_i32 s36, s12, 0x80
	ds_read_b128 v[162:165], v238 offset:49152
	ds_read_b128 v[166:169], v238 offset:50176
	ds_read_b128 v[170:173], v238 offset:51200
	ds_read_b128 v[174:177], v238 offset:52224
	ds_read_b128 v[178:181], v238 offset:53248
	ds_read_b128 v[182:185], v238 offset:54272
	ds_read_b128 v[186:189], v238 offset:55296
	ds_read_b128 v[190:193], v238 offset:56320
	s_setprio 0
	buffer_load_dwordx4 v207, s[40:43], s36 offen lds
	s_mov_b32 m0, s76
	s_add_i32 s12, s12, 0x80080
	buffer_load_dwordx4 v224, s[40:43], s36 offen lds
	s_mov_b32 m0, s79
	s_addk_i32 s13, 0x80
	buffer_load_dwordx4 v207, s[40:43], s12 offen lds
	s_mov_b32 m0, s68
	s_nop 0
	buffer_load_dwordx4 v224, s[40:43], s12 offen lds
	s_mov_b32 m0, s77
	s_nop 0
	buffer_load_dwordx4 v195, s[4:7], s13 offen lds
	s_waitcnt vmcnt(7)
	s_waitcnt lgkmcnt(0)
	s_setprio 1
	s_barrier
	v_mfma_f32_16x16x32_bf16 v[62:65], v[130:133], v[162:165], v[62:65]
	v_mfma_f32_16x16x32_bf16 v[58:61], v[138:141], v[162:165], v[58:61]
	v_mfma_f32_16x16x32_bf16 v[42:45], v[138:141], v[170:173], v[42:45]
	v_mfma_f32_16x16x32_bf16 v[46:49], v[130:133], v[170:173], v[46:49]
	v_mfma_f32_16x16x32_bf16 v[30:33], v[130:133], v[178:181], v[30:33]
	v_mfma_f32_16x16x32_bf16 v[26:29], v[138:141], v[178:181], v[26:29]
	v_mfma_f32_16x16x32_bf16 v[10:13], v[138:141], v[186:189], v[10:13]
	v_mfma_f32_16x16x32_bf16 v[14:17], v[130:133], v[186:189], v[14:17]
	v_mfma_f32_16x16x32_bf16 v[62:65], v[134:137], v[166:169], v[62:65]
	v_mfma_f32_16x16x32_bf16 v[58:61], v[142:145], v[166:169], v[58:61]
	v_mfma_f32_16x16x32_bf16 v[42:45], v[142:145], v[174:177], v[42:45]
	v_mfma_f32_16x16x32_bf16 v[46:49], v[134:137], v[174:177], v[46:49]
	v_mfma_f32_16x16x32_bf16 v[30:33], v[134:137], v[182:185], v[30:33]
	v_mfma_f32_16x16x32_bf16 v[26:29], v[142:145], v[182:185], v[26:29]
	v_mfma_f32_16x16x32_bf16 v[10:13], v[142:145], v[190:193], v[10:13]
	v_mfma_f32_16x16x32_bf16 v[14:17], v[134:137], v[190:193], v[14:17]
	v_mfma_f32_16x16x32_bf16 v[54:57], v[146:149], v[162:165], v[54:57]
	v_mfma_f32_16x16x32_bf16 v[50:53], v[154:157], v[162:165], v[50:53]
	v_mfma_f32_16x16x32_bf16 v[34:37], v[154:157], v[170:173], v[34:37]
	v_mfma_f32_16x16x32_bf16 v[38:41], v[146:149], v[170:173], v[38:41]
	v_mfma_f32_16x16x32_bf16 v[22:25], v[146:149], v[178:181], v[22:25]
	v_mfma_f32_16x16x32_bf16 v[18:21], v[154:157], v[178:181], v[18:21]
	v_mfma_f32_16x16x32_bf16 v[2:5], v[154:157], v[186:189], v[2:5]
	v_mfma_f32_16x16x32_bf16 v[6:9], v[146:149], v[186:189], v[6:9]
	v_mfma_f32_16x16x32_bf16 v[54:57], v[150:153], v[166:169], v[54:57]
	v_mfma_f32_16x16x32_bf16 v[50:53], v[158:161], v[166:169], v[50:53]
	v_mfma_f32_16x16x32_bf16 v[34:37], v[158:161], v[174:177], v[34:37]
	v_mfma_f32_16x16x32_bf16 v[38:41], v[150:153], v[174:177], v[38:41]
	v_mfma_f32_16x16x32_bf16 v[22:25], v[150:153], v[182:185], v[22:25]
	v_mfma_f32_16x16x32_bf16 v[18:21], v[158:161], v[182:185], v[18:21]
	v_mfma_f32_16x16x32_bf16 v[2:5], v[158:161], v[190:193], v[2:5]
	v_mfma_f32_16x16x32_bf16 v[6:9], v[150:153], v[190:193], v[6:9]
	s_barrier
	s_setprio 0
	s_add_i32 s23, s23, 2
	s_add_u32 s20, s20, 0x100
	s_addc_u32 s21, s21, 0
	s_cmp_gt_u32 s23, 29
	s_mov_b64 s[12:13], s[16:17]
	s_cbranch_scc0 .LBB0_312
	s_and_b64 vcc, exec, s[48:49]
	s_cbranch_vccz .LBB0_315
	s_barrier

; #define PG8_STAGE(bufoff, gbase, voff) do { const int so_ = (int)(unsigned)((const char*)(gbase) - base_##voff); _Pragma("unroll") for (int _i = 0; _i < 2; ++_i) \
;         __builtin_amdgcn_raw_ptr_buffer_load_lds(rs_##voff, (PG8_LAS unsigned*)(lds + (bufoff) + ldsw + _i * 8192), 16, (int)(voff)[_i], so_, 0, 0); } while (0)
; #define PG8_LDA(dst, b, h) do { _Pragma("unroll") for (int m = 0; m < 4; ++m) _Pragma("unroll") for (int k = 0; k < 2; ++k) dst[m][k] = *(const PG8_LAS bf16x8*)(lds + PG8_SA(b, h) + aoff + m * 2048 + k * 1024); } while (0)
; #define PG8_LDB(dst, b, h) do { _Pragma("unroll") for (int n = 0; n < 2; ++n) _Pragma("unroll") for (int k = 0; k < 2; ++k) dst[n][k] = *(const PG8_LAS bf16x8*)(lds + PG8_SB(b, h) + boff + n * 2048 + k * 1024); } while (0)
; #define PG8_MMA(ai, bj, At, Bt) do { __builtin_amdgcn_s_setprio(1); _Pragma("unroll") for (int m = 0; m < 4; ++m) _Pragma("unroll") for (int n = 0; n < 2; ++n) _Pragma("unroll") for (int k = 0; k < 2; ++k) \
;         acc[ai][bj][m][n] = __builtin_amdgcn_mfma_f32_16x16x32_bf16(Bt[n][k], At[m][k], acc[ai][bj][m][n], 0, 0, 0); __builtin_amdgcn_s_setprio(0); } while (0)
; #define PG8_WAIT_V(n) asm volatile("s_waitcnt vmcnt(" #n ")" ::: "memory")
; #define PG8_WAIT_L(n) asm volatile("s_waitcnt lgkmcnt(" #n ")" ::: "memory")
; #define PG8_BAR __builtin_amdgcn_s_barrier()
; #define PG8_SCHED __builtin_amdgcn_sched_barrier(0)
; template <class Epi, class Sched, bool ALIGN_EPI = false, bool SP2 = false>
; __device__ __forceinline__ void gemm_phase(PG8_LAS unsigned char* lds, const Gemm g, const Sched& S, const Epi& E, int tid_in) {
;     ...
;             PG8_LDB(B0, 0, 0); PG8_LDB(B1, 0, 1); PG8_SCHED; PG8_LDA(At, 0, 0); PG8_STAGE(PG8_SA(1, 1), a1 + hstepA, voffA);
;             PG8_WAIT_V(8); PG8_WAIT_L(0); PG8_BAR; PG8_MMA(0, 0, At, B0); PG8_MMA(0, 1, At, B1); PG8_BAR; PG8_SCHED;
;             PG8_LDA(At, 0, 1); PG8_STAGE(PG8_SB(0, 0), b2, voffB); PG8_STAGE(PG8_SB(0, 1), b2 + hstepB, voffB); PG8_STAGE(PG8_SA(0, 0), a2, voffA);
;             PG8_WAIT_V(8); PG8_WAIT_L(0); PG8_BAR; PG8_MMA(1, 0, At, B0); PG8_MMA(1, 1, At, B1); PG8_BAR; PG8_SCHED;
.LBB0_1037:
	v_add_u32_e32 v0, 0x10000, v236
	ds_read_b128 v[132:135], v0
	ds_read_b128 v[136:139], v0 offset:1024
	ds_read_b128 v[140:143], v0 offset:2048
	ds_read_b128 v[144:147], v0 offset:3072
	v_add_u32_e32 v0, 0x14000, v236
	ds_read_b128 v[148:151], v0
	ds_read_b128 v[152:155], v0 offset:1024
	ds_read_b128 v[156:159], v0 offset:2048
	ds_read_b128 v[160:163], v0 offset:3072
	s_add_u32 s16, s12, 0x100
	s_addc_u32 s17, s13, 0
	s_sub_i32 s12, s12, s4
	s_add_i32 s12, s12, 0xc0080
	s_sub_i32 s39, s12, 0xc0000
	s_cmp_eq_u32 s38, 12
	s_cselect_b32 s13, s24, s16
	s_mov_b32 m0, s76
	ds_read_b128 v[164:167], v237
	ds_read_b128 v[168:171], v237 offset:1024
	ds_read_b128 v[172:175], v237 offset:2048
	ds_read_b128 v[176:179], v237 offset:3072
	ds_read_b128 v[180:183], v237 offset:4096
	ds_read_b128 v[184:187], v237 offset:5120
	ds_read_b128 v[188:191], v237 offset:6144
	ds_read_b128 v[192:195], v237 offset:7168
	s_mov_b32 m0, s73
	s_nop 0
	buffer_load_dwordx4 v222, s[4:7], s39 offen lds
	s_mov_b32 m0, s76
	s_nop 0
	buffer_load_dwordx4 v220, s[4:7], s12 offen lds
	s_mov_b32 m0, s77
	s_nop 0
	buffer_load_dwordx4 v222, s[4:7], s12 offen lds
	s_waitcnt vmcnt(8)
	s_waitcnt lgkmcnt(0)
	s_setprio 1
	s_barrier
	v_mfma_f32_16x16x32_bf16 v[128:131], v[132:135], v[164:167], v[128:131]
	v_mfma_f32_16x16x32_bf16 v[124:127], v[140:143], v[164:167], v[124:127]
	v_mfma_f32_16x16x32_bf16 v[116:119], v[140:143], v[172:175], v[116:119]
	v_mfma_f32_16x16x32_bf16 v[120:123], v[132:135], v[172:175], v[120:123]
	v_mfma_f32_16x16x32_bf16 v[112:115], v[132:135], v[180:183], v[112:115]
	v_mfma_f32_16x16x32_bf16 v[108:111], v[140:143], v[180:183], v[108:111]
	v_mfma_f32_16x16x32_bf16 v[100:103], v[140:143], v[188:191], v[100:103]
	v_mfma_f32_16x16x32_bf16 v[104:107], v[132:135], v[188:191], v[104:107]
	v_mfma_f32_16x16x32_bf16 v[128:131], v[136:139], v[168:171], v[128:131]
	v_mfma_f32_16x16x32_bf16 v[124:127], v[144:147], v[168:171], v[124:127]
	v_mfma_f32_16x16x32_bf16 v[116:119], v[144:147], v[176:179], v[116:119]
	v_mfma_f32_16x16x32_bf16 v[120:123], v[136:139], v[176:179], v[120:123]
	v_mfma_f32_16x16x32_bf16 v[112:115], v[136:139], v[184:187], v[112:115]
	v_mfma_f32_16x16x32_bf16 v[108:111], v[144:147], v[184:187], v[108:111]
	v_mfma_f32_16x16x32_bf16 v[100:103], v[144:147], v[192:195], v[100:103]
	v_mfma_f32_16x16x32_bf16 v[104:107], v[136:139], v[192:195], v[104:107]
	v_mfma_f32_16x16x32_bf16 v[96:99], v[148:151], v[164:167], v[96:99]
	v_mfma_f32_16x16x32_bf16 v[92:95], v[156:159], v[164:167], v[92:95]
	v_mfma_f32_16x16x32_bf16 v[84:87], v[156:159], v[172:175], v[84:87]
	v_mfma_f32_16x16x32_bf16 v[88:91], v[148:151], v[172:175], v[88:91]
	v_mfma_f32_16x16x32_bf16 v[80:83], v[148:151], v[180:183], v[80:83]
	v_mfma_f32_16x16x32_bf16 v[76:79], v[156:159], v[180:183], v[76:79]
	v_mfma_f32_16x16x32_bf16 v[68:71], v[156:159], v[188:191], v[68:71]
	v_mfma_f32_16x16x32_bf16 v[72:75], v[148:151], v[188:191], v[72:75]
	v_mfma_f32_16x16x32_bf16 v[96:99], v[152:155], v[168:171], v[96:99]
	v_mfma_f32_16x16x32_bf16 v[92:95], v[160:163], v[168:171], v[92:95]
	v_mfma_f32_16x16x32_bf16 v[84:87], v[160:163], v[176:179], v[84:87]
	v_mfma_f32_16x16x32_bf16 v[88:91], v[152:155], v[176:179], v[88:91]
	v_mfma_f32_16x16x32_bf16 v[80:83], v[152:155], v[184:187], v[80:83]
	v_mfma_f32_16x16x32_bf16 v[76:79], v[160:163], v[184:187], v[76:79]
	v_mfma_f32_16x16x32_bf16 v[68:71], v[160:163], v[192:195], v[68:71]
	v_mfma_f32_16x16x32_bf16 v[72:75], v[152:155], v[192:195], v[72:75]
	s_barrier
	s_cselect_b32 s12, s18, s19
	s_mov_b32 m0, s26
	s_mov_b32 s46, s6
	s_mov_b32 s47, s7
	s_sub_i32 s12, s12, s44
	ds_read_b128 v[164:167], v237 offset:16384
	ds_read_b128 v[168:171], v237 offset:17408
	ds_read_b128 v[172:175], v237 offset:18432
	ds_read_b128 v[176:179], v237 offset:19456
	ds_read_b128 v[180:183], v237 offset:20480
	ds_read_b128 v[184:187], v237 offset:21504
	ds_read_b128 v[188:191], v237 offset:22528
	ds_read_b128 v[192:195], v237 offset:23552
	s_setprio 0
	buffer_load_dwordx4 v221, s[44:47], s12 offen lds
	s_mov_b32 m0, s53
	s_add_i32 s39, s12, 0x40000
	buffer_load_dwordx4 v223, s[44:47], s12 offen lds
	s_mov_b32 m0, s60
	s_sub_i32 s13, s13, s4
	buffer_load_dwordx4 v221, s[44:47], s39 offen lds
	s_mov_b32 m0, s61
	s_nop 0
	buffer_load_dwordx4 v223, s[44:47], s39 offen lds
	s_mov_b32 m0, s21
	s_nop 0
	buffer_load_dwordx4 v220, s[4:7], s13 offen lds
	s_waitcnt vmcnt(7)
	s_waitcnt lgkmcnt(0)
	s_setprio 1
	s_barrier
	v_mfma_f32_16x16x32_bf16 v[64:67], v[132:135], v[164:167], v[64:67]
	v_mfma_f32_16x16x32_bf16 v[60:63], v[140:143], v[164:167], v[60:63]
	v_mfma_f32_16x16x32_bf16 v[52:55], v[140:143], v[172:175], v[52:55]
	v_mfma_f32_16x16x32_bf16 v[56:59], v[132:135], v[172:175], v[56:59]
	v_mfma_f32_16x16x32_bf16 v[48:51], v[132:135], v[180:183], v[48:51]
	v_mfma_f32_16x16x32_bf16 v[44:47], v[140:143], v[180:183], v[44:47]
	v_mfma_f32_16x16x32_bf16 v[36:39], v[140:143], v[188:191], v[36:39]
	v_mfma_f32_16x16x32_bf16 v[40:43], v[132:135], v[188:191], v[40:43]
	v_mfma_f32_16x16x32_bf16 v[64:67], v[136:139], v[168:171], v[64:67]
	v_mfma_f32_16x16x32_bf16 v[60:63], v[144:147], v[168:171], v[60:63]
	v_mfma_f32_16x16x32_bf16 v[52:55], v[144:147], v[176:179], v[52:55]
	v_mfma_f32_16x16x32_bf16 v[56:59], v[136:139], v[176:179], v[56:59]
	v_mfma_f32_16x16x32_bf16 v[48:51], v[136:139], v[184:187], v[48:51]
	v_mfma_f32_16x16x32_bf16 v[44:47], v[144:147], v[184:187], v[44:47]
	v_mfma_f32_16x16x32_bf16 v[36:39], v[144:147], v[192:195], v[36:39]
	v_mfma_f32_16x16x32_bf16 v[40:43], v[136:139], v[192:195], v[40:43]
	v_mfma_f32_16x16x32_bf16 v[32:35], v[148:151], v[164:167], v[32:35]
	v_mfma_f32_16x16x32_bf16 v[28:31], v[156:159], v[164:167], v[28:31]
	v_mfma_f32_16x16x32_bf16 v[20:23], v[156:159], v[172:175], v[20:23]
	v_mfma_f32_16x16x32_bf16 v[24:27], v[148:151], v[172:175], v[24:27]
	v_mfma_f32_16x16x32_bf16 v[16:19], v[148:151], v[180:183], v[16:19]
	v_mfma_f32_16x16x32_bf16 v[12:15], v[156:159], v[180:183], v[12:15]
	v_mfma_f32_16x16x32_bf16 v[2:5], v[156:159], v[188:191], v[4:7]
	v_mfma_f32_16x16x32_bf16 v[8:11], v[148:151], v[188:191], v[8:11]
	v_mfma_f32_16x16x32_bf16 v[32:35], v[152:155], v[168:171], v[32:35]
	v_mfma_f32_16x16x32_bf16 v[28:31], v[160:163], v[168:171], v[28:31]
	v_mfma_f32_16x16x32_bf16 v[20:23], v[160:163], v[176:179], v[20:23]
	v_mfma_f32_16x16x32_bf16 v[24:27], v[152:155], v[176:179], v[24:27]
	v_mfma_f32_16x16x32_bf16 v[16:19], v[152:155], v[184:187], v[16:19]
	v_mfma_f32_16x16x32_bf16 v[12:15], v[160:163], v[184:187], v[12:15]
	v_mfma_f32_16x16x32_bf16 v[2:5], v[160:163], v[192:195], v[2:5]
	v_mfma_f32_16x16x32_bf16 v[8:11], v[152:155], v[192:195], v[8:11]
	s_barrier
; #define PG8_STAGE(bufoff, gbase, voff) do { const int so_ = (int)(unsigned)((const char*)(gbase) - base_##voff); _Pragma("unroll") for (int _i = 0; _i < 2; ++_i) \
;         __builtin_amdgcn_raw_ptr_buffer_load_lds(rs_##voff, (PG8_LAS unsigned*)(lds + (bufoff) + ldsw + _i * 8192), 16, (int)(voff)[_i], so_, 0, 0); } while (0)
; #define PG8_LDA(dst, b, h) do { _Pragma("unroll") for (int m = 0; m < 4; ++m) _Pragma("unroll") for (int k = 0; k < 2; ++k) dst[m][k] = *(const PG8_LAS bf16x8*)(lds + PG8_SA(b, h) + aoff + m * 2048 + k * 1024); } while (0)
; #define PG8_LDB(dst, b, h) do { _Pragma("unroll") for (int n = 0; n < 2; ++n) _Pragma("unroll") for (int k = 0; k < 2; ++k) dst[n][k] = *(const PG8_LAS bf16x8*)(lds + PG8_SB(b, h) + boff + n * 2048 + k * 1024); } while (0)
; #define PG8_MMA(ai, bj, At, Bt) do { __builtin_amdgcn_s_setprio(1); _Pragma("unroll") for (int m = 0; m < 4; ++m) _Pragma("unroll") for (int n = 0; n < 2; ++n) _Pragma("unroll") for (int k = 0; k < 2; ++k) \
;         acc[ai][bj][m][n] = __builtin_amdgcn_mfma_f32_16x16x32_bf16(Bt[n][k], At[m][k], acc[ai][bj][m][n], 0, 0, 0); __builtin_amdgcn_s_setprio(0); } while (0)
; #define PG8_WAIT_V(n) asm volatile("s_waitcnt vmcnt(" #n ")" ::: "memory")
; #define PG8_WAIT_L(n) asm volatile("s_waitcnt lgkmcnt(" #n ")" ::: "memory")
; #define PG8_BAR __builtin_amdgcn_s_barrier()
; #define PG8_SCHED __builtin_amdgcn_sched_barrier(0)
; template <class Epi, class Sched, bool ALIGN_EPI = false, bool SP2 = false>
; __device__ __forceinline__ void gemm_phase(PG8_LAS unsigned char* lds, const Gemm g, const Sched& S, const Epi& E, int tid_in) {
;     ...
;             PG8_LDB(B0, 1, 0); PG8_LDB(B1, 1, 1); PG8_SCHED; PG8_LDA(At, 1, 0); PG8_STAGE(PG8_SA(0, 1), a2 + hstepA, voffA);
;             PG8_WAIT_V(8); PG8_WAIT_L(0); PG8_BAR; PG8_MMA(0, 0, At, B0); PG8_MMA(0, 1, At, B1); PG8_BAR; PG8_SCHED;
;             PG8_LDA(At, 1, 1); PG8_STAGE(PG8_SB(1, 0), b3, voffB); PG8_STAGE(PG8_SB(1, 1), b3 + hstepB, voffB); PG8_STAGE(PG8_SA(1, 0), a3, voffA);
;             PG8_WAIT_V(8); PG8_WAIT_L(0); PG8_BAR; PG8_MMA(1, 0, At, B0); PG8_MMA(1, 1, At, B1); PG8_BAR; PG8_SCHED;
;     ...
;         if constexpr (ALIGN_EPI) { if (wr == 0) PG8_BAR; }
	v_add_u32_e32 v0, 0x18000, v236
	ds_read_b128 v[132:135], v0
	ds_read_b128 v[136:139], v0 offset:1024
	ds_read_b128 v[140:143], v0 offset:2048
	ds_read_b128 v[144:147], v0 offset:3072
	v_add_u32_e32 v0, 0x1c000, v236
	ds_read_b128 v[148:151], v0
	ds_read_b128 v[152:155], v0 offset:1024
	ds_read_b128 v[156:159], v0 offset:2048
	ds_read_b128 v[160:163], v0 offset:3072
	s_add_i32 s39, s13, 0xc0000
	s_mov_b32 m0, s63
	ds_read_b128 v[164:167], v237 offset:32768
	ds_read_b128 v[168:171], v237 offset:33792
	ds_read_b128 v[172:175], v237 offset:34816
	ds_read_b128 v[176:179], v237 offset:35840
	ds_read_b128 v[180:183], v237 offset:36864
	ds_read_b128 v[184:187], v237 offset:37888
	ds_read_b128 v[188:191], v237 offset:38912
	ds_read_b128 v[192:195], v237 offset:39936
	s_setprio 0
	s_mov_b32 m0, s62
	s_nop 0
	buffer_load_dwordx4 v222, s[4:7], s13 offen lds
	s_mov_b32 m0, s63
	s_nop 0
	buffer_load_dwordx4 v220, s[4:7], s39 offen lds
	s_mov_b32 m0, s66
	s_nop 0
	buffer_load_dwordx4 v222, s[4:7], s39 offen lds
	s_waitcnt vmcnt(8)
	s_waitcnt lgkmcnt(0)
	s_setprio 1
	s_barrier
	v_mfma_f32_16x16x32_bf16 v[128:131], v[132:135], v[164:167], v[128:131]
	v_mfma_f32_16x16x32_bf16 v[124:127], v[140:143], v[164:167], v[124:127]
	v_mfma_f32_16x16x32_bf16 v[116:119], v[140:143], v[172:175], v[116:119]
	v_mfma_f32_16x16x32_bf16 v[120:123], v[132:135], v[172:175], v[120:123]
	v_mfma_f32_16x16x32_bf16 v[112:115], v[132:135], v[180:183], v[112:115]
	v_mfma_f32_16x16x32_bf16 v[108:111], v[140:143], v[180:183], v[108:111]
	v_mfma_f32_16x16x32_bf16 v[100:103], v[140:143], v[188:191], v[100:103]
	v_mfma_f32_16x16x32_bf16 v[104:107], v[132:135], v[188:191], v[104:107]
	v_mfma_f32_16x16x32_bf16 v[128:131], v[136:139], v[168:171], v[128:131]
	v_mfma_f32_16x16x32_bf16 v[124:127], v[144:147], v[168:171], v[124:127]
	v_mfma_f32_16x16x32_bf16 v[116:119], v[144:147], v[176:179], v[116:119]
	v_mfma_f32_16x16x32_bf16 v[120:123], v[136:139], v[176:179], v[120:123]
	v_mfma_f32_16x16x32_bf16 v[112:115], v[136:139], v[184:187], v[112:115]
	v_mfma_f32_16x16x32_bf16 v[108:111], v[144:147], v[184:187], v[108:111]
	v_mfma_f32_16x16x32_bf16 v[100:103], v[144:147], v[192:195], v[100:103]
	v_mfma_f32_16x16x32_bf16 v[104:107], v[136:139], v[192:195], v[104:107]
	v_mfma_f32_16x16x32_bf16 v[96:99], v[148:151], v[164:167], v[96:99]
	v_mfma_f32_16x16x32_bf16 v[92:95], v[156:159], v[164:167], v[92:95]
	v_mfma_f32_16x16x32_bf16 v[84:87], v[156:159], v[172:175], v[84:87]
	v_mfma_f32_16x16x32_bf16 v[88:91], v[148:151], v[172:175], v[88:91]
	v_mfma_f32_16x16x32_bf16 v[80:83], v[148:151], v[180:183], v[80:83]
	v_mfma_f32_16x16x32_bf16 v[76:79], v[156:159], v[180:183], v[76:79]
	v_mfma_f32_16x16x32_bf16 v[68:71], v[156:159], v[188:191], v[68:71]
	v_mfma_f32_16x16x32_bf16 v[72:75], v[148:151], v[188:191], v[72:75]
	v_mfma_f32_16x16x32_bf16 v[96:99], v[152:155], v[168:171], v[96:99]
	v_mfma_f32_16x16x32_bf16 v[92:95], v[160:163], v[168:171], v[92:95]
	v_mfma_f32_16x16x32_bf16 v[84:87], v[160:163], v[176:179], v[84:87]
	v_mfma_f32_16x16x32_bf16 v[88:91], v[152:155], v[176:179], v[88:91]
	v_mfma_f32_16x16x32_bf16 v[80:83], v[152:155], v[184:187], v[80:83]
	v_mfma_f32_16x16x32_bf16 v[76:79], v[160:163], v[184:187], v[76:79]
	v_mfma_f32_16x16x32_bf16 v[68:71], v[160:163], v[192:195], v[68:71]
	v_mfma_f32_16x16x32_bf16 v[72:75], v[152:155], v[192:195], v[72:75]
	s_barrier
	s_mov_b32 m0, s69
	s_add_i32 s39, s12, 0x80
	ds_read_b128 v[164:167], v237 offset:49152
	ds_read_b128 v[168:171], v237 offset:50176
	ds_read_b128 v[172:175], v237 offset:51200
	ds_read_b128 v[176:179], v237 offset:52224
	ds_read_b128 v[180:183], v237 offset:53248
	ds_read_b128 v[184:187], v237 offset:54272
	ds_read_b128 v[188:191], v237 offset:55296
	ds_read_b128 v[192:195], v237 offset:56320
	s_setprio 0
	buffer_load_dwordx4 v221, s[44:47], s39 offen lds
	s_mov_b32 m0, s71
	s_add_i32 s12, s12, 0x40080
	buffer_load_dwordx4 v223, s[44:47], s39 offen lds
	s_mov_b32 m0, s74
	s_addk_i32 s13, 0x80
	buffer_load_dwordx4 v221, s[44:47], s12 offen lds
	s_mov_b32 m0, s75
	s_nop 0
	buffer_load_dwordx4 v223, s[44:47], s12 offen lds
	s_mov_b32 m0, s72
	s_nop 0
	buffer_load_dwordx4 v220, s[4:7], s13 offen lds
	s_waitcnt vmcnt(7)
	s_waitcnt lgkmcnt(0)
	s_setprio 1
	s_barrier
	v_mfma_f32_16x16x32_bf16 v[64:67], v[132:135], v[164:167], v[64:67]
	v_mfma_f32_16x16x32_bf16 v[60:63], v[140:143], v[164:167], v[60:63]
	v_mfma_f32_16x16x32_bf16 v[52:55], v[140:143], v[172:175], v[52:55]
	v_mfma_f32_16x16x32_bf16 v[56:59], v[132:135], v[172:175], v[56:59]
	v_mfma_f32_16x16x32_bf16 v[48:51], v[132:135], v[180:183], v[48:51]
	v_mfma_f32_16x16x32_bf16 v[44:47], v[140:143], v[180:183], v[44:47]
	v_mfma_f32_16x16x32_bf16 v[36:39], v[140:143], v[188:191], v[36:39]
	v_mfma_f32_16x16x32_bf16 v[40:43], v[132:135], v[188:191], v[40:43]
	v_mfma_f32_16x16x32_bf16 v[64:67], v[136:139], v[168:171], v[64:67]
	v_mfma_f32_16x16x32_bf16 v[60:63], v[144:147], v[168:171], v[60:63]
	v_mfma_f32_16x16x32_bf16 v[52:55], v[144:147], v[176:179], v[52:55]
	v_mfma_f32_16x16x32_bf16 v[56:59], v[136:139], v[176:179], v[56:59]
	v_mfma_f32_16x16x32_bf16 v[48:51], v[136:139], v[184:187], v[48:51]
	v_mfma_f32_16x16x32_bf16 v[44:47], v[144:147], v[184:187], v[44:47]
	v_mfma_f32_16x16x32_bf16 v[36:39], v[144:147], v[192:195], v[36:39]
	v_mfma_f32_16x16x32_bf16 v[40:43], v[136:139], v[192:195], v[40:43]
	v_mfma_f32_16x16x32_bf16 v[32:35], v[148:151], v[164:167], v[32:35]
	v_mfma_f32_16x16x32_bf16 v[28:31], v[156:159], v[164:167], v[28:31]
	v_mfma_f32_16x16x32_bf16 v[20:23], v[156:159], v[172:175], v[20:23]
	v_mfma_f32_16x16x32_bf16 v[24:27], v[148:151], v[172:175], v[24:27]
	v_mfma_f32_16x16x32_bf16 v[16:19], v[148:151], v[180:183], v[16:19]
	v_mfma_f32_16x16x32_bf16 v[12:15], v[156:159], v[180:183], v[12:15]
	v_mfma_f32_16x16x32_bf16 v[2:5], v[156:159], v[188:191], v[2:5]
	v_mfma_f32_16x16x32_bf16 v[6:9], v[148:151], v[188:191], v[8:11]
	v_mfma_f32_16x16x32_bf16 v[32:35], v[152:155], v[168:171], v[32:35]
	v_mfma_f32_16x16x32_bf16 v[28:31], v[160:163], v[168:171], v[28:31]
	v_mfma_f32_16x16x32_bf16 v[20:23], v[160:163], v[176:179], v[20:23]
	v_mfma_f32_16x16x32_bf16 v[24:27], v[152:155], v[176:179], v[24:27]
	v_mfma_f32_16x16x32_bf16 v[16:19], v[152:155], v[184:187], v[16:19]
	v_mfma_f32_16x16x32_bf16 v[12:15], v[160:163], v[184:187], v[12:15]
	v_mfma_f32_16x16x32_bf16 v[8:11], v[152:155], v[192:195], v[6:9]
	v_mfma_f32_16x16x32_bf16 v[4:7], v[160:163], v[192:195], v[2:5]
	s_barrier
	s_setprio 0
	s_add_i32 s38, s38, 2
	s_add_u32 s19, s19, 0x100
	s_addc_u32 s23, s23, 0
	s_cmp_gt_u32 s38, 13
	s_mov_b64 s[12:13], s[16:17]
	s_cbranch_scc0 .LBB0_1037
	s_and_b64 vcc, exec, s[14:15]
	s_cbranch_vccz .LBB0_1040
	s_barrier

; #define PG8_STAGE(bufoff, gbase, voff) do { const int so_ = (int)(unsigned)((const char*)(gbase) - base_##voff); _Pragma("unroll") for (int _i = 0; _i < 2; ++_i) \
;         __builtin_amdgcn_raw_ptr_buffer_load_lds(rs_##voff, (PG8_LAS unsigned*)(lds + (bufoff) + ldsw + _i * 8192), 16, (int)(voff)[_i], so_, 0, 0); } while (0)
; #define PG8_LDA(dst, b, h) do { _Pragma("unroll") for (int m = 0; m < 4; ++m) _Pragma("unroll") for (int k = 0; k < 2; ++k) dst[m][k] = *(const PG8_LAS bf16x8*)(lds + PG8_SA(b, h) + aoff + m * 2048 + k * 1024); } while (0)
; #define PG8_LDB(dst, b, h) do { _Pragma("unroll") for (int n = 0; n < 2; ++n) _Pragma("unroll") for (int k = 0; k < 2; ++k) dst[n][k] = *(const PG8_LAS bf16x8*)(lds + PG8_SB(b, h) + boff + n * 2048 + k * 1024); } while (0)
; #define PG8_MMA(ai, bj, At, Bt) do { __builtin_amdgcn_s_setprio(1); _Pragma("unroll") for (int m = 0; m < 4; ++m) _Pragma("unroll") for (int n = 0; n < 2; ++n) _Pragma("unroll") for (int k = 0; k < 2; ++k) \
;         acc[ai][bj][m][n] = __builtin_amdgcn_mfma_f32_16x16x32_bf16(Bt[n][k], At[m][k], acc[ai][bj][m][n], 0, 0, 0); __builtin_amdgcn_s_setprio(0); } while (0)
; #define PG8_WAIT_V(n) asm volatile("s_waitcnt vmcnt(" #n ")" ::: "memory")
; #define PG8_WAIT_L(n) asm volatile("s_waitcnt lgkmcnt(" #n ")" ::: "memory")
; #define PG8_BAR __builtin_amdgcn_s_barrier()
; #define PG8_SCHED __builtin_amdgcn_sched_barrier(0)
; template <class Epi, class Sched, bool ALIGN_EPI = false, bool SP2 = false>
; __device__ __forceinline__ void gemm_phase(PG8_LAS unsigned char* lds, const Gemm g, const Sched& S, const Epi& E, int tid_in) {
;     ...
;             PG8_LDB(B0, 0, 0); PG8_LDB(B1, 0, 1); PG8_SCHED; PG8_LDA(At, 0, 0); PG8_STAGE(PG8_SA(1, 1), a1 + hstepA, voffA);
;             PG8_WAIT_V(8); PG8_WAIT_L(0); PG8_BAR; PG8_MMA(0, 0, At, B0); PG8_MMA(0, 1, At, B1); PG8_BAR; PG8_SCHED;
;             PG8_LDA(At, 0, 1); PG8_STAGE(PG8_SB(0, 0), b2, voffB); PG8_STAGE(PG8_SB(0, 1), b2 + hstepB, voffB); PG8_STAGE(PG8_SA(0, 0), a2, voffA);
;             PG8_WAIT_V(8); PG8_WAIT_L(0); PG8_BAR; PG8_MMA(1, 0, At, B0); PG8_MMA(1, 1, At, B1); PG8_BAR; PG8_SCHED;
.LBB0_1265:
	v_add_u32_e32 v133, 0x10000, v131
	ds_read_b128 v[134:137], v133
	ds_read_b128 v[138:141], v133 offset:1024
	ds_read_b128 v[142:145], v133 offset:2048
	ds_read_b128 v[146:149], v133 offset:3072
	v_add_u32_e32 v133, 0x14000, v131
	ds_read_b128 v[150:153], v133
	ds_read_b128 v[154:157], v133 offset:1024
	ds_read_b128 v[158:161], v133 offset:2048
	ds_read_b128 v[166:169], v133 offset:3072
	s_add_i32 s42, s18, s44
	s_add_i32 s21, s14, s44
	s_add_i32 s79, s12, s44
	s_addk_i32 s42, 0xff80
	s_sub_i32 vcc_lo, s42, 0x80000
	s_cmp_eq_u32 s19, 28
	s_cselect_b32 s21, s15, s21
	s_mov_b32 m0, s75
	ds_read_b128 v[170:173], v132
	ds_read_b128 v[174:177], v132 offset:1024
	ds_read_b128 v[178:181], v132 offset:2048
	ds_read_b128 v[182:185], v132 offset:3072
	ds_read_b128 v[186:189], v132 offset:4096
	ds_read_b128 v[190:193], v132 offset:5120
	ds_read_b128 v[200:203], v132 offset:6144
	ds_read_b128 v[206:209], v132 offset:7168
	s_mov_b32 m0, s72
	s_nop 0
	buffer_load_dwordx4 v130, s[4:7], vcc_lo offen lds
	s_mov_b32 m0, s75
	s_nop 0
	buffer_load_dwordx4 v0, s[4:7], s42 offen lds
	s_mov_b32 m0, s76
	s_nop 0
	buffer_load_dwordx4 v130, s[4:7], s42 offen lds
	s_waitcnt vmcnt(8)
	s_waitcnt lgkmcnt(0)
	s_setprio 1
	s_barrier
	v_mfma_f32_16x16x32_bf16 v[34:37], v[134:137], v[170:173], v[34:37]
	v_mfma_f32_16x16x32_bf16 v[18:21], v[142:145], v[170:173], v[18:21]
	v_mfma_f32_16x16x32_bf16 v[78:81], v[142:145], v[178:181], v[78:81]
	v_mfma_f32_16x16x32_bf16 v[86:89], v[134:137], v[178:181], v[86:89]
	v_mfma_f32_16x16x32_bf16 v[106:109], v[134:137], v[186:189], v[106:109]
	v_mfma_f32_16x16x32_bf16 v[102:105], v[142:145], v[186:189], v[102:105]
	v_mfma_f32_16x16x32_bf16 v[122:125], v[142:145], v[200:203], v[122:125]
	v_mfma_f32_16x16x32_bf16 v[126:129], v[134:137], v[200:203], v[126:129]
	v_mfma_f32_16x16x32_bf16 v[34:37], v[138:141], v[174:177], v[34:37]
	v_mfma_f32_16x16x32_bf16 v[18:21], v[146:149], v[174:177], v[18:21]
	v_mfma_f32_16x16x32_bf16 v[78:81], v[146:149], v[182:185], v[78:81]
	v_mfma_f32_16x16x32_bf16 v[86:89], v[138:141], v[182:185], v[86:89]
	v_mfma_f32_16x16x32_bf16 v[106:109], v[138:141], v[190:193], v[106:109]
	v_mfma_f32_16x16x32_bf16 v[102:105], v[146:149], v[190:193], v[102:105]
	v_mfma_f32_16x16x32_bf16 v[122:125], v[146:149], v[206:209], v[122:125]
	v_mfma_f32_16x16x32_bf16 v[126:129], v[138:141], v[206:209], v[126:129]
	v_mfma_f32_16x16x32_bf16 v[14:17], v[150:153], v[170:173], v[14:17]
	v_mfma_f32_16x16x32_bf16 v[38:41], v[158:161], v[170:173], v[38:41]
	v_mfma_f32_16x16x32_bf16 v[90:93], v[158:161], v[178:181], v[90:93]
	v_mfma_f32_16x16x32_bf16 v[74:77], v[150:153], v[178:181], v[74:77]
	v_mfma_f32_16x16x32_bf16 v[98:101], v[150:153], v[186:189], v[98:101]
	v_mfma_f32_16x16x32_bf16 v[110:113], v[158:161], v[186:189], v[110:113]
	v_mfma_f32_16x16x32_bf16 v[114:117], v[158:161], v[200:203], v[114:117]
	v_mfma_f32_16x16x32_bf16 v[118:121], v[150:153], v[200:203], v[118:121]
	v_mfma_f32_16x16x32_bf16 v[14:17], v[154:157], v[174:177], v[14:17]
	v_mfma_f32_16x16x32_bf16 v[38:41], v[166:169], v[174:177], v[38:41]
	v_mfma_f32_16x16x32_bf16 v[90:93], v[166:169], v[182:185], v[90:93]
	v_mfma_f32_16x16x32_bf16 v[74:77], v[154:157], v[182:185], v[74:77]
	v_mfma_f32_16x16x32_bf16 v[98:101], v[154:157], v[190:193], v[98:101]
	v_mfma_f32_16x16x32_bf16 v[110:113], v[166:169], v[190:193], v[110:113]
	v_mfma_f32_16x16x32_bf16 v[114:117], v[166:169], v[206:209], v[114:117]
	v_mfma_f32_16x16x32_bf16 v[118:121], v[154:157], v[206:209], v[118:121]
	s_barrier
	s_cselect_b32 s79, s17, s79
	s_mov_b32 m0, s49
	s_mov_b32 s42, s6
	s_mov_b32 s43, s7
	s_sub_i32 s79, s79, s40
	ds_read_b128 v[170:173], v132 offset:16384
	ds_read_b128 v[174:177], v132 offset:17408
	ds_read_b128 v[178:181], v132 offset:18432
	ds_read_b128 v[182:185], v132 offset:19456
	ds_read_b128 v[186:189], v132 offset:20480
	ds_read_b128 v[190:193], v132 offset:21504
	ds_read_b128 v[200:203], v132 offset:22528
	ds_read_b128 v[206:209], v132 offset:23552
	s_setprio 0
	buffer_load_dwordx4 v0, s[40:43], s79 offen lds
	s_mov_b32 m0, s60
	s_add_i32 vcc_lo, s79, 0x80000
	buffer_load_dwordx4 v130, s[40:43], s79 offen lds
	s_mov_b32 m0, s61
	s_sub_i32 s21, s21, s4
	buffer_load_dwordx4 v0, s[40:43], vcc_lo offen lds
	s_mov_b32 m0, s62
	s_nop 0
	buffer_load_dwordx4 v130, s[40:43], vcc_lo offen lds
	s_mov_b32 m0, s35
	s_nop 0
	buffer_load_dwordx4 v0, s[4:7], s21 offen lds
	s_waitcnt vmcnt(7)
	s_waitcnt lgkmcnt(0)
	s_setprio 1
	s_barrier
	v_mfma_f32_16x16x32_bf16 v[50:53], v[134:137], v[170:173], v[50:53]
	v_mfma_f32_16x16x32_bf16 v[30:33], v[142:145], v[170:173], v[30:33]
	v_mfma_f32_16x16x32_bf16 v[58:61], v[142:145], v[178:181], v[58:61]
	v_mfma_f32_16x16x32_bf16 v[62:65], v[134:137], v[178:181], v[62:65]
	v_mfma_f32_16x16x32_bf16 v[94:97], v[134:137], v[186:189], v[94:97]
	v_mfma_f32_16x16x32_bf16 v[82:85], v[142:145], v[186:189], v[82:85]
	v_mfma_f32_16x16x32_bf16 v[26:29], v[142:145], v[200:203], v[26:29]
	v_mfma_f32_16x16x32_bf16 v[46:49], v[134:137], v[200:203], v[46:49]
	v_mfma_f32_16x16x32_bf16 v[50:53], v[138:141], v[174:177], v[50:53]
	v_mfma_f32_16x16x32_bf16 v[30:33], v[146:149], v[174:177], v[30:33]
	v_mfma_f32_16x16x32_bf16 v[58:61], v[146:149], v[182:185], v[58:61]
	v_mfma_f32_16x16x32_bf16 v[62:65], v[138:141], v[182:185], v[62:65]
	v_mfma_f32_16x16x32_bf16 v[94:97], v[138:141], v[190:193], v[94:97]
	v_mfma_f32_16x16x32_bf16 v[82:85], v[146:149], v[190:193], v[82:85]
	v_mfma_f32_16x16x32_bf16 v[26:29], v[146:149], v[206:209], v[26:29]
	v_mfma_f32_16x16x32_bf16 v[46:49], v[138:141], v[206:209], v[46:49]
	v_mfma_f32_16x16x32_bf16 v[22:25], v[150:153], v[170:173], v[22:25]
	v_mfma_f32_16x16x32_bf16 v[10:13], v[158:161], v[170:173], v[10:13]
	v_mfma_f32_16x16x32_bf16 v[66:69], v[158:161], v[178:181], v[66:69]
	v_mfma_f32_16x16x32_bf16 v[54:57], v[150:153], v[178:181], v[54:57]
	v_mfma_f32_16x16x32_bf16 v[70:73], v[150:153], v[186:189], v[70:73]
	v_mfma_f32_16x16x32_bf16 v[42:45], v[158:161], v[186:189], v[42:45]
	v_mfma_f32_16x16x32_bf16 v[2:5], v[158:161], v[200:203], v[2:5]
	v_mfma_f32_16x16x32_bf16 v[6:9], v[150:153], v[200:203], v[6:9]
	v_mfma_f32_16x16x32_bf16 v[22:25], v[154:157], v[174:177], v[22:25]
	v_mfma_f32_16x16x32_bf16 v[10:13], v[166:169], v[174:177], v[10:13]
	v_mfma_f32_16x16x32_bf16 v[66:69], v[166:169], v[182:185], v[66:69]
	v_mfma_f32_16x16x32_bf16 v[54:57], v[154:157], v[182:185], v[54:57]
	v_mfma_f32_16x16x32_bf16 v[70:73], v[154:157], v[190:193], v[70:73]
	v_mfma_f32_16x16x32_bf16 v[42:45], v[166:169], v[190:193], v[42:45]
	v_mfma_f32_16x16x32_bf16 v[2:5], v[166:169], v[206:209], v[2:5]
	v_mfma_f32_16x16x32_bf16 v[6:9], v[154:157], v[206:209], v[6:9]
	s_barrier
; #define PG8_STAGE(bufoff, gbase, voff) do { const int so_ = (int)(unsigned)((const char*)(gbase) - base_##voff); _Pragma("unroll") for (int _i = 0; _i < 2; ++_i) \
;         __builtin_amdgcn_raw_ptr_buffer_load_lds(rs_##voff, (PG8_LAS unsigned*)(lds + (bufoff) + ldsw + _i * 8192), 16, (int)(voff)[_i], so_, 0, 0); } while (0)
; #define PG8_LDA(dst, b, h) do { _Pragma("unroll") for (int m = 0; m < 4; ++m) _Pragma("unroll") for (int k = 0; k < 2; ++k) dst[m][k] = *(const PG8_LAS bf16x8*)(lds + PG8_SA(b, h) + aoff + m * 2048 + k * 1024); } while (0)
; #define PG8_LDB(dst, b, h) do { _Pragma("unroll") for (int n = 0; n < 2; ++n) _Pragma("unroll") for (int k = 0; k < 2; ++k) dst[n][k] = *(const PG8_LAS bf16x8*)(lds + PG8_SB(b, h) + boff + n * 2048 + k * 1024); } while (0)
; #define PG8_MMA(ai, bj, At, Bt) do { __builtin_amdgcn_s_setprio(1); _Pragma("unroll") for (int m = 0; m < 4; ++m) _Pragma("unroll") for (int n = 0; n < 2; ++n) _Pragma("unroll") for (int k = 0; k < 2; ++k) \
;         acc[ai][bj][m][n] = __builtin_amdgcn_mfma_f32_16x16x32_bf16(Bt[n][k], At[m][k], acc[ai][bj][m][n], 0, 0, 0); __builtin_amdgcn_s_setprio(0); } while (0)
; #define PG8_WAIT_V(n) asm volatile("s_waitcnt vmcnt(" #n ")" ::: "memory")
; #define PG8_WAIT_L(n) asm volatile("s_waitcnt lgkmcnt(" #n ")" ::: "memory")
; #define PG8_BAR __builtin_amdgcn_s_barrier()
; #define PG8_SCHED __builtin_amdgcn_sched_barrier(0)
; template <class Epi, class Sched, bool ALIGN_EPI = false, bool SP2 = false>
; __device__ __forceinline__ void gemm_phase(PG8_LAS unsigned char* lds, const Gemm g, const Sched& S, const Epi& E, int tid_in) {
;     ...
;             PG8_LDB(B0, 1, 0); PG8_LDB(B1, 1, 1); PG8_SCHED; PG8_LDA(At, 1, 0); PG8_STAGE(PG8_SA(0, 1), a2 + hstepA, voffA);
;             PG8_WAIT_V(8); PG8_WAIT_L(0); PG8_BAR; PG8_MMA(0, 0, At, B0); PG8_MMA(0, 1, At, B1); PG8_BAR; PG8_SCHED;
;             PG8_LDA(At, 1, 1); PG8_STAGE(PG8_SB(1, 0), b3, voffB); PG8_STAGE(PG8_SB(1, 1), b3 + hstepB, voffB); PG8_STAGE(PG8_SA(1, 0), a3, voffA);
;             PG8_WAIT_V(8); PG8_WAIT_L(0); PG8_BAR; PG8_MMA(1, 0, At, B0); PG8_MMA(1, 1, At, B1); PG8_BAR; PG8_SCHED;
	v_add_u32_e32 v133, 0x18000, v131
	ds_read_b128 v[134:137], v133
	ds_read_b128 v[138:141], v133 offset:1024
	ds_read_b128 v[142:145], v133 offset:2048
	ds_read_b128 v[146:149], v133 offset:3072
	v_add_u32_e32 v133, 0x1c000, v131
	ds_read_b128 v[150:153], v133
	ds_read_b128 v[154:157], v133 offset:1024
	ds_read_b128 v[158:161], v133 offset:2048
	ds_read_b128 v[166:169], v133 offset:3072
	s_add_i32 vcc_lo, s21, 0x80000
	s_mov_b32 m0, s66
	ds_read_b128 v[170:173], v132 offset:32768
	ds_read_b128 v[174:177], v132 offset:33792
	ds_read_b128 v[178:181], v132 offset:34816
	ds_read_b128 v[182:185], v132 offset:35840
	ds_read_b128 v[186:189], v132 offset:36864
	ds_read_b128 v[190:193], v132 offset:37888
	ds_read_b128 v[200:203], v132 offset:38912
	ds_read_b128 v[206:209], v132 offset:39936
	s_setprio 0
	s_mov_b32 m0, s63
	s_nop 0
	buffer_load_dwordx4 v130, s[4:7], s21 offen lds
	s_mov_b32 m0, s66
	s_nop 0
	buffer_load_dwordx4 v0, s[4:7], vcc_lo offen lds
	s_mov_b32 m0, s67
	s_nop 0
	buffer_load_dwordx4 v130, s[4:7], vcc_lo offen lds
	s_waitcnt vmcnt(8)
	s_waitcnt lgkmcnt(0)
	s_setprio 1
	s_barrier
	v_mfma_f32_16x16x32_bf16 v[34:37], v[134:137], v[170:173], v[34:37]
	v_mfma_f32_16x16x32_bf16 v[18:21], v[142:145], v[170:173], v[18:21]
	v_mfma_f32_16x16x32_bf16 v[78:81], v[142:145], v[178:181], v[78:81]
	v_mfma_f32_16x16x32_bf16 v[86:89], v[134:137], v[178:181], v[86:89]
	v_mfma_f32_16x16x32_bf16 v[106:109], v[134:137], v[186:189], v[106:109]
	v_mfma_f32_16x16x32_bf16 v[102:105], v[142:145], v[186:189], v[102:105]
	v_mfma_f32_16x16x32_bf16 v[122:125], v[142:145], v[200:203], v[122:125]
	v_mfma_f32_16x16x32_bf16 v[126:129], v[134:137], v[200:203], v[126:129]
	v_mfma_f32_16x16x32_bf16 v[34:37], v[138:141], v[174:177], v[34:37]
	v_mfma_f32_16x16x32_bf16 v[18:21], v[146:149], v[174:177], v[18:21]
	v_mfma_f32_16x16x32_bf16 v[78:81], v[146:149], v[182:185], v[78:81]
	v_mfma_f32_16x16x32_bf16 v[86:89], v[138:141], v[182:185], v[86:89]
	v_mfma_f32_16x16x32_bf16 v[106:109], v[138:141], v[190:193], v[106:109]
	v_mfma_f32_16x16x32_bf16 v[102:105], v[146:149], v[190:193], v[102:105]
	v_mfma_f32_16x16x32_bf16 v[122:125], v[146:149], v[206:209], v[122:125]
	v_mfma_f32_16x16x32_bf16 v[126:129], v[138:141], v[206:209], v[126:129]
	v_mfma_f32_16x16x32_bf16 v[14:17], v[150:153], v[170:173], v[14:17]
	v_mfma_f32_16x16x32_bf16 v[38:41], v[158:161], v[170:173], v[38:41]
	v_mfma_f32_16x16x32_bf16 v[90:93], v[158:161], v[178:181], v[90:93]
	v_mfma_f32_16x16x32_bf16 v[74:77], v[150:153], v[178:181], v[74:77]
	v_mfma_f32_16x16x32_bf16 v[98:101], v[150:153], v[186:189], v[98:101]
	v_mfma_f32_16x16x32_bf16 v[110:113], v[158:161], v[186:189], v[110:113]
	v_mfma_f32_16x16x32_bf16 v[114:117], v[158:161], v[200:203], v[114:117]
	v_mfma_f32_16x16x32_bf16 v[118:121], v[150:153], v[200:203], v[118:121]
	v_mfma_f32_16x16x32_bf16 v[14:17], v[154:157], v[174:177], v[14:17]
	v_mfma_f32_16x16x32_bf16 v[38:41], v[166:169], v[174:177], v[38:41]
	v_mfma_f32_16x16x32_bf16 v[90:93], v[166:169], v[182:185], v[90:93]
	v_mfma_f32_16x16x32_bf16 v[74:77], v[154:157], v[182:185], v[74:77]
	v_mfma_f32_16x16x32_bf16 v[98:101], v[154:157], v[190:193], v[98:101]
	v_mfma_f32_16x16x32_bf16 v[110:113], v[166:169], v[190:193], v[110:113]
	v_mfma_f32_16x16x32_bf16 v[114:117], v[166:169], v[206:209], v[114:117]
	v_mfma_f32_16x16x32_bf16 v[118:121], v[154:157], v[206:209], v[118:121]
	s_barrier
	s_mov_b32 m0, s68
	s_add_i32 vcc_lo, s79, 0x80
	ds_read_b128 v[170:173], v132 offset:49152
	ds_read_b128 v[174:177], v132 offset:50176
	ds_read_b128 v[178:181], v132 offset:51200
	ds_read_b128 v[182:185], v132 offset:52224
	ds_read_b128 v[186:189], v132 offset:53248
	ds_read_b128 v[190:193], v132 offset:54272
	ds_read_b128 v[200:203], v132 offset:55296
	ds_read_b128 v[206:209], v132 offset:56320
	s_setprio 0
	buffer_load_dwordx4 v0, s[40:43], vcc_lo offen lds
	s_mov_b32 m0, s69
	s_add_i32 s79, s79, 0x80080
	buffer_load_dwordx4 v130, s[40:43], vcc_lo offen lds
	s_mov_b32 m0, s73
	s_addk_i32 s21, 0x80
	buffer_load_dwordx4 v0, s[40:43], s79 offen lds
	s_mov_b32 m0, s74
	s_nop 0
	buffer_load_dwordx4 v130, s[40:43], s79 offen lds
	s_mov_b32 m0, s71
	s_nop 0
	buffer_load_dwordx4 v0, s[4:7], s21 offen lds
	s_waitcnt vmcnt(7)
	s_waitcnt lgkmcnt(0)
	s_setprio 1
	s_barrier
;     static __device__ __forceinline__ bool last_of_chain(const Unit& u) { return (u.pn >> 3) == 2; }
; template <class Epi, class Sched, bool ALIGN_EPI = false, bool SP2 = false>
; __device__ __forceinline__ void gemm_phase(PG8_LAS unsigned char* lds, const Gemm g, const Sched& S, const Epi& E, int tid_in) {
;     ...
;             PG8_WAIT_V(8); PG8_WAIT_L(0); PG8_BAR; PG8_MMA(1, 0, At, B0); PG8_MMA(1, 1, At, B1); PG8_BAR; PG8_SCHED;
;             } else {
;             PG8_LDB(B0, 0, 0); PG8_SCHED; PG8_LDA(At, 0, 0); PG8_STAGE(PG8_SA(1, 1), a1 + hstepA, voffA);
;             PG8_WAIT_L(8); PG8_BAR; PG8_WAIT_L(0); PG8_MMA(0, 0, At, B0); PG8_BAR; PG8_SCHED;
;             PG8_LDB(B1, 0, 1); PG8_STAGE(PG8_SB(0, 0), b2, voffB);
;             PG8_BAR; PG8_WAIT_L(0); PG8_MMA(0, 1, At, B1); PG8_BAR;
;             PG8_LDA(At, 0, 1); PG8_STAGE(PG8_SA(0, 0), a2, voffA);
;             PG8_BAR; PG8_WAIT_L(0); PG8_MMA(1, 0, At, B0); PG8_BAR; PG8_SCHED;
;             PG8_STAGE(PG8_SB(0, 1), b2 + hstepB, voffB);
;             PG8_WAIT_V(6); PG8_BAR; PG8_MMA(1, 1, At, B1); PG8_BAR;
;             PG8_LDB(B0, 1, 0); PG8_SCHED; PG8_LDA(At, 1, 0); PG8_STAGE(PG8_SA(0, 1), a2 + hstepA, voffA);
;             PG8_WAIT_L(8); PG8_BAR; PG8_WAIT_L(0); PG8_MMA(0, 0, At, B0); PG8_BAR; PG8_SCHED;
;             PG8_LDB(B1, 1, 1); PG8_STAGE(PG8_SB(1, 0), b3, voffB);
;             PG8_BAR; PG8_WAIT_L(0); PG8_MMA(0, 1, At, B1); PG8_BAR;
;             PG8_LDA(At, 1, 1); PG8_STAGE(PG8_SA(1, 0), a3, voffA);
;             PG8_BAR; PG8_WAIT_L(0); PG8_MMA(1, 0, At, B0); PG8_BAR; PG8_SCHED;
;             PG8_STAGE(PG8_SB(1, 1), b3 + hstepB, voffB);
;             PG8_WAIT_V(6); PG8_BAR; PG8_MMA(1, 1, At, B1); PG8_BAR;
;             }
;         }
;         if constexpr (ALIGN_EPI) { if (wr == 0) PG8_BAR; }
;         if constexpr (!Epi::AFTER_DRAIN) { E(acc, cur, wr, wc, fr, fq); S.done(cur); }
;         if (!has_next) break;
;         bool zero_acc = true; if constexpr (Epi::CHAIN) zero_acc = Epi::last_of_chain(cur);
;         if (zero_acc) {
; #pragma unroll
;         for (int a = 0; a < 2; ++a)
; #pragma unroll
;             for (int b = 0; b < 2; ++b)
; #pragma unroll
;                 for (int m = 0; m < 4; ++m)
; #pragma unroll
;                     for (int n = 0; n < 2; ++n) acc[a][b][m][n] = (f32x4){0.f, 0.f, 0.f, 0.f};
;         }
;         cur = nxt; cA = nA; cB = nB; ++ui;
	v_mfma_f32_16x16x32_bf16 v[50:53], v[134:137], v[170:173], v[50:53]
	v_mfma_f32_16x16x32_bf16 v[30:33], v[142:145], v[170:173], v[30:33]
	v_mfma_f32_16x16x32_bf16 v[58:61], v[142:145], v[178:181], v[58:61]
	v_mfma_f32_16x16x32_bf16 v[62:65], v[134:137], v[178:181], v[62:65]
	v_mfma_f32_16x16x32_bf16 v[94:97], v[134:137], v[186:189], v[94:97]
	v_mfma_f32_16x16x32_bf16 v[82:85], v[142:145], v[186:189], v[82:85]
	v_mfma_f32_16x16x32_bf16 v[26:29], v[142:145], v[200:203], v[26:29]
	v_mfma_f32_16x16x32_bf16 v[46:49], v[134:137], v[200:203], v[46:49]
	v_mfma_f32_16x16x32_bf16 v[50:53], v[138:141], v[174:177], v[50:53]
	v_mfma_f32_16x16x32_bf16 v[30:33], v[146:149], v[174:177], v[30:33]
	v_mfma_f32_16x16x32_bf16 v[58:61], v[146:149], v[182:185], v[58:61]
	v_mfma_f32_16x16x32_bf16 v[62:65], v[138:141], v[182:185], v[62:65]
	v_mfma_f32_16x16x32_bf16 v[94:97], v[138:141], v[190:193], v[94:97]
	v_mfma_f32_16x16x32_bf16 v[82:85], v[146:149], v[190:193], v[82:85]
	v_mfma_f32_16x16x32_bf16 v[26:29], v[146:149], v[206:209], v[26:29]
	v_mfma_f32_16x16x32_bf16 v[46:49], v[138:141], v[206:209], v[46:49]
	v_mfma_f32_16x16x32_bf16 v[22:25], v[150:153], v[170:173], v[22:25]
	v_mfma_f32_16x16x32_bf16 v[10:13], v[158:161], v[170:173], v[10:13]
	v_mfma_f32_16x16x32_bf16 v[66:69], v[158:161], v[178:181], v[66:69]
	v_mfma_f32_16x16x32_bf16 v[54:57], v[150:153], v[178:181], v[54:57]
	v_mfma_f32_16x16x32_bf16 v[70:73], v[150:153], v[186:189], v[70:73]
	v_mfma_f32_16x16x32_bf16 v[42:45], v[158:161], v[186:189], v[42:45]
	v_mfma_f32_16x16x32_bf16 v[2:5], v[158:161], v[200:203], v[2:5]
	v_mfma_f32_16x16x32_bf16 v[6:9], v[150:153], v[200:203], v[6:9]
	v_mfma_f32_16x16x32_bf16 v[22:25], v[154:157], v[174:177], v[22:25]
	v_mfma_f32_16x16x32_bf16 v[10:13], v[166:169], v[174:177], v[10:13]
	v_mfma_f32_16x16x32_bf16 v[66:69], v[166:169], v[182:185], v[66:69]
	v_mfma_f32_16x16x32_bf16 v[54:57], v[154:157], v[182:185], v[54:57]
	v_mfma_f32_16x16x32_bf16 v[70:73], v[154:157], v[190:193], v[70:73]
	v_mfma_f32_16x16x32_bf16 v[42:45], v[166:169], v[190:193], v[42:45]
	v_mfma_f32_16x16x32_bf16 v[2:5], v[166:169], v[206:209], v[2:5]
	v_mfma_f32_16x16x32_bf16 v[6:9], v[154:157], v[206:209], v[6:9]
	s_barrier
	s_setprio 0
	s_add_i32 s19, s19, 2
	s_add_u32 s44, s44, 0x100
	s_addc_u32 s45, s45, 0
	s_cmp_gt_u32 s19, 29
	s_cbranch_scc0 .LBB0_1265
	s_andn2_b64 vcc, exec, s[38:39]
	s_cbranch_vccnz .LBB0_1257
	v_mov_b32_e32 v2, 0
	s_mov_b64 s[12:13], s[24:25]
	s_mov_b32 s10, s16
	s_mov_b32 s48, s20
	s_mov_b64 s[14:15], s[22:23]
	s_mov_b32 s13, s78
	v_mov_b32_e32 v3, v2
	v_mov_b32_e32 v4, v2
	v_mov_b32_e32 v5, v2
	v_mov_b32_e32 v6, v2
	v_mov_b32_e32 v7, v2
	v_mov_b32_e32 v8, v2
	v_mov_b32_e32 v9, v2
	v_mov_b32_e32 v42, v2
	v_mov_b32_e32 v43, v2
	v_mov_b32_e32 v44, v2
	v_mov_b32_e32 v45, v2
	v_mov_b32_e32 v70, v2
	v_mov_b32_e32 v71, v2
	v_mov_b32_e32 v72, v2
	v_mov_b32_e32 v73, v2
	v_mov_b32_e32 v66, v2
	v_mov_b32_e32 v67, v2
	v_mov_b32_e32 v68, v2
	v_mov_b32_e32 v69, v2
	v_mov_b32_e32 v54, v2
	v_mov_b32_e32 v55, v2
	v_mov_b32_e32 v56, v2
	v_mov_b32_e32 v57, v2
	v_mov_b32_e32 v10, v2
	v_mov_b32_e32 v11, v2
	v_mov_b32_e32 v12, v2
	v_mov_b32_e32 v13, v2
	v_mov_b32_e32 v22, v2
	v_mov_b32_e32 v23, v2
	v_mov_b32_e32 v24, v2
	v_mov_b32_e32 v25, v2
	v_mov_b32_e32 v26, v2
	v_mov_b32_e32 v27, v2
	v_mov_b32_e32 v28, v2
	v_mov_b32_e32 v29, v2
	v_mov_b32_e32 v46, v2
	v_mov_b32_e32 v47, v2
	v_mov_b32_e32 v48, v2
	v_mov_b32_e32 v49, v2
	v_mov_b32_e32 v82, v2
	v_mov_b32_e32 v83, v2
	v_mov_b32_e32 v84, v2
	v_mov_b32_e32 v85, v2
	v_mov_b32_e32 v94, v2
	v_mov_b32_e32 v95, v2
	v_mov_b32_e32 v96, v2
	v_mov_b32_e32 v97, v2
	v_mov_b32_e32 v58, v2
	v_mov_b32_e32 v59, v2
	v_mov_b32_e32 v60, v2
	v_mov_b32_e32 v61, v2
	v_mov_b32_e32 v62, v2
	v_mov_b32_e32 v63, v2
	v_mov_b32_e32 v64, v2
	v_mov_b32_e32 v65, v2
	v_mov_b32_e32 v30, v2
	v_mov_b32_e32 v31, v2
	v_mov_b32_e32 v32, v2
	v_mov_b32_e32 v33, v2
	v_mov_b32_e32 v50, v2
	v_mov_b32_e32 v51, v2
	v_mov_b32_e32 v52, v2
	v_mov_b32_e32 v53, v2
	v_mov_b32_e32 v114, v2
	v_mov_b32_e32 v115, v2
	v_mov_b32_e32 v116, v2
	v_mov_b32_e32 v117, v2
	v_mov_b32_e32 v118, v2
	v_mov_b32_e32 v119, v2
	v_mov_b32_e32 v120, v2
	v_mov_b32_e32 v121, v2
	v_mov_b32_e32 v110, v2
	v_mov_b32_e32 v111, v2
	v_mov_b32_e32 v112, v2
	v_mov_b32_e32 v113, v2
	v_mov_b32_e32 v98, v2
	v_mov_b32_e32 v99, v2
	v_mov_b32_e32 v100, v2
	v_mov_b32_e32 v101, v2
	v_mov_b32_e32 v90, v2
	v_mov_b32_e32 v91, v2
	v_mov_b32_e32 v92, v2
	v_mov_b32_e32 v93, v2
	v_mov_b32_e32 v74, v2
	v_mov_b32_e32 v75, v2
	v_mov_b32_e32 v76, v2
	v_mov_b32_e32 v77, v2
	v_mov_b32_e32 v38, v2
	v_mov_b32_e32 v39, v2
	v_mov_b32_e32 v40, v2
	v_mov_b32_e32 v41, v2
	v_mov_b32_e32 v14, v2
	v_mov_b32_e32 v15, v2
	v_mov_b32_e32 v16, v2
	v_mov_b32_e32 v17, v2
	v_mov_b32_e32 v122, v2
	v_mov_b32_e32 v123, v2
	v_mov_b32_e32 v124, v2
	v_mov_b32_e32 v125, v2
	v_mov_b32_e32 v126, v2
	v_mov_b32_e32 v127, v2
	v_mov_b32_e32 v128, v2
	v_mov_b32_e32 v129, v2
	v_mov_b32_e32 v102, v2
	v_mov_b32_e32 v103, v2
	v_mov_b32_e32 v104, v2
	v_mov_b32_e32 v105, v2
	v_mov_b32_e32 v106, v2
	v_mov_b32_e32 v107, v2
	v_mov_b32_e32 v108, v2
	v_mov_b32_e32 v109, v2
	v_mov_b32_e32 v78, v2
	v_mov_b32_e32 v79, v2
	v_mov_b32_e32 v80, v2
	v_mov_b32_e32 v81, v2
	v_mov_b32_e32 v86, v2
	v_mov_b32_e32 v87, v2
	v_mov_b32_e32 v88, v2
	v_mov_b32_e32 v89, v2
	v_mov_b32_e32 v18, v2
	v_mov_b32_e32 v19, v2
	v_mov_b32_e32 v20, v2
	v_mov_b32_e32 v21, v2
	v_mov_b32_e32 v34, v2
	v_mov_b32_e32 v35, v2
	v_mov_b32_e32 v36, v2
	v_mov_b32_e32 v37, v2
	s_branch .LBB0_1257

;     __host__ __device__ bool next(int i, Unit& u) const { const int t = i / 3, b = i - 3 * t; Unit v; if (!StaticOrder::next(t, v)) return false; u.pm = v.pm; u.pn = 8 * b + v.pn; return true; }
; #define PG8_STAGE(bufoff, gbase, voff) do { const int so_ = (int)(unsigned)((const char*)(gbase) - base_##voff); _Pragma("unroll") for (int _i = 0; _i < 2; ++_i) \
;         __builtin_amdgcn_raw_ptr_buffer_load_lds(rs_##voff, (PG8_LAS unsigned*)(lds + (bufoff) + ldsw + _i * 8192), 16, (int)(voff)[_i], so_, 0, 0); } while (0)
; #define PG8_LDA(dst, b, h) do { _Pragma("unroll") for (int m = 0; m < 4; ++m) _Pragma("unroll") for (int k = 0; k < 2; ++k) dst[m][k] = *(const PG8_LAS bf16x8*)(lds + PG8_SA(b, h) + aoff + m * 2048 + k * 1024); } while (0)
; #define PG8_WAIT_V(n) asm volatile("s_waitcnt vmcnt(" #n ")" ::: "memory")
; #define PG8_WAIT_L(n) asm volatile("s_waitcnt lgkmcnt(" #n ")" ::: "memory")
; #define PG8_BAR __builtin_amdgcn_s_barrier()
; template <class Epi, class Sched, bool ALIGN_EPI = false, bool SP2 = false>
; __device__ __forceinline__ void gemm_phase(PG8_LAS unsigned char* lds, const Gemm g, const Sched& S, const Epi& E, int tid_in) {
;     ...
;         const bool has_next = S.next(ui + 1, nxt);
;         const char* nA = has_next ? (const char*)g.A + (size_t)nxt.pm * tstepA + (g.grp ? (size_t)(nxt.pn / g.grp) * g.agrp : (size_t)0) : cA; const char* nB = has_next ? (const char*)g.Bt + (size_t)nxt.pn * tstepB : cB;
;         for (int t = 0; t < nt; t += 2) {
;             const bool last = (t == nt - 2);
;             const char* a1 = cA + (size_t)(t + 1) * kstep;
;             const char* a2 = last ? nA : cA + (size_t)(t + 2) * kstep; const char* b2 = last ? nB : cB + (size_t)(t + 2) * kstep;
;             const char* a3 = a2 + kstep; const char* b3 = b2 + kstep;
;             if (last && has_next) S.a_ready(nxt);
;             if constexpr (SP2) {
;             PG8_LDB(B0, 0, 0); PG8_LDB(B1, 0, 1); PG8_SCHED; PG8_LDA(At, 0, 0); PG8_STAGE(PG8_SA(1, 1), a1 + hstepA, voffA);
;             PG8_WAIT_V(8); PG8_WAIT_L(0); PG8_BAR; PG8_MMA(0, 0, At, B0); PG8_MMA(0, 1, At, B1); PG8_BAR; PG8_SCHED;
;             PG8_LDA(At, 0, 1); PG8_STAGE(PG8_SB(0, 0), b2, voffB); PG8_STAGE(PG8_SB(0, 1), b2 + hstepB, voffB); PG8_STAGE(PG8_SA(0, 0), a2, voffA);
;             PG8_WAIT_V(8); PG8_WAIT_L(0); PG8_BAR; PG8_MMA(1, 0, At, B0); PG8_MMA(1, 1, At, B1); PG8_BAR; PG8_SCHED;
.LBB0_1513:
	s_ashr_i32 s21, s20, 31
	s_lshl_b64 s[18:19], s[20:21], 20
	s_add_u32 s22, s4, s18
	s_addc_u32 s23, s9, s19
	s_and_b64 s[18:19], s[36:37], exec
	s_cselect_b32 s18, s22, s16
	s_ashr_i32 s15, s14, 31
	s_lshl_b64 s[24:25], s[14:15], 20
	s_add_u32 s24, s40, s24
	s_addc_u32 s25, s26, s25
	s_and_b64 s[42:43], s[36:37], exec
	s_cselect_b32 s15, s24, s38
	s_add_u32 s19, s38, 0x100
	v_mov_b32_e32 v2, 0
	s_addc_u32 s21, s39, 0
	s_mov_b32 s73, -2
	v_add_u32_e32 v141, 0x10000, v139
	ds_read_b128 v[130:133], v141
	ds_read_b128 v[142:145], v141 offset:1024
	ds_read_b128 v[146:149], v141 offset:2048
	ds_read_b128 v[150:153], v141 offset:3072
	v_add_u32_e32 v141, 0x14000, v139
	ds_read_b128 v[154:157], v141
	ds_read_b128 v[158:161], v141 offset:1024
	ds_read_b128 v[162:165], v141 offset:2048
	ds_read_b128 v[166:169], v141 offset:3072
	s_add_u32 s38, s16, 0x100
	s_addc_u32 s39, s17, 0
	s_sub_i32 s16, s16, s4
	s_add_i32 s16, s16, 0x80080
	s_sub_i32 s74, s16, 0x80000
	s_cmp_eq_u32 s73, 28
	s_cselect_b32 s17, s18, s38
	s_mov_b32 m0, s67
	ds_read_b128 v[170:173], v140
	ds_read_b128 v[174:177], v140 offset:1024
	ds_read_b128 v[178:181], v140 offset:2048
	ds_read_b128 v[182:185], v140 offset:3072
	ds_read_b128 v[186:189], v140 offset:4096
	ds_read_b128 v[190:193], v140 offset:5120
	ds_read_b128 v[200:203], v140 offset:6144
	ds_read_b128 v[206:209], v140 offset:7168
	s_mov_b32 m0, s62
	s_nop 0
	buffer_load_dwordx4 v135, s[4:7], s74 offen lds
	s_mov_b32 m0, s67
	s_nop 0
	buffer_load_dwordx4 v0, s[4:7], s16 offen lds
	s_mov_b32 m0, s68
	s_nop 0
	buffer_load_dwordx4 v135, s[4:7], s16 offen lds
	s_waitcnt vmcnt(8)
	s_waitcnt lgkmcnt(0)
	s_setprio 1
	s_barrier
	v_mfma_f32_16x16x32_bf16 v[126:129], v[130:133], v[170:173], 0
	v_mfma_f32_16x16x32_bf16 v[122:125], v[146:149], v[170:173], 0
	v_mfma_f32_16x16x32_bf16 v[106:109], v[146:149], v[178:181], 0
	v_mfma_f32_16x16x32_bf16 v[110:113], v[130:133], v[178:181], 0
	v_mfma_f32_16x16x32_bf16 v[94:97], v[130:133], v[186:189], 0
	v_mfma_f32_16x16x32_bf16 v[90:93], v[146:149], v[186:189], 0
	v_mfma_f32_16x16x32_bf16 v[74:77], v[146:149], v[200:203], 0
	v_mfma_f32_16x16x32_bf16 v[78:81], v[130:133], v[200:203], 0
	v_mfma_f32_16x16x32_bf16 v[126:129], v[142:145], v[174:177], v[126:129]
	v_mfma_f32_16x16x32_bf16 v[122:125], v[150:153], v[174:177], v[122:125]
	v_mfma_f32_16x16x32_bf16 v[106:109], v[150:153], v[182:185], v[106:109]
	v_mfma_f32_16x16x32_bf16 v[110:113], v[142:145], v[182:185], v[110:113]
	v_mfma_f32_16x16x32_bf16 v[94:97], v[142:145], v[190:193], v[94:97]
	v_mfma_f32_16x16x32_bf16 v[90:93], v[150:153], v[190:193], v[90:93]
	v_mfma_f32_16x16x32_bf16 v[74:77], v[150:153], v[206:209], v[74:77]
	v_mfma_f32_16x16x32_bf16 v[78:81], v[142:145], v[206:209], v[78:81]
	v_mfma_f32_16x16x32_bf16 v[118:121], v[154:157], v[170:173], 0
	v_mfma_f32_16x16x32_bf16 v[114:117], v[162:165], v[170:173], 0
	v_mfma_f32_16x16x32_bf16 v[98:101], v[162:165], v[178:181], 0
	v_mfma_f32_16x16x32_bf16 v[102:105], v[154:157], v[178:181], 0
	v_mfma_f32_16x16x32_bf16 v[86:89], v[154:157], v[186:189], 0
	v_mfma_f32_16x16x32_bf16 v[82:85], v[162:165], v[186:189], 0
	v_mfma_f32_16x16x32_bf16 v[66:69], v[162:165], v[200:203], 0
	v_mfma_f32_16x16x32_bf16 v[70:73], v[154:157], v[200:203], 0
	v_mfma_f32_16x16x32_bf16 v[118:121], v[158:161], v[174:177], v[118:121]
	v_mfma_f32_16x16x32_bf16 v[114:117], v[166:169], v[174:177], v[114:117]
	v_mfma_f32_16x16x32_bf16 v[98:101], v[166:169], v[182:185], v[98:101]
	v_mfma_f32_16x16x32_bf16 v[102:105], v[158:161], v[182:185], v[102:105]
	v_mfma_f32_16x16x32_bf16 v[86:89], v[158:161], v[190:193], v[86:89]
	v_mfma_f32_16x16x32_bf16 v[82:85], v[166:169], v[190:193], v[82:85]
	v_mfma_f32_16x16x32_bf16 v[66:69], v[166:169], v[206:209], v[66:69]
	v_mfma_f32_16x16x32_bf16 v[70:73], v[158:161], v[206:209], v[70:73]
	s_barrier
	s_cselect_b32 s16, s15, s19
	s_mov_b32 m0, s35
	s_mov_b32 s42, s6
	s_mov_b32 s43, s7
	s_sub_i32 s16, s16, s40
	ds_read_b128 v[170:173], v140 offset:16384
	ds_read_b128 v[174:177], v140 offset:17408
	ds_read_b128 v[178:181], v140 offset:18432
	ds_read_b128 v[182:185], v140 offset:19456
	ds_read_b128 v[186:189], v140 offset:20480
	ds_read_b128 v[190:193], v140 offset:21504
	ds_read_b128 v[200:203], v140 offset:22528
	ds_read_b128 v[206:209], v140 offset:23552
	s_setprio 0
	buffer_load_dwordx4 v134, s[40:43], s16 offen lds
	s_mov_b32 m0, s44
	s_add_i32 s74, s16, 0x80000
	buffer_load_dwordx4 v136, s[40:43], s16 offen lds
	s_mov_b32 m0, s45
	s_sub_i32 s17, s17, s4
	buffer_load_dwordx4 v134, s[40:43], s74 offen lds
	s_mov_b32 m0, s46
	s_nop 0
	buffer_load_dwordx4 v136, s[40:43], s74 offen lds
	s_mov_b32 m0, s34
	s_nop 0
	buffer_load_dwordx4 v0, s[4:7], s17 offen lds
	s_waitcnt vmcnt(7)
	s_waitcnt lgkmcnt(0)
	s_setprio 1
	s_barrier
; #define PG8_STAGE(bufoff, gbase, voff) do { const int so_ = (int)(unsigned)((const char*)(gbase) - base_##voff); _Pragma("unroll") for (int _i = 0; _i < 2; ++_i) \
;         __builtin_amdgcn_raw_ptr_buffer_load_lds(rs_##voff, (PG8_LAS unsigned*)(lds + (bufoff) + ldsw + _i * 8192), 16, (int)(voff)[_i], so_, 0, 0); } while (0)
; #define PG8_LDA(dst, b, h) do { _Pragma("unroll") for (int m = 0; m < 4; ++m) _Pragma("unroll") for (int k = 0; k < 2; ++k) dst[m][k] = *(const PG8_LAS bf16x8*)(lds + PG8_SA(b, h) + aoff + m * 2048 + k * 1024); } while (0)
; #define PG8_LDB(dst, b, h) do { _Pragma("unroll") for (int n = 0; n < 2; ++n) _Pragma("unroll") for (int k = 0; k < 2; ++k) dst[n][k] = *(const PG8_LAS bf16x8*)(lds + PG8_SB(b, h) + boff + n * 2048 + k * 1024); } while (0)
; #define PG8_MMA(ai, bj, At, Bt) do { __builtin_amdgcn_s_setprio(1); _Pragma("unroll") for (int m = 0; m < 4; ++m) _Pragma("unroll") for (int n = 0; n < 2; ++n) _Pragma("unroll") for (int k = 0; k < 2; ++k) \
;         acc[ai][bj][m][n] = __builtin_amdgcn_mfma_f32_16x16x32_bf16(Bt[n][k], At[m][k], acc[ai][bj][m][n], 0, 0, 0); __builtin_amdgcn_s_setprio(0); } while (0)
; #define PG8_WAIT_V(n) asm volatile("s_waitcnt vmcnt(" #n ")" ::: "memory")
; #define PG8_WAIT_L(n) asm volatile("s_waitcnt lgkmcnt(" #n ")" ::: "memory")
; #define PG8_BAR __builtin_amdgcn_s_barrier()
; #define PG8_SCHED __builtin_amdgcn_sched_barrier(0)
; template <class Epi, class Sched, bool ALIGN_EPI = false, bool SP2 = false>
; __device__ __forceinline__ void gemm_phase(PG8_LAS unsigned char* lds, const Gemm g, const Sched& S, const Epi& E, int tid_in) {
;     ...
;             PG8_WAIT_V(8); PG8_WAIT_L(0); PG8_BAR; PG8_MMA(1, 0, At, B0); PG8_MMA(1, 1, At, B1); PG8_BAR; PG8_SCHED;
;             PG8_LDB(B0, 1, 0); PG8_LDB(B1, 1, 1); PG8_SCHED; PG8_LDA(At, 1, 0); PG8_STAGE(PG8_SA(0, 1), a2 + hstepA, voffA);
;             PG8_WAIT_V(8); PG8_WAIT_L(0); PG8_BAR; PG8_MMA(0, 0, At, B0); PG8_MMA(0, 1, At, B1); PG8_BAR; PG8_SCHED;
	v_mfma_f32_16x16x32_bf16 v[62:65], v[130:133], v[170:173], 0
	v_mfma_f32_16x16x32_bf16 v[58:61], v[146:149], v[170:173], 0
	v_mfma_f32_16x16x32_bf16 v[42:45], v[146:149], v[178:181], 0
	v_mfma_f32_16x16x32_bf16 v[46:49], v[130:133], v[178:181], 0
	v_mfma_f32_16x16x32_bf16 v[30:33], v[130:133], v[186:189], 0
	v_mfma_f32_16x16x32_bf16 v[26:29], v[146:149], v[186:189], 0
	v_mfma_f32_16x16x32_bf16 v[10:13], v[146:149], v[200:203], 0
	v_mfma_f32_16x16x32_bf16 v[14:17], v[130:133], v[200:203], 0
	v_mfma_f32_16x16x32_bf16 v[62:65], v[142:145], v[174:177], v[62:65]
	v_mfma_f32_16x16x32_bf16 v[58:61], v[150:153], v[174:177], v[58:61]
	v_mfma_f32_16x16x32_bf16 v[42:45], v[150:153], v[182:185], v[42:45]
	v_mfma_f32_16x16x32_bf16 v[46:49], v[142:145], v[182:185], v[46:49]
	v_mfma_f32_16x16x32_bf16 v[30:33], v[142:145], v[190:193], v[30:33]
	v_mfma_f32_16x16x32_bf16 v[26:29], v[150:153], v[190:193], v[26:29]
	v_mfma_f32_16x16x32_bf16 v[10:13], v[150:153], v[206:209], v[10:13]
	v_mfma_f32_16x16x32_bf16 v[14:17], v[142:145], v[206:209], v[14:17]
	v_mfma_f32_16x16x32_bf16 v[54:57], v[154:157], v[170:173], 0
	v_mfma_f32_16x16x32_bf16 v[50:53], v[162:165], v[170:173], 0
	v_mfma_f32_16x16x32_bf16 v[34:37], v[162:165], v[178:181], 0
	v_mfma_f32_16x16x32_bf16 v[38:41], v[154:157], v[178:181], 0
	v_mfma_f32_16x16x32_bf16 v[22:25], v[154:157], v[186:189], 0
	v_mfma_f32_16x16x32_bf16 v[18:21], v[162:165], v[186:189], 0
	v_mfma_f32_16x16x32_bf16 v[2:5], v[162:165], v[200:203], 0
	v_mfma_f32_16x16x32_bf16 v[6:9], v[154:157], v[200:203], 0
	v_mfma_f32_16x16x32_bf16 v[54:57], v[158:161], v[174:177], v[54:57]
	v_mfma_f32_16x16x32_bf16 v[50:53], v[166:169], v[174:177], v[50:53]
	v_mfma_f32_16x16x32_bf16 v[34:37], v[166:169], v[182:185], v[34:37]
	v_mfma_f32_16x16x32_bf16 v[38:41], v[158:161], v[182:185], v[38:41]
	v_mfma_f32_16x16x32_bf16 v[22:25], v[158:161], v[190:193], v[22:25]
	v_mfma_f32_16x16x32_bf16 v[18:21], v[166:169], v[190:193], v[18:21]
	v_mfma_f32_16x16x32_bf16 v[2:5], v[166:169], v[206:209], v[2:5]
	v_mfma_f32_16x16x32_bf16 v[6:9], v[158:161], v[206:209], v[6:9]
	s_barrier
	v_add_u32_e32 v141, 0x18000, v139
	ds_read_b128 v[130:133], v141
	ds_read_b128 v[142:145], v141 offset:1024
	ds_read_b128 v[146:149], v141 offset:2048
	ds_read_b128 v[150:153], v141 offset:3072
	v_add_u32_e32 v141, 0x1c000, v139
	ds_read_b128 v[154:157], v141
	ds_read_b128 v[158:161], v141 offset:1024
	ds_read_b128 v[162:165], v141 offset:2048
	ds_read_b128 v[166:169], v141 offset:3072
	s_add_i32 s74, s17, 0x80000
	s_mov_b32 m0, s48
	ds_read_b128 v[170:173], v140 offset:32768
	ds_read_b128 v[174:177], v140 offset:33792
	ds_read_b128 v[178:181], v140 offset:34816
	ds_read_b128 v[182:185], v140 offset:35840
	ds_read_b128 v[186:189], v140 offset:36864
	ds_read_b128 v[190:193], v140 offset:37888
	ds_read_b128 v[200:203], v140 offset:38912
	ds_read_b128 v[206:209], v140 offset:39936
	s_setprio 0
	s_mov_b32 m0, s47
	s_nop 0
	buffer_load_dwordx4 v135, s[4:7], s17 offen lds
	s_mov_b32 m0, s48
	s_nop 0
	buffer_load_dwordx4 v0, s[4:7], s74 offen lds
	s_mov_b32 m0, s49
	s_nop 0
	buffer_load_dwordx4 v135, s[4:7], s74 offen lds
	s_waitcnt vmcnt(8)
	s_waitcnt lgkmcnt(0)
	s_setprio 1
	s_barrier
	v_mfma_f32_16x16x32_bf16 v[126:129], v[130:133], v[170:173], v[126:129]
	v_mfma_f32_16x16x32_bf16 v[122:125], v[146:149], v[170:173], v[122:125]
	v_mfma_f32_16x16x32_bf16 v[106:109], v[146:149], v[178:181], v[106:109]
	v_mfma_f32_16x16x32_bf16 v[110:113], v[130:133], v[178:181], v[110:113]
	v_mfma_f32_16x16x32_bf16 v[94:97], v[130:133], v[186:189], v[94:97]
	v_mfma_f32_16x16x32_bf16 v[90:93], v[146:149], v[186:189], v[90:93]
	v_mfma_f32_16x16x32_bf16 v[74:77], v[146:149], v[200:203], v[74:77]
	v_mfma_f32_16x16x32_bf16 v[78:81], v[130:133], v[200:203], v[78:81]
	v_mfma_f32_16x16x32_bf16 v[126:129], v[142:145], v[174:177], v[126:129]
	v_mfma_f32_16x16x32_bf16 v[122:125], v[150:153], v[174:177], v[122:125]
	v_mfma_f32_16x16x32_bf16 v[106:109], v[150:153], v[182:185], v[106:109]
	v_mfma_f32_16x16x32_bf16 v[110:113], v[142:145], v[182:185], v[110:113]
	v_mfma_f32_16x16x32_bf16 v[94:97], v[142:145], v[190:193], v[94:97]
	v_mfma_f32_16x16x32_bf16 v[90:93], v[150:153], v[190:193], v[90:93]
	v_mfma_f32_16x16x32_bf16 v[74:77], v[150:153], v[206:209], v[74:77]
	v_mfma_f32_16x16x32_bf16 v[78:81], v[142:145], v[206:209], v[78:81]
	v_mfma_f32_16x16x32_bf16 v[118:121], v[154:157], v[170:173], v[118:121]
	v_mfma_f32_16x16x32_bf16 v[114:117], v[162:165], v[170:173], v[114:117]
	v_mfma_f32_16x16x32_bf16 v[98:101], v[162:165], v[178:181], v[98:101]
	v_mfma_f32_16x16x32_bf16 v[102:105], v[154:157], v[178:181], v[102:105]
	v_mfma_f32_16x16x32_bf16 v[86:89], v[154:157], v[186:189], v[86:89]
	v_mfma_f32_16x16x32_bf16 v[82:85], v[162:165], v[186:189], v[82:85]
	v_mfma_f32_16x16x32_bf16 v[66:69], v[162:165], v[200:203], v[66:69]
	v_mfma_f32_16x16x32_bf16 v[70:73], v[154:157], v[200:203], v[70:73]
	v_mfma_f32_16x16x32_bf16 v[118:121], v[158:161], v[174:177], v[118:121]
	v_mfma_f32_16x16x32_bf16 v[114:117], v[166:169], v[174:177], v[114:117]
	v_mfma_f32_16x16x32_bf16 v[98:101], v[166:169], v[182:185], v[98:101]
	v_mfma_f32_16x16x32_bf16 v[102:105], v[158:161], v[182:185], v[102:105]
	v_mfma_f32_16x16x32_bf16 v[86:89], v[158:161], v[190:193], v[86:89]
	v_mfma_f32_16x16x32_bf16 v[82:85], v[166:169], v[190:193], v[82:85]
	v_mfma_f32_16x16x32_bf16 v[66:69], v[166:169], v[206:209], v[66:69]
	v_mfma_f32_16x16x32_bf16 v[70:73], v[158:161], v[206:209], v[70:73]
	s_barrier
; #define PG8_STAGE(bufoff, gbase, voff) do { const int so_ = (int)(unsigned)((const char*)(gbase) - base_##voff); _Pragma("unroll") for (int _i = 0; _i < 2; ++_i) \
;         __builtin_amdgcn_raw_ptr_buffer_load_lds(rs_##voff, (PG8_LAS unsigned*)(lds + (bufoff) + ldsw + _i * 8192), 16, (int)(voff)[_i], so_, 0, 0); } while (0)
; #define PG8_LDA(dst, b, h) do { _Pragma("unroll") for (int m = 0; m < 4; ++m) _Pragma("unroll") for (int k = 0; k < 2; ++k) dst[m][k] = *(const PG8_LAS bf16x8*)(lds + PG8_SA(b, h) + aoff + m * 2048 + k * 1024); } while (0)
; #define PG8_LDB(dst, b, h) do { _Pragma("unroll") for (int n = 0; n < 2; ++n) _Pragma("unroll") for (int k = 0; k < 2; ++k) dst[n][k] = *(const PG8_LAS bf16x8*)(lds + PG8_SB(b, h) + boff + n * 2048 + k * 1024); } while (0)
; #define PG8_MMA(ai, bj, At, Bt) do { __builtin_amdgcn_s_setprio(1); _Pragma("unroll") for (int m = 0; m < 4; ++m) _Pragma("unroll") for (int n = 0; n < 2; ++n) _Pragma("unroll") for (int k = 0; k < 2; ++k) \
;         acc[ai][bj][m][n] = __builtin_amdgcn_mfma_f32_16x16x32_bf16(Bt[n][k], At[m][k], acc[ai][bj][m][n], 0, 0, 0); __builtin_amdgcn_s_setprio(0); } while (0)
; template <class Epi, class Sched, bool ALIGN_EPI = false, bool SP2 = false>
; __device__ __forceinline__ void gemm_phase(PG8_LAS unsigned char* lds, const Gemm g, const Sched& S, const Epi& E, int tid_in) {
;     ...
;             PG8_LDB(B0, 0, 0); PG8_LDB(B1, 0, 1); PG8_SCHED; PG8_LDA(At, 0, 0); PG8_STAGE(PG8_SA(1, 1), a1 + hstepA, voffA);
;             PG8_WAIT_V(8); PG8_WAIT_L(0); PG8_BAR; PG8_MMA(0, 0, At, B0); PG8_MMA(0, 1, At, B1); PG8_BAR; PG8_SCHED;
;             PG8_LDA(At, 0, 1); PG8_STAGE(PG8_SB(0, 0), b2, voffB); PG8_STAGE(PG8_SB(0, 1), b2 + hstepB, voffB); PG8_STAGE(PG8_SA(0, 0), a2, voffA);
;             PG8_WAIT_V(8); PG8_WAIT_L(0); PG8_BAR; PG8_MMA(1, 0, At, B0); PG8_MMA(1, 1, At, B1); PG8_BAR; PG8_SCHED;
;             PG8_LDB(B0, 1, 0); PG8_LDB(B1, 1, 1); PG8_SCHED; PG8_LDA(At, 1, 0); PG8_STAGE(PG8_SA(0, 1), a2 + hstepA, voffA);
;             PG8_WAIT_V(8); PG8_WAIT_L(0); PG8_BAR; PG8_MMA(0, 0, At, B0); PG8_MMA(0, 1, At, B1); PG8_BAR; PG8_SCHED;
;             PG8_LDA(At, 1, 1); PG8_STAGE(PG8_SB(1, 0), b3, voffB); PG8_STAGE(PG8_SB(1, 1), b3 + hstepB, voffB); PG8_STAGE(PG8_SA(1, 0), a3, voffA);
;             PG8_WAIT_V(8); PG8_WAIT_L(0); PG8_BAR; PG8_MMA(1, 0, At, B0); PG8_MMA(1, 1, At, B1); PG8_BAR; PG8_SCHED;
	s_mov_b32 m0, s53
	s_add_i32 s74, s16, 0x80
	ds_read_b128 v[170:173], v140 offset:49152
	ds_read_b128 v[174:177], v140 offset:50176
	ds_read_b128 v[178:181], v140 offset:51200
	ds_read_b128 v[182:185], v140 offset:52224
	ds_read_b128 v[186:189], v140 offset:53248
	ds_read_b128 v[190:193], v140 offset:54272
	ds_read_b128 v[200:203], v140 offset:55296
	ds_read_b128 v[206:209], v140 offset:56320
	s_setprio 0
	buffer_load_dwordx4 v134, s[40:43], s74 offen lds
	s_mov_b32 m0, s60
	s_add_i32 s16, s16, 0x80080
	buffer_load_dwordx4 v136, s[40:43], s74 offen lds
	s_mov_b32 m0, s63
	s_addk_i32 s17, 0x80
	buffer_load_dwordx4 v134, s[40:43], s16 offen lds
	s_mov_b32 m0, s66
	s_nop 0
	buffer_load_dwordx4 v136, s[40:43], s16 offen lds
	s_mov_b32 m0, s61
	s_nop 0
	buffer_load_dwordx4 v0, s[4:7], s17 offen lds
	s_waitcnt vmcnt(7)
	s_waitcnt lgkmcnt(0)
	s_setprio 1
	s_barrier
	v_mfma_f32_16x16x32_bf16 v[62:65], v[130:133], v[170:173], v[62:65]
	v_mfma_f32_16x16x32_bf16 v[58:61], v[146:149], v[170:173], v[58:61]
	v_mfma_f32_16x16x32_bf16 v[42:45], v[146:149], v[178:181], v[42:45]
	v_mfma_f32_16x16x32_bf16 v[46:49], v[130:133], v[178:181], v[46:49]
	v_mfma_f32_16x16x32_bf16 v[30:33], v[130:133], v[186:189], v[30:33]
	v_mfma_f32_16x16x32_bf16 v[26:29], v[146:149], v[186:189], v[26:29]
	v_mfma_f32_16x16x32_bf16 v[10:13], v[146:149], v[200:203], v[10:13]
	v_mfma_f32_16x16x32_bf16 v[14:17], v[130:133], v[200:203], v[14:17]
	v_mfma_f32_16x16x32_bf16 v[62:65], v[142:145], v[174:177], v[62:65]
	v_mfma_f32_16x16x32_bf16 v[58:61], v[150:153], v[174:177], v[58:61]
	v_mfma_f32_16x16x32_bf16 v[42:45], v[150:153], v[182:185], v[42:45]
	v_mfma_f32_16x16x32_bf16 v[46:49], v[142:145], v[182:185], v[46:49]
	v_mfma_f32_16x16x32_bf16 v[30:33], v[142:145], v[190:193], v[30:33]
	v_mfma_f32_16x16x32_bf16 v[26:29], v[150:153], v[190:193], v[26:29]
	v_mfma_f32_16x16x32_bf16 v[10:13], v[150:153], v[206:209], v[10:13]
	v_mfma_f32_16x16x32_bf16 v[14:17], v[142:145], v[206:209], v[14:17]
	v_mfma_f32_16x16x32_bf16 v[54:57], v[154:157], v[170:173], v[54:57]
	v_mfma_f32_16x16x32_bf16 v[50:53], v[162:165], v[170:173], v[50:53]
	v_mfma_f32_16x16x32_bf16 v[34:37], v[162:165], v[178:181], v[34:37]
	v_mfma_f32_16x16x32_bf16 v[38:41], v[154:157], v[178:181], v[38:41]
	v_mfma_f32_16x16x32_bf16 v[22:25], v[154:157], v[186:189], v[22:25]
	v_mfma_f32_16x16x32_bf16 v[18:21], v[162:165], v[186:189], v[18:21]
	v_mfma_f32_16x16x32_bf16 v[2:5], v[162:165], v[200:203], v[2:5]
	v_mfma_f32_16x16x32_bf16 v[6:9], v[154:157], v[200:203], v[6:9]
	v_mfma_f32_16x16x32_bf16 v[54:57], v[158:161], v[174:177], v[54:57]
	v_mfma_f32_16x16x32_bf16 v[50:53], v[166:169], v[174:177], v[50:53]
	v_mfma_f32_16x16x32_bf16 v[34:37], v[166:169], v[182:185], v[34:37]
	v_mfma_f32_16x16x32_bf16 v[38:41], v[158:161], v[182:185], v[38:41]
	v_mfma_f32_16x16x32_bf16 v[22:25], v[158:161], v[190:193], v[22:25]
	v_mfma_f32_16x16x32_bf16 v[18:21], v[166:169], v[190:193], v[18:21]
	v_mfma_f32_16x16x32_bf16 v[2:5], v[166:169], v[206:209], v[2:5]
	v_mfma_f32_16x16x32_bf16 v[6:9], v[158:161], v[206:209], v[6:9]
	s_barrier
	s_setprio 0
	s_add_i32 s73, s73, 2
	s_add_u32 s19, s19, 0x100
	s_addc_u32 s21, s21, 0
	s_cmp_gt_u32 s73, 29
	s_mov_b64 s[16:17], s[38:39]
.LBB0_1514:
	v_add_u32_e32 v141, 0x10000, v139
	ds_read_b128 v[130:133], v141
	ds_read_b128 v[142:145], v141 offset:1024
	ds_read_b128 v[146:149], v141 offset:2048
	ds_read_b128 v[150:153], v141 offset:3072
	v_add_u32_e32 v141, 0x14000, v139
	ds_read_b128 v[154:157], v141
	ds_read_b128 v[158:161], v141 offset:1024
	ds_read_b128 v[162:165], v141 offset:2048
	ds_read_b128 v[166:169], v141 offset:3072
	s_add_u32 s38, s16, 0x100
	s_addc_u32 s39, s17, 0
	s_sub_i32 s16, s16, s4
	s_add_i32 s16, s16, 0x80080
	s_sub_i32 s74, s16, 0x80000
	s_cmp_eq_u32 s73, 28
	s_cselect_b32 s17, s18, s38
	s_mov_b32 m0, s67
	ds_read_b128 v[170:173], v140
	ds_read_b128 v[174:177], v140 offset:1024
	ds_read_b128 v[178:181], v140 offset:2048
	ds_read_b128 v[182:185], v140 offset:3072
	ds_read_b128 v[186:189], v140 offset:4096
	ds_read_b128 v[190:193], v140 offset:5120
	ds_read_b128 v[200:203], v140 offset:6144
	ds_read_b128 v[206:209], v140 offset:7168
	s_mov_b32 m0, s62
	s_nop 0
	buffer_load_dwordx4 v135, s[4:7], s74 offen lds
	s_mov_b32 m0, s67
	s_nop 0
	buffer_load_dwordx4 v0, s[4:7], s16 offen lds
	s_mov_b32 m0, s68
	s_nop 0
	buffer_load_dwordx4 v135, s[4:7], s16 offen lds
	s_waitcnt vmcnt(8)
	s_waitcnt lgkmcnt(0)
	s_setprio 1
	s_barrier
	v_mfma_f32_16x16x32_bf16 v[126:129], v[130:133], v[170:173], v[126:129]
	v_mfma_f32_16x16x32_bf16 v[122:125], v[146:149], v[170:173], v[122:125]
	v_mfma_f32_16x16x32_bf16 v[106:109], v[146:149], v[178:181], v[106:109]
	v_mfma_f32_16x16x32_bf16 v[110:113], v[130:133], v[178:181], v[110:113]
	v_mfma_f32_16x16x32_bf16 v[94:97], v[130:133], v[186:189], v[94:97]
	v_mfma_f32_16x16x32_bf16 v[90:93], v[146:149], v[186:189], v[90:93]
	v_mfma_f32_16x16x32_bf16 v[74:77], v[146:149], v[200:203], v[74:77]
	v_mfma_f32_16x16x32_bf16 v[78:81], v[130:133], v[200:203], v[78:81]
	v_mfma_f32_16x16x32_bf16 v[126:129], v[142:145], v[174:177], v[126:129]
	v_mfma_f32_16x16x32_bf16 v[122:125], v[150:153], v[174:177], v[122:125]
	v_mfma_f32_16x16x32_bf16 v[106:109], v[150:153], v[182:185], v[106:109]
	v_mfma_f32_16x16x32_bf16 v[110:113], v[142:145], v[182:185], v[110:113]
	v_mfma_f32_16x16x32_bf16 v[94:97], v[142:145], v[190:193], v[94:97]
	v_mfma_f32_16x16x32_bf16 v[90:93], v[150:153], v[190:193], v[90:93]
	v_mfma_f32_16x16x32_bf16 v[74:77], v[150:153], v[206:209], v[74:77]
	v_mfma_f32_16x16x32_bf16 v[78:81], v[142:145], v[206:209], v[78:81]
	v_mfma_f32_16x16x32_bf16 v[118:121], v[154:157], v[170:173], v[118:121]
	v_mfma_f32_16x16x32_bf16 v[114:117], v[162:165], v[170:173], v[114:117]
	v_mfma_f32_16x16x32_bf16 v[98:101], v[162:165], v[178:181], v[98:101]
	v_mfma_f32_16x16x32_bf16 v[102:105], v[154:157], v[178:181], v[102:105]
	v_mfma_f32_16x16x32_bf16 v[86:89], v[154:157], v[186:189], v[86:89]
	v_mfma_f32_16x16x32_bf16 v[82:85], v[162:165], v[186:189], v[82:85]
	v_mfma_f32_16x16x32_bf16 v[66:69], v[162:165], v[200:203], v[66:69]
	v_mfma_f32_16x16x32_bf16 v[70:73], v[154:157], v[200:203], v[70:73]
	v_mfma_f32_16x16x32_bf16 v[118:121], v[158:161], v[174:177], v[118:121]
	v_mfma_f32_16x16x32_bf16 v[114:117], v[166:169], v[174:177], v[114:117]
	v_mfma_f32_16x16x32_bf16 v[98:101], v[166:169], v[182:185], v[98:101]
	v_mfma_f32_16x16x32_bf16 v[102:105], v[158:161], v[182:185], v[102:105]
	v_mfma_f32_16x16x32_bf16 v[86:89], v[158:161], v[190:193], v[86:89]
	v_mfma_f32_16x16x32_bf16 v[82:85], v[166:169], v[190:193], v[82:85]
	v_mfma_f32_16x16x32_bf16 v[66:69], v[166:169], v[206:209], v[66:69]
	v_mfma_f32_16x16x32_bf16 v[70:73], v[158:161], v[206:209], v[70:73]
	s_barrier
; #define PG8_STAGE(bufoff, gbase, voff) do { const int so_ = (int)(unsigned)((const char*)(gbase) - base_##voff); _Pragma("unroll") for (int _i = 0; _i < 2; ++_i) \
;         __builtin_amdgcn_raw_ptr_buffer_load_lds(rs_##voff, (PG8_LAS unsigned*)(lds + (bufoff) + ldsw + _i * 8192), 16, (int)(voff)[_i], so_, 0, 0); } while (0)
; #define PG8_LDA(dst, b, h) do { _Pragma("unroll") for (int m = 0; m < 4; ++m) _Pragma("unroll") for (int k = 0; k < 2; ++k) dst[m][k] = *(const PG8_LAS bf16x8*)(lds + PG8_SA(b, h) + aoff + m * 2048 + k * 1024); } while (0)
; #define PG8_LDB(dst, b, h) do { _Pragma("unroll") for (int n = 0; n < 2; ++n) _Pragma("unroll") for (int k = 0; k < 2; ++k) dst[n][k] = *(const PG8_LAS bf16x8*)(lds + PG8_SB(b, h) + boff + n * 2048 + k * 1024); } while (0)
; #define PG8_MMA(ai, bj, At, Bt) do { __builtin_amdgcn_s_setprio(1); _Pragma("unroll") for (int m = 0; m < 4; ++m) _Pragma("unroll") for (int n = 0; n < 2; ++n) _Pragma("unroll") for (int k = 0; k < 2; ++k) \
;         acc[ai][bj][m][n] = __builtin_amdgcn_mfma_f32_16x16x32_bf16(Bt[n][k], At[m][k], acc[ai][bj][m][n], 0, 0, 0); __builtin_amdgcn_s_setprio(0); } while (0)
; #define PG8_WAIT_V(n) asm volatile("s_waitcnt vmcnt(" #n ")" ::: "memory")
; #define PG8_WAIT_L(n) asm volatile("s_waitcnt lgkmcnt(" #n ")" ::: "memory")
; #define PG8_BAR __builtin_amdgcn_s_barrier()
; #define PG8_SCHED __builtin_amdgcn_sched_barrier(0)
; template <class Epi, class Sched, bool ALIGN_EPI = false, bool SP2 = false>
; __device__ __forceinline__ void gemm_phase(PG8_LAS unsigned char* lds, const Gemm g, const Sched& S, const Epi& E, int tid_in) {
;     ...
;             PG8_LDA(At, 0, 1); PG8_STAGE(PG8_SB(0, 0), b2, voffB); PG8_STAGE(PG8_SB(0, 1), b2 + hstepB, voffB); PG8_STAGE(PG8_SA(0, 0), a2, voffA);
;             PG8_WAIT_V(8); PG8_WAIT_L(0); PG8_BAR; PG8_MMA(1, 0, At, B0); PG8_MMA(1, 1, At, B1); PG8_BAR; PG8_SCHED;
;             PG8_LDB(B0, 1, 0); PG8_LDB(B1, 1, 1); PG8_SCHED; PG8_LDA(At, 1, 0); PG8_STAGE(PG8_SA(0, 1), a2 + hstepA, voffA);
;             PG8_WAIT_V(8); PG8_WAIT_L(0); PG8_BAR; PG8_MMA(0, 0, At, B0); PG8_MMA(0, 1, At, B1); PG8_BAR; PG8_SCHED;
	s_cselect_b32 s16, s15, s19
	s_mov_b32 m0, s35
	s_mov_b32 s42, s6
	s_mov_b32 s43, s7
	s_sub_i32 s16, s16, s40
	ds_read_b128 v[170:173], v140 offset:16384
	ds_read_b128 v[174:177], v140 offset:17408
	ds_read_b128 v[178:181], v140 offset:18432
	ds_read_b128 v[182:185], v140 offset:19456
	ds_read_b128 v[186:189], v140 offset:20480
	ds_read_b128 v[190:193], v140 offset:21504
	ds_read_b128 v[200:203], v140 offset:22528
	ds_read_b128 v[206:209], v140 offset:23552
	s_setprio 0
	buffer_load_dwordx4 v134, s[40:43], s16 offen lds
	s_mov_b32 m0, s44
	s_add_i32 s74, s16, 0x80000
	buffer_load_dwordx4 v136, s[40:43], s16 offen lds
	s_mov_b32 m0, s45
	s_sub_i32 s17, s17, s4
	buffer_load_dwordx4 v134, s[40:43], s74 offen lds
	s_mov_b32 m0, s46
	s_nop 0
	buffer_load_dwordx4 v136, s[40:43], s74 offen lds
	s_mov_b32 m0, s34
	s_nop 0
	buffer_load_dwordx4 v0, s[4:7], s17 offen lds
	s_waitcnt vmcnt(7)
	s_waitcnt lgkmcnt(0)
	s_setprio 1
	s_barrier
	v_mfma_f32_16x16x32_bf16 v[62:65], v[130:133], v[170:173], v[62:65]
	v_mfma_f32_16x16x32_bf16 v[58:61], v[146:149], v[170:173], v[58:61]
	v_mfma_f32_16x16x32_bf16 v[42:45], v[146:149], v[178:181], v[42:45]
	v_mfma_f32_16x16x32_bf16 v[46:49], v[130:133], v[178:181], v[46:49]
	v_mfma_f32_16x16x32_bf16 v[30:33], v[130:133], v[186:189], v[30:33]
	v_mfma_f32_16x16x32_bf16 v[26:29], v[146:149], v[186:189], v[26:29]
	v_mfma_f32_16x16x32_bf16 v[10:13], v[146:149], v[200:203], v[10:13]
	v_mfma_f32_16x16x32_bf16 v[14:17], v[130:133], v[200:203], v[14:17]
	v_mfma_f32_16x16x32_bf16 v[62:65], v[142:145], v[174:177], v[62:65]
	v_mfma_f32_16x16x32_bf16 v[58:61], v[150:153], v[174:177], v[58:61]
	v_mfma_f32_16x16x32_bf16 v[42:45], v[150:153], v[182:185], v[42:45]
	v_mfma_f32_16x16x32_bf16 v[46:49], v[142:145], v[182:185], v[46:49]
	v_mfma_f32_16x16x32_bf16 v[30:33], v[142:145], v[190:193], v[30:33]
	v_mfma_f32_16x16x32_bf16 v[26:29], v[150:153], v[190:193], v[26:29]
	v_mfma_f32_16x16x32_bf16 v[10:13], v[150:153], v[206:209], v[10:13]
	v_mfma_f32_16x16x32_bf16 v[14:17], v[142:145], v[206:209], v[14:17]
	v_mfma_f32_16x16x32_bf16 v[54:57], v[154:157], v[170:173], v[54:57]
	v_mfma_f32_16x16x32_bf16 v[50:53], v[162:165], v[170:173], v[50:53]
	v_mfma_f32_16x16x32_bf16 v[34:37], v[162:165], v[178:181], v[34:37]
	v_mfma_f32_16x16x32_bf16 v[38:41], v[154:157], v[178:181], v[38:41]
	v_mfma_f32_16x16x32_bf16 v[22:25], v[154:157], v[186:189], v[22:25]
	v_mfma_f32_16x16x32_bf16 v[18:21], v[162:165], v[186:189], v[18:21]
	v_mfma_f32_16x16x32_bf16 v[2:5], v[162:165], v[200:203], v[2:5]
	v_mfma_f32_16x16x32_bf16 v[6:9], v[154:157], v[200:203], v[6:9]
	v_mfma_f32_16x16x32_bf16 v[54:57], v[158:161], v[174:177], v[54:57]
	v_mfma_f32_16x16x32_bf16 v[50:53], v[166:169], v[174:177], v[50:53]
	v_mfma_f32_16x16x32_bf16 v[34:37], v[166:169], v[182:185], v[34:37]
	v_mfma_f32_16x16x32_bf16 v[38:41], v[158:161], v[182:185], v[38:41]
	v_mfma_f32_16x16x32_bf16 v[22:25], v[158:161], v[190:193], v[22:25]
	v_mfma_f32_16x16x32_bf16 v[18:21], v[166:169], v[190:193], v[18:21]
	v_mfma_f32_16x16x32_bf16 v[2:5], v[166:169], v[206:209], v[2:5]
	v_mfma_f32_16x16x32_bf16 v[6:9], v[158:161], v[206:209], v[6:9]
	s_barrier
	v_add_u32_e32 v141, 0x18000, v139
	ds_read_b128 v[130:133], v141
	ds_read_b128 v[142:145], v141 offset:1024
	ds_read_b128 v[146:149], v141 offset:2048
	ds_read_b128 v[150:153], v141 offset:3072
	v_add_u32_e32 v141, 0x1c000, v139
	ds_read_b128 v[154:157], v141
	ds_read_b128 v[158:161], v141 offset:1024
	ds_read_b128 v[162:165], v141 offset:2048
	ds_read_b128 v[166:169], v141 offset:3072
	s_add_i32 s74, s17, 0x80000
	s_mov_b32 m0, s48
	ds_read_b128 v[170:173], v140 offset:32768
	ds_read_b128 v[174:177], v140 offset:33792
	ds_read_b128 v[178:181], v140 offset:34816
	ds_read_b128 v[182:185], v140 offset:35840
	ds_read_b128 v[186:189], v140 offset:36864
	ds_read_b128 v[190:193], v140 offset:37888
	ds_read_b128 v[200:203], v140 offset:38912
	ds_read_b128 v[206:209], v140 offset:39936
	s_setprio 0
	s_mov_b32 m0, s47
	s_nop 0
	buffer_load_dwordx4 v135, s[4:7], s17 offen lds
	s_mov_b32 m0, s48
	s_nop 0
	buffer_load_dwordx4 v0, s[4:7], s74 offen lds
	s_mov_b32 m0, s49
	s_nop 0
	buffer_load_dwordx4 v135, s[4:7], s74 offen lds
	s_waitcnt vmcnt(8)
	s_waitcnt lgkmcnt(0)
	s_setprio 1
	s_barrier
; #define PG8_STAGE(bufoff, gbase, voff) do { const int so_ = (int)(unsigned)((const char*)(gbase) - base_##voff); _Pragma("unroll") for (int _i = 0; _i < 2; ++_i) \
;         __builtin_amdgcn_raw_ptr_buffer_load_lds(rs_##voff, (PG8_LAS unsigned*)(lds + (bufoff) + ldsw + _i * 8192), 16, (int)(voff)[_i], so_, 0, 0); } while (0)
; #define PG8_WAIT_V(n) asm volatile("s_waitcnt vmcnt(" #n ")" ::: "memory")
; template <class Epi, class Sched, bool ALIGN_EPI = false, bool SP2 = false>
; __device__ __forceinline__ void gemm_phase(PG8_LAS unsigned char* lds, const Gemm g, const Sched& S, const Epi& E, int tid_in) {
;     ...
;             PG8_WAIT_V(8); PG8_WAIT_L(0); PG8_BAR; PG8_MMA(0, 0, At, B0); PG8_MMA(0, 1, At, B1); PG8_BAR; PG8_SCHED;
;             PG8_LDA(At, 1, 1); PG8_STAGE(PG8_SB(1, 0), b3, voffB); PG8_STAGE(PG8_SB(1, 1), b3 + hstepB, voffB); PG8_STAGE(PG8_SA(1, 0), a3, voffA);
;             PG8_WAIT_V(8); PG8_WAIT_L(0); PG8_BAR; PG8_MMA(1, 0, At, B0); PG8_MMA(1, 1, At, B1); PG8_BAR; PG8_SCHED;
;             } else {
;             PG8_LDB(B0, 0, 0); PG8_SCHED; PG8_LDA(At, 0, 0); PG8_STAGE(PG8_SA(1, 1), a1 + hstepA, voffA);
;             PG8_WAIT_L(8); PG8_BAR; PG8_WAIT_L(0); PG8_MMA(0, 0, At, B0); PG8_BAR; PG8_SCHED;
;             PG8_LDB(B1, 0, 1); PG8_STAGE(PG8_SB(0, 0), b2, voffB);
;             PG8_BAR; PG8_WAIT_L(0); PG8_MMA(0, 1, At, B1); PG8_BAR;
;             PG8_LDA(At, 0, 1); PG8_STAGE(PG8_SA(0, 0), a2, voffA);
;             PG8_BAR; PG8_WAIT_L(0); PG8_MMA(1, 0, At, B0); PG8_BAR; PG8_SCHED;
;             PG8_STAGE(PG8_SB(0, 1), b2 + hstepB, voffB);
;             PG8_WAIT_V(6); PG8_BAR; PG8_MMA(1, 1, At, B1); PG8_BAR;
;             PG8_LDB(B0, 1, 0); PG8_SCHED; PG8_LDA(At, 1, 0); PG8_STAGE(PG8_SA(0, 1), a2 + hstepA, voffA);
;             PG8_WAIT_L(8); PG8_BAR; PG8_WAIT_L(0); PG8_MMA(0, 0, At, B0); PG8_BAR; PG8_SCHED;
;             PG8_LDB(B1, 1, 1); PG8_STAGE(PG8_SB(1, 0), b3, voffB);
;             PG8_BAR; PG8_WAIT_L(0); PG8_MMA(0, 1, At, B1); PG8_BAR;
;             PG8_LDA(At, 1, 1); PG8_STAGE(PG8_SA(1, 0), a3, voffA);
;             PG8_BAR; PG8_WAIT_L(0); PG8_MMA(1, 0, At, B0); PG8_BAR; PG8_SCHED;
;             PG8_STAGE(PG8_SB(1, 1), b3 + hstepB, voffB);
;             PG8_WAIT_V(6); PG8_BAR; PG8_MMA(1, 1, At, B1); PG8_BAR;
;             }
;         }
;         if constexpr (ALIGN_EPI) { if (wr == 0) PG8_BAR; }
	v_mfma_f32_16x16x32_bf16 v[126:129], v[130:133], v[170:173], v[126:129]
	v_mfma_f32_16x16x32_bf16 v[122:125], v[146:149], v[170:173], v[122:125]
	v_mfma_f32_16x16x32_bf16 v[106:109], v[146:149], v[178:181], v[106:109]
	v_mfma_f32_16x16x32_bf16 v[110:113], v[130:133], v[178:181], v[110:113]
	v_mfma_f32_16x16x32_bf16 v[94:97], v[130:133], v[186:189], v[94:97]
	v_mfma_f32_16x16x32_bf16 v[90:93], v[146:149], v[186:189], v[90:93]
	v_mfma_f32_16x16x32_bf16 v[74:77], v[146:149], v[200:203], v[74:77]
	v_mfma_f32_16x16x32_bf16 v[78:81], v[130:133], v[200:203], v[78:81]
	v_mfma_f32_16x16x32_bf16 v[126:129], v[142:145], v[174:177], v[126:129]
	v_mfma_f32_16x16x32_bf16 v[122:125], v[150:153], v[174:177], v[122:125]
	v_mfma_f32_16x16x32_bf16 v[106:109], v[150:153], v[182:185], v[106:109]
	v_mfma_f32_16x16x32_bf16 v[110:113], v[142:145], v[182:185], v[110:113]
	v_mfma_f32_16x16x32_bf16 v[94:97], v[142:145], v[190:193], v[94:97]
	v_mfma_f32_16x16x32_bf16 v[90:93], v[150:153], v[190:193], v[90:93]
	v_mfma_f32_16x16x32_bf16 v[74:77], v[150:153], v[206:209], v[74:77]
	v_mfma_f32_16x16x32_bf16 v[78:81], v[142:145], v[206:209], v[78:81]
	v_mfma_f32_16x16x32_bf16 v[118:121], v[154:157], v[170:173], v[118:121]
	v_mfma_f32_16x16x32_bf16 v[114:117], v[162:165], v[170:173], v[114:117]
	v_mfma_f32_16x16x32_bf16 v[98:101], v[162:165], v[178:181], v[98:101]
	v_mfma_f32_16x16x32_bf16 v[102:105], v[154:157], v[178:181], v[102:105]
	v_mfma_f32_16x16x32_bf16 v[86:89], v[154:157], v[186:189], v[86:89]
	v_mfma_f32_16x16x32_bf16 v[82:85], v[162:165], v[186:189], v[82:85]
	v_mfma_f32_16x16x32_bf16 v[66:69], v[162:165], v[200:203], v[66:69]
	v_mfma_f32_16x16x32_bf16 v[70:73], v[154:157], v[200:203], v[70:73]
	v_mfma_f32_16x16x32_bf16 v[118:121], v[158:161], v[174:177], v[118:121]
	v_mfma_f32_16x16x32_bf16 v[114:117], v[166:169], v[174:177], v[114:117]
	v_mfma_f32_16x16x32_bf16 v[98:101], v[166:169], v[182:185], v[98:101]
	v_mfma_f32_16x16x32_bf16 v[102:105], v[158:161], v[182:185], v[102:105]
	v_mfma_f32_16x16x32_bf16 v[86:89], v[158:161], v[190:193], v[86:89]
	v_mfma_f32_16x16x32_bf16 v[82:85], v[166:169], v[190:193], v[82:85]
	v_mfma_f32_16x16x32_bf16 v[66:69], v[166:169], v[206:209], v[66:69]
	v_mfma_f32_16x16x32_bf16 v[70:73], v[158:161], v[206:209], v[70:73]
	s_barrier
	s_mov_b32 m0, s53
	s_add_i32 s74, s16, 0x80
	ds_read_b128 v[170:173], v140 offset:49152
	ds_read_b128 v[174:177], v140 offset:50176
	ds_read_b128 v[178:181], v140 offset:51200
	ds_read_b128 v[182:185], v140 offset:52224
	ds_read_b128 v[186:189], v140 offset:53248
	ds_read_b128 v[190:193], v140 offset:54272
	ds_read_b128 v[200:203], v140 offset:55296
	ds_read_b128 v[206:209], v140 offset:56320
	s_setprio 0
	buffer_load_dwordx4 v134, s[40:43], s74 offen lds
	s_mov_b32 m0, s60
	s_add_i32 s16, s16, 0x80080
	buffer_load_dwordx4 v136, s[40:43], s74 offen lds
	s_mov_b32 m0, s63
	s_addk_i32 s17, 0x80
	buffer_load_dwordx4 v134, s[40:43], s16 offen lds
	s_mov_b32 m0, s66
	s_nop 0
	buffer_load_dwordx4 v136, s[40:43], s16 offen lds
	s_mov_b32 m0, s61
	s_nop 0
	buffer_load_dwordx4 v0, s[4:7], s17 offen lds
	s_waitcnt vmcnt(7)
	s_waitcnt lgkmcnt(0)
	s_setprio 1
	s_barrier
	v_mfma_f32_16x16x32_bf16 v[62:65], v[130:133], v[170:173], v[62:65]
	v_mfma_f32_16x16x32_bf16 v[58:61], v[146:149], v[170:173], v[58:61]
	v_mfma_f32_16x16x32_bf16 v[42:45], v[146:149], v[178:181], v[42:45]
	v_mfma_f32_16x16x32_bf16 v[46:49], v[130:133], v[178:181], v[46:49]
	v_mfma_f32_16x16x32_bf16 v[30:33], v[130:133], v[186:189], v[30:33]
	v_mfma_f32_16x16x32_bf16 v[26:29], v[146:149], v[186:189], v[26:29]
	v_mfma_f32_16x16x32_bf16 v[10:13], v[146:149], v[200:203], v[10:13]
	v_mfma_f32_16x16x32_bf16 v[14:17], v[130:133], v[200:203], v[14:17]
	v_mfma_f32_16x16x32_bf16 v[62:65], v[142:145], v[174:177], v[62:65]
	v_mfma_f32_16x16x32_bf16 v[58:61], v[150:153], v[174:177], v[58:61]
	v_mfma_f32_16x16x32_bf16 v[42:45], v[150:153], v[182:185], v[42:45]
	v_mfma_f32_16x16x32_bf16 v[46:49], v[142:145], v[182:185], v[46:49]
	v_mfma_f32_16x16x32_bf16 v[30:33], v[142:145], v[190:193], v[30:33]
	v_mfma_f32_16x16x32_bf16 v[26:29], v[150:153], v[190:193], v[26:29]
	v_mfma_f32_16x16x32_bf16 v[10:13], v[150:153], v[206:209], v[10:13]
	v_mfma_f32_16x16x32_bf16 v[14:17], v[142:145], v[206:209], v[14:17]
	v_mfma_f32_16x16x32_bf16 v[54:57], v[154:157], v[170:173], v[54:57]
	v_mfma_f32_16x16x32_bf16 v[50:53], v[162:165], v[170:173], v[50:53]
	v_mfma_f32_16x16x32_bf16 v[34:37], v[162:165], v[178:181], v[34:37]
	v_mfma_f32_16x16x32_bf16 v[38:41], v[154:157], v[178:181], v[38:41]
	v_mfma_f32_16x16x32_bf16 v[22:25], v[154:157], v[186:189], v[22:25]
	v_mfma_f32_16x16x32_bf16 v[18:21], v[162:165], v[186:189], v[18:21]
	v_mfma_f32_16x16x32_bf16 v[2:5], v[162:165], v[200:203], v[2:5]
	v_mfma_f32_16x16x32_bf16 v[6:9], v[154:157], v[200:203], v[6:9]
	v_mfma_f32_16x16x32_bf16 v[54:57], v[158:161], v[174:177], v[54:57]
	v_mfma_f32_16x16x32_bf16 v[50:53], v[166:169], v[174:177], v[50:53]
	v_mfma_f32_16x16x32_bf16 v[34:37], v[166:169], v[182:185], v[34:37]
	v_mfma_f32_16x16x32_bf16 v[38:41], v[158:161], v[182:185], v[38:41]
	v_mfma_f32_16x16x32_bf16 v[22:25], v[158:161], v[190:193], v[22:25]
	v_mfma_f32_16x16x32_bf16 v[18:21], v[166:169], v[190:193], v[18:21]
	v_mfma_f32_16x16x32_bf16 v[2:5], v[166:169], v[206:209], v[2:5]
	v_mfma_f32_16x16x32_bf16 v[6:9], v[158:161], v[206:209], v[6:9]
	s_barrier
	s_setprio 0
	s_add_i32 s73, s73, 2
	s_add_u32 s19, s19, 0x100
	s_addc_u32 s21, s21, 0
	s_cmp_gt_u32 s73, 29
	s_mov_b64 s[16:17], s[38:39]
	s_cbranch_scc0 .LBB0_1514
	s_and_b64 vcc, exec, s[12:13]
	s_cbranch_vccz .LBB0_1517
	s_barrier

; #define PG8_STAGE(bufoff, gbase, voff) do { const int so_ = (int)(unsigned)((const char*)(gbase) - base_##voff); _Pragma("unroll") for (int _i = 0; _i < 2; ++_i) \
;         __builtin_amdgcn_raw_ptr_buffer_load_lds(rs_##voff, (PG8_LAS unsigned*)(lds + (bufoff) + ldsw + _i * 8192), 16, (int)(voff)[_i], so_, 0, 0); } while (0)
; #define PG8_LDA(dst, b, h) do { _Pragma("unroll") for (int m = 0; m < 4; ++m) _Pragma("unroll") for (int k = 0; k < 2; ++k) dst[m][k] = *(const PG8_LAS bf16x8*)(lds + PG8_SA(b, h) + aoff + m * 2048 + k * 1024); } while (0)
; #define PG8_LDB(dst, b, h) do { _Pragma("unroll") for (int n = 0; n < 2; ++n) _Pragma("unroll") for (int k = 0; k < 2; ++k) dst[n][k] = *(const PG8_LAS bf16x8*)(lds + PG8_SB(b, h) + boff + n * 2048 + k * 1024); } while (0)
; #define PG8_MMA(ai, bj, At, Bt) do { __builtin_amdgcn_s_setprio(1); _Pragma("unroll") for (int m = 0; m < 4; ++m) _Pragma("unroll") for (int n = 0; n < 2; ++n) _Pragma("unroll") for (int k = 0; k < 2; ++k) \
;         acc[ai][bj][m][n] = __builtin_amdgcn_mfma_f32_16x16x32_bf16(Bt[n][k], At[m][k], acc[ai][bj][m][n], 0, 0, 0); __builtin_amdgcn_s_setprio(0); } while (0)
; #define PG8_WAIT_V(n) asm volatile("s_waitcnt vmcnt(" #n ")" ::: "memory")
; #define PG8_WAIT_L(n) asm volatile("s_waitcnt lgkmcnt(" #n ")" ::: "memory")
; #define PG8_BAR __builtin_amdgcn_s_barrier()
; #define PG8_SCHED __builtin_amdgcn_sched_barrier(0)
; template <class Epi, class Sched, bool ALIGN_EPI = false, bool SP2 = false>
; __device__ __forceinline__ void gemm_phase(PG8_LAS unsigned char* lds, const Gemm g, const Sched& S, const Epi& E, int tid_in) {
;     ...
;             PG8_LDB(B0, 0, 0); PG8_LDB(B1, 0, 1); PG8_SCHED; PG8_LDA(At, 0, 0); PG8_STAGE(PG8_SA(1, 1), a1 + hstepA, voffA);
;             PG8_WAIT_V(8); PG8_WAIT_L(0); PG8_BAR; PG8_MMA(0, 0, At, B0); PG8_MMA(0, 1, At, B1); PG8_BAR; PG8_SCHED;
;             PG8_LDA(At, 0, 1); PG8_STAGE(PG8_SB(0, 0), b2, voffB); PG8_STAGE(PG8_SB(0, 1), b2 + hstepB, voffB); PG8_STAGE(PG8_SA(0, 0), a2, voffA);
;             PG8_WAIT_V(8); PG8_WAIT_L(0); PG8_BAR; PG8_MMA(1, 0, At, B0); PG8_MMA(1, 1, At, B1); PG8_BAR; PG8_SCHED;
.LBB0_1584:
	v_add_u32_e32 v133, 0x10000, v131
	ds_read_b128 v[134:137], v133
	ds_read_b128 v[138:141], v133 offset:1024
	ds_read_b128 v[142:145], v133 offset:2048
	ds_read_b128 v[146:149], v133 offset:3072
	v_add_u32_e32 v133, 0x14000, v131
	ds_read_b128 v[150:153], v133
	ds_read_b128 v[154:157], v133 offset:1024
	ds_read_b128 v[158:161], v133 offset:2048
	ds_read_b128 v[166:169], v133 offset:3072
	s_add_i32 s43, s38, s22
	s_add_i32 s42, s14, s22
	s_add_i32 s76, s12, s22
	s_addk_i32 s43, 0xff80
	s_sub_i32 s78, s43, 0x160000
	s_cmpk_eq_i32 s39, 0x54
	s_cselect_b32 s77, s16, s42
	s_mov_b32 m0, s68
	ds_read_b128 v[170:173], v132
	ds_read_b128 v[174:177], v132 offset:1024
	ds_read_b128 v[178:181], v132 offset:2048
	ds_read_b128 v[182:185], v132 offset:3072
	ds_read_b128 v[186:189], v132 offset:4096
	ds_read_b128 v[190:193], v132 offset:5120
	ds_read_b128 v[200:203], v132 offset:6144
	ds_read_b128 v[206:209], v132 offset:7168
	s_mov_b32 m0, s63
	s_nop 0
	buffer_load_dwordx4 v130, s[4:7], s78 offen lds
	s_mov_b32 m0, s68
	s_nop 0
	buffer_load_dwordx4 v0, s[4:7], s43 offen lds
	s_mov_b32 m0, s69
	s_nop 0
	buffer_load_dwordx4 v130, s[4:7], s43 offen lds
	s_waitcnt vmcnt(8)
	s_waitcnt lgkmcnt(0)
	s_setprio 1
	s_barrier
	v_mfma_f32_16x16x32_bf16 v[22:25], v[134:137], v[170:173], v[22:25]
	v_mfma_f32_16x16x32_bf16 v[14:17], v[142:145], v[170:173], v[14:17]
	v_mfma_f32_16x16x32_bf16 v[54:57], v[142:145], v[178:181], v[54:57]
	v_mfma_f32_16x16x32_bf16 v[74:77], v[134:137], v[178:181], v[74:77]
	v_mfma_f32_16x16x32_bf16 v[106:109], v[134:137], v[186:189], v[106:109]
	v_mfma_f32_16x16x32_bf16 v[102:105], v[142:145], v[186:189], v[102:105]
	v_mfma_f32_16x16x32_bf16 v[118:121], v[142:145], v[200:203], v[118:121]
	v_mfma_f32_16x16x32_bf16 v[122:125], v[134:137], v[200:203], v[122:125]
	v_mfma_f32_16x16x32_bf16 v[22:25], v[138:141], v[174:177], v[22:25]
	v_mfma_f32_16x16x32_bf16 v[14:17], v[146:149], v[174:177], v[14:17]
	v_mfma_f32_16x16x32_bf16 v[54:57], v[146:149], v[182:185], v[54:57]
	v_mfma_f32_16x16x32_bf16 v[74:77], v[138:141], v[182:185], v[74:77]
	v_mfma_f32_16x16x32_bf16 v[106:109], v[138:141], v[190:193], v[106:109]
	v_mfma_f32_16x16x32_bf16 v[102:105], v[146:149], v[190:193], v[102:105]
	v_mfma_f32_16x16x32_bf16 v[118:121], v[146:149], v[206:209], v[118:121]
	v_mfma_f32_16x16x32_bf16 v[122:125], v[138:141], v[206:209], v[122:125]
	v_mfma_f32_16x16x32_bf16 v[6:9], v[150:153], v[170:173], v[6:9]
	v_mfma_f32_16x16x32_bf16 v[18:21], v[158:161], v[170:173], v[18:21]
	v_mfma_f32_16x16x32_bf16 v[78:81], v[158:161], v[178:181], v[78:81]
	v_mfma_f32_16x16x32_bf16 v[50:53], v[150:153], v[178:181], v[50:53]
	v_mfma_f32_16x16x32_bf16 v[98:101], v[150:153], v[186:189], v[98:101]
	v_mfma_f32_16x16x32_bf16 v[110:113], v[158:161], v[186:189], v[110:113]
	v_mfma_f32_16x16x32_bf16 v[126:129], v[158:161], v[200:203], v[126:129]
	v_mfma_f32_16x16x32_bf16 v[114:117], v[150:153], v[200:203], v[114:117]
	v_mfma_f32_16x16x32_bf16 v[6:9], v[154:157], v[174:177], v[6:9]
	v_mfma_f32_16x16x32_bf16 v[18:21], v[166:169], v[174:177], v[18:21]
	v_mfma_f32_16x16x32_bf16 v[78:81], v[166:169], v[182:185], v[78:81]
	v_mfma_f32_16x16x32_bf16 v[50:53], v[154:157], v[182:185], v[50:53]
	v_mfma_f32_16x16x32_bf16 v[98:101], v[154:157], v[190:193], v[98:101]
	v_mfma_f32_16x16x32_bf16 v[110:113], v[166:169], v[190:193], v[110:113]
	v_mfma_f32_16x16x32_bf16 v[126:129], v[166:169], v[206:209], v[126:129]
	v_mfma_f32_16x16x32_bf16 v[114:117], v[154:157], v[206:209], v[114:117]
	s_barrier
	s_cselect_b32 s76, s20, s76
	s_mov_b32 m0, s26
	s_mov_b32 s42, s6
	s_mov_b32 s43, s7
	s_sub_i32 s76, s76, s40
	ds_read_b128 v[170:173], v132 offset:16384
	ds_read_b128 v[174:177], v132 offset:17408
	ds_read_b128 v[178:181], v132 offset:18432
	ds_read_b128 v[182:185], v132 offset:19456
	ds_read_b128 v[186:189], v132 offset:20480
	ds_read_b128 v[190:193], v132 offset:21504
	ds_read_b128 v[200:203], v132 offset:22528
	ds_read_b128 v[206:209], v132 offset:23552
	s_setprio 0
	buffer_load_dwordx4 v0, s[40:43], s76 offen lds
	s_mov_b32 m0, s44
	s_add_i32 s78, s76, 0x160000
	buffer_load_dwordx4 v130, s[40:43], s76 offen lds
	s_mov_b32 m0, s45
	s_sub_i32 s77, s77, s4
	buffer_load_dwordx4 v0, s[40:43], s78 offen lds
	s_mov_b32 m0, s46
	s_nop 0
	buffer_load_dwordx4 v130, s[40:43], s78 offen lds
	s_mov_b32 m0, s19
	s_nop 0
	buffer_load_dwordx4 v0, s[4:7], s77 offen lds
	s_waitcnt vmcnt(7)
	s_waitcnt lgkmcnt(0)
	s_setprio 1
	s_barrier
	v_mfma_f32_16x16x32_bf16 v[62:65], v[134:137], v[170:173], v[62:65]
	v_mfma_f32_16x16x32_bf16 v[46:49], v[142:145], v[170:173], v[46:49]
	v_mfma_f32_16x16x32_bf16 v[70:73], v[142:145], v[178:181], v[70:73]
	v_mfma_f32_16x16x32_bf16 v[82:85], v[134:137], v[178:181], v[82:85]
	v_mfma_f32_16x16x32_bf16 v[94:97], v[134:137], v[186:189], v[94:97]
	v_mfma_f32_16x16x32_bf16 v[90:93], v[142:145], v[186:189], v[90:93]
	v_mfma_f32_16x16x32_bf16 v[26:29], v[142:145], v[200:203], v[26:29]
	v_mfma_f32_16x16x32_bf16 v[38:41], v[134:137], v[200:203], v[38:41]
	v_mfma_f32_16x16x32_bf16 v[62:65], v[138:141], v[174:177], v[62:65]
	v_mfma_f32_16x16x32_bf16 v[46:49], v[146:149], v[174:177], v[46:49]
	v_mfma_f32_16x16x32_bf16 v[70:73], v[146:149], v[182:185], v[70:73]
	v_mfma_f32_16x16x32_bf16 v[82:85], v[138:141], v[182:185], v[82:85]
	v_mfma_f32_16x16x32_bf16 v[94:97], v[138:141], v[190:193], v[94:97]
	v_mfma_f32_16x16x32_bf16 v[90:93], v[146:149], v[190:193], v[90:93]
	v_mfma_f32_16x16x32_bf16 v[26:29], v[146:149], v[206:209], v[26:29]
	v_mfma_f32_16x16x32_bf16 v[38:41], v[138:141], v[206:209], v[38:41]
	v_mfma_f32_16x16x32_bf16 v[42:45], v[150:153], v[170:173], v[42:45]
	v_mfma_f32_16x16x32_bf16 v[30:33], v[158:161], v[170:173], v[30:33]
	v_mfma_f32_16x16x32_bf16 v[86:89], v[158:161], v[178:181], v[86:89]
	v_mfma_f32_16x16x32_bf16 v[66:69], v[150:153], v[178:181], v[66:69]
	v_mfma_f32_16x16x32_bf16 v[58:61], v[150:153], v[186:189], v[58:61]
	v_mfma_f32_16x16x32_bf16 v[34:37], v[158:161], v[186:189], v[34:37]
	v_mfma_f32_16x16x32_bf16 v[2:5], v[158:161], v[200:203], v[2:5]
	v_mfma_f32_16x16x32_bf16 v[10:13], v[150:153], v[200:203], v[10:13]
	v_mfma_f32_16x16x32_bf16 v[42:45], v[154:157], v[174:177], v[42:45]
	v_mfma_f32_16x16x32_bf16 v[30:33], v[166:169], v[174:177], v[30:33]
	v_mfma_f32_16x16x32_bf16 v[86:89], v[166:169], v[182:185], v[86:89]
	v_mfma_f32_16x16x32_bf16 v[66:69], v[154:157], v[182:185], v[66:69]
	v_mfma_f32_16x16x32_bf16 v[58:61], v[154:157], v[190:193], v[58:61]
	v_mfma_f32_16x16x32_bf16 v[34:37], v[166:169], v[190:193], v[34:37]
	v_mfma_f32_16x16x32_bf16 v[2:5], v[166:169], v[206:209], v[2:5]
	v_mfma_f32_16x16x32_bf16 v[10:13], v[154:157], v[206:209], v[10:13]
	s_barrier
; #define PG8_STAGE(bufoff, gbase, voff) do { const int so_ = (int)(unsigned)((const char*)(gbase) - base_##voff); _Pragma("unroll") for (int _i = 0; _i < 2; ++_i) \
;         __builtin_amdgcn_raw_ptr_buffer_load_lds(rs_##voff, (PG8_LAS unsigned*)(lds + (bufoff) + ldsw + _i * 8192), 16, (int)(voff)[_i], so_, 0, 0); } while (0)
; #define PG8_LDA(dst, b, h) do { _Pragma("unroll") for (int m = 0; m < 4; ++m) _Pragma("unroll") for (int k = 0; k < 2; ++k) dst[m][k] = *(const PG8_LAS bf16x8*)(lds + PG8_SA(b, h) + aoff + m * 2048 + k * 1024); } while (0)
; #define PG8_LDB(dst, b, h) do { _Pragma("unroll") for (int n = 0; n < 2; ++n) _Pragma("unroll") for (int k = 0; k < 2; ++k) dst[n][k] = *(const PG8_LAS bf16x8*)(lds + PG8_SB(b, h) + boff + n * 2048 + k * 1024); } while (0)
; #define PG8_MMA(ai, bj, At, Bt) do { __builtin_amdgcn_s_setprio(1); _Pragma("unroll") for (int m = 0; m < 4; ++m) _Pragma("unroll") for (int n = 0; n < 2; ++n) _Pragma("unroll") for (int k = 0; k < 2; ++k) \
;         acc[ai][bj][m][n] = __builtin_amdgcn_mfma_f32_16x16x32_bf16(Bt[n][k], At[m][k], acc[ai][bj][m][n], 0, 0, 0); __builtin_amdgcn_s_setprio(0); } while (0)
; #define PG8_WAIT_V(n) asm volatile("s_waitcnt vmcnt(" #n ")" ::: "memory")
; #define PG8_WAIT_L(n) asm volatile("s_waitcnt lgkmcnt(" #n ")" ::: "memory")
; #define PG8_BAR __builtin_amdgcn_s_barrier()
; #define PG8_SCHED __builtin_amdgcn_sched_barrier(0)
; template <class Epi, class Sched, bool ALIGN_EPI = false, bool SP2 = false>
; __device__ __forceinline__ void gemm_phase(PG8_LAS unsigned char* lds, const Gemm g, const Sched& S, const Epi& E, int tid_in) {
;     ...
;             PG8_WAIT_V(8); PG8_WAIT_L(0); PG8_BAR; PG8_MMA(1, 0, At, B0); PG8_MMA(1, 1, At, B1); PG8_BAR; PG8_SCHED;
;             PG8_LDB(B0, 1, 0); PG8_LDB(B1, 1, 1); PG8_SCHED; PG8_LDA(At, 1, 0); PG8_STAGE(PG8_SA(0, 1), a2 + hstepA, voffA);
;             PG8_WAIT_V(8); PG8_WAIT_L(0); PG8_BAR; PG8_MMA(0, 0, At, B0); PG8_MMA(0, 1, At, B1); PG8_BAR; PG8_SCHED;
;             PG8_LDA(At, 1, 1); PG8_STAGE(PG8_SB(1, 0), b3, voffB); PG8_STAGE(PG8_SB(1, 1), b3 + hstepB, voffB); PG8_STAGE(PG8_SA(1, 0), a3, voffA);
;             PG8_WAIT_V(8); PG8_WAIT_L(0); PG8_BAR; PG8_MMA(1, 0, At, B0); PG8_MMA(1, 1, At, B1); PG8_BAR; PG8_SCHED;
	v_add_u32_e32 v133, 0x18000, v131
	ds_read_b128 v[134:137], v133
	ds_read_b128 v[138:141], v133 offset:1024
	ds_read_b128 v[142:145], v133 offset:2048
	ds_read_b128 v[146:149], v133 offset:3072
	v_add_u32_e32 v133, 0x1c000, v131
	ds_read_b128 v[150:153], v133
	ds_read_b128 v[154:157], v133 offset:1024
	ds_read_b128 v[158:161], v133 offset:2048
	ds_read_b128 v[166:169], v133 offset:3072
	s_add_i32 s78, s77, 0x160000
	s_mov_b32 m0, s48
	ds_read_b128 v[170:173], v132 offset:32768
	ds_read_b128 v[174:177], v132 offset:33792
	ds_read_b128 v[178:181], v132 offset:34816
	ds_read_b128 v[182:185], v132 offset:35840
	ds_read_b128 v[186:189], v132 offset:36864
	ds_read_b128 v[190:193], v132 offset:37888
	ds_read_b128 v[200:203], v132 offset:38912
	ds_read_b128 v[206:209], v132 offset:39936
	s_setprio 0
	s_mov_b32 m0, s47
	s_nop 0
	buffer_load_dwordx4 v130, s[4:7], s77 offen lds
	s_mov_b32 m0, s48
	s_nop 0
	buffer_load_dwordx4 v0, s[4:7], s78 offen lds
	s_mov_b32 m0, s49
	s_nop 0
	buffer_load_dwordx4 v130, s[4:7], s78 offen lds
	s_waitcnt vmcnt(8)
	s_waitcnt lgkmcnt(0)
	s_setprio 1
	s_barrier
	v_mfma_f32_16x16x32_bf16 v[22:25], v[134:137], v[170:173], v[22:25]
	v_mfma_f32_16x16x32_bf16 v[14:17], v[142:145], v[170:173], v[14:17]
	v_mfma_f32_16x16x32_bf16 v[54:57], v[142:145], v[178:181], v[54:57]
	v_mfma_f32_16x16x32_bf16 v[74:77], v[134:137], v[178:181], v[74:77]
	v_mfma_f32_16x16x32_bf16 v[106:109], v[134:137], v[186:189], v[106:109]
	v_mfma_f32_16x16x32_bf16 v[102:105], v[142:145], v[186:189], v[102:105]
	v_mfma_f32_16x16x32_bf16 v[118:121], v[142:145], v[200:203], v[118:121]
	v_mfma_f32_16x16x32_bf16 v[122:125], v[134:137], v[200:203], v[122:125]
	v_mfma_f32_16x16x32_bf16 v[22:25], v[138:141], v[174:177], v[22:25]
	v_mfma_f32_16x16x32_bf16 v[14:17], v[146:149], v[174:177], v[14:17]
	v_mfma_f32_16x16x32_bf16 v[54:57], v[146:149], v[182:185], v[54:57]
	v_mfma_f32_16x16x32_bf16 v[74:77], v[138:141], v[182:185], v[74:77]
	v_mfma_f32_16x16x32_bf16 v[106:109], v[138:141], v[190:193], v[106:109]
	v_mfma_f32_16x16x32_bf16 v[102:105], v[146:149], v[190:193], v[102:105]
	v_mfma_f32_16x16x32_bf16 v[118:121], v[146:149], v[206:209], v[118:121]
	v_mfma_f32_16x16x32_bf16 v[122:125], v[138:141], v[206:209], v[122:125]
	v_mfma_f32_16x16x32_bf16 v[6:9], v[150:153], v[170:173], v[6:9]
	v_mfma_f32_16x16x32_bf16 v[18:21], v[158:161], v[170:173], v[18:21]
	v_mfma_f32_16x16x32_bf16 v[78:81], v[158:161], v[178:181], v[78:81]
	v_mfma_f32_16x16x32_bf16 v[50:53], v[150:153], v[178:181], v[50:53]
	v_mfma_f32_16x16x32_bf16 v[98:101], v[150:153], v[186:189], v[98:101]
	v_mfma_f32_16x16x32_bf16 v[110:113], v[158:161], v[186:189], v[110:113]
	v_mfma_f32_16x16x32_bf16 v[126:129], v[158:161], v[200:203], v[126:129]
	v_mfma_f32_16x16x32_bf16 v[114:117], v[150:153], v[200:203], v[114:117]
	v_mfma_f32_16x16x32_bf16 v[6:9], v[154:157], v[174:177], v[6:9]
	v_mfma_f32_16x16x32_bf16 v[18:21], v[166:169], v[174:177], v[18:21]
	v_mfma_f32_16x16x32_bf16 v[78:81], v[166:169], v[182:185], v[78:81]
	v_mfma_f32_16x16x32_bf16 v[50:53], v[154:157], v[182:185], v[50:53]
	v_mfma_f32_16x16x32_bf16 v[98:101], v[154:157], v[190:193], v[98:101]
	v_mfma_f32_16x16x32_bf16 v[110:113], v[166:169], v[190:193], v[110:113]
	v_mfma_f32_16x16x32_bf16 v[126:129], v[166:169], v[206:209], v[126:129]
	v_mfma_f32_16x16x32_bf16 v[114:117], v[154:157], v[206:209], v[114:117]
	s_barrier
	s_mov_b32 m0, s60
	s_add_i32 s78, s76, 0x80
	ds_read_b128 v[170:173], v132 offset:49152
	ds_read_b128 v[174:177], v132 offset:50176
	ds_read_b128 v[178:181], v132 offset:51200
	ds_read_b128 v[182:185], v132 offset:52224
	ds_read_b128 v[186:189], v132 offset:53248
	ds_read_b128 v[190:193], v132 offset:54272
	ds_read_b128 v[200:203], v132 offset:55296
	ds_read_b128 v[206:209], v132 offset:56320
	s_setprio 0
	buffer_load_dwordx4 v0, s[40:43], s78 offen lds
	s_mov_b32 m0, s61
	s_add_i32 s76, s76, 0x160080
	buffer_load_dwordx4 v130, s[40:43], s78 offen lds
	s_mov_b32 m0, s66
	s_addk_i32 s77, 0x80
	buffer_load_dwordx4 v0, s[40:43], s76 offen lds
	s_mov_b32 m0, s67
	s_nop 0
	buffer_load_dwordx4 v130, s[40:43], s76 offen lds
	s_mov_b32 m0, s62
	s_nop 0
	buffer_load_dwordx4 v0, s[4:7], s77 offen lds
	s_waitcnt vmcnt(7)
	s_waitcnt lgkmcnt(0)
	s_setprio 1
	s_barrier
;     static __device__ __forceinline__ bool last_of_chain(const Unit& u) { return (u.pn >> 3) == 2; }
; template <class Epi, class Sched, bool ALIGN_EPI = false, bool SP2 = false>
; __device__ __forceinline__ void gemm_phase(PG8_LAS unsigned char* lds, const Gemm g, const Sched& S, const Epi& E, int tid_in) {
;     ...
;             PG8_WAIT_V(8); PG8_WAIT_L(0); PG8_BAR; PG8_MMA(1, 0, At, B0); PG8_MMA(1, 1, At, B1); PG8_BAR; PG8_SCHED;
;             } else {
;             PG8_LDB(B0, 0, 0); PG8_SCHED; PG8_LDA(At, 0, 0); PG8_STAGE(PG8_SA(1, 1), a1 + hstepA, voffA);
;             PG8_WAIT_L(8); PG8_BAR; PG8_WAIT_L(0); PG8_MMA(0, 0, At, B0); PG8_BAR; PG8_SCHED;
;             PG8_LDB(B1, 0, 1); PG8_STAGE(PG8_SB(0, 0), b2, voffB);
;             PG8_BAR; PG8_WAIT_L(0); PG8_MMA(0, 1, At, B1); PG8_BAR;
;             PG8_LDA(At, 0, 1); PG8_STAGE(PG8_SA(0, 0), a2, voffA);
;             PG8_BAR; PG8_WAIT_L(0); PG8_MMA(1, 0, At, B0); PG8_BAR; PG8_SCHED;
;             PG8_STAGE(PG8_SB(0, 1), b2 + hstepB, voffB);
;             PG8_WAIT_V(6); PG8_BAR; PG8_MMA(1, 1, At, B1); PG8_BAR;
;             PG8_LDB(B0, 1, 0); PG8_SCHED; PG8_LDA(At, 1, 0); PG8_STAGE(PG8_SA(0, 1), a2 + hstepA, voffA);
;             PG8_WAIT_L(8); PG8_BAR; PG8_WAIT_L(0); PG8_MMA(0, 0, At, B0); PG8_BAR; PG8_SCHED;
;             PG8_LDB(B1, 1, 1); PG8_STAGE(PG8_SB(1, 0), b3, voffB);
;             PG8_BAR; PG8_WAIT_L(0); PG8_MMA(0, 1, At, B1); PG8_BAR;
;             PG8_LDA(At, 1, 1); PG8_STAGE(PG8_SA(1, 0), a3, voffA);
;             PG8_BAR; PG8_WAIT_L(0); PG8_MMA(1, 0, At, B0); PG8_BAR; PG8_SCHED;
;             PG8_STAGE(PG8_SB(1, 1), b3 + hstepB, voffB);
;             PG8_WAIT_V(6); PG8_BAR; PG8_MMA(1, 1, At, B1); PG8_BAR;
;             }
;         }
;         if constexpr (ALIGN_EPI) { if (wr == 0) PG8_BAR; }
;         if constexpr (!Epi::AFTER_DRAIN) { E(acc, cur, wr, wc, fr, fq); S.done(cur); }
;         if (!has_next) break;
;         bool zero_acc = true; if constexpr (Epi::CHAIN) zero_acc = Epi::last_of_chain(cur);
;         if (zero_acc) {
; #pragma unroll
;         for (int a = 0; a < 2; ++a)
; #pragma unroll
;             for (int b = 0; b < 2; ++b)
; #pragma unroll
;                 for (int m = 0; m < 4; ++m)
; #pragma unroll
;                     for (int n = 0; n < 2; ++n) acc[a][b][m][n] = (f32x4){0.f, 0.f, 0.f, 0.f};
;         }
;         cur = nxt; cA = nA; cB = nB; ++ui;
	v_mfma_f32_16x16x32_bf16 v[62:65], v[134:137], v[170:173], v[62:65]
	v_mfma_f32_16x16x32_bf16 v[46:49], v[142:145], v[170:173], v[46:49]
	v_mfma_f32_16x16x32_bf16 v[70:73], v[142:145], v[178:181], v[70:73]
	v_mfma_f32_16x16x32_bf16 v[82:85], v[134:137], v[178:181], v[82:85]
	v_mfma_f32_16x16x32_bf16 v[94:97], v[134:137], v[186:189], v[94:97]
	v_mfma_f32_16x16x32_bf16 v[90:93], v[142:145], v[186:189], v[90:93]
	v_mfma_f32_16x16x32_bf16 v[26:29], v[142:145], v[200:203], v[26:29]
	v_mfma_f32_16x16x32_bf16 v[38:41], v[134:137], v[200:203], v[38:41]
	v_mfma_f32_16x16x32_bf16 v[62:65], v[138:141], v[174:177], v[62:65]
	v_mfma_f32_16x16x32_bf16 v[46:49], v[146:149], v[174:177], v[46:49]
	v_mfma_f32_16x16x32_bf16 v[70:73], v[146:149], v[182:185], v[70:73]
	v_mfma_f32_16x16x32_bf16 v[82:85], v[138:141], v[182:185], v[82:85]
	v_mfma_f32_16x16x32_bf16 v[94:97], v[138:141], v[190:193], v[94:97]
	v_mfma_f32_16x16x32_bf16 v[90:93], v[146:149], v[190:193], v[90:93]
	v_mfma_f32_16x16x32_bf16 v[26:29], v[146:149], v[206:209], v[26:29]
	v_mfma_f32_16x16x32_bf16 v[38:41], v[138:141], v[206:209], v[38:41]
	v_mfma_f32_16x16x32_bf16 v[42:45], v[150:153], v[170:173], v[42:45]
	v_mfma_f32_16x16x32_bf16 v[30:33], v[158:161], v[170:173], v[30:33]
	v_mfma_f32_16x16x32_bf16 v[86:89], v[158:161], v[178:181], v[86:89]
	v_mfma_f32_16x16x32_bf16 v[66:69], v[150:153], v[178:181], v[66:69]
	v_mfma_f32_16x16x32_bf16 v[58:61], v[150:153], v[186:189], v[58:61]
	v_mfma_f32_16x16x32_bf16 v[34:37], v[158:161], v[186:189], v[34:37]
	v_mfma_f32_16x16x32_bf16 v[2:5], v[158:161], v[200:203], v[2:5]
	v_mfma_f32_16x16x32_bf16 v[10:13], v[150:153], v[200:203], v[10:13]
	v_mfma_f32_16x16x32_bf16 v[42:45], v[154:157], v[174:177], v[42:45]
	v_mfma_f32_16x16x32_bf16 v[30:33], v[166:169], v[174:177], v[30:33]
	v_mfma_f32_16x16x32_bf16 v[86:89], v[166:169], v[182:185], v[86:89]
	v_mfma_f32_16x16x32_bf16 v[66:69], v[154:157], v[182:185], v[66:69]
	v_mfma_f32_16x16x32_bf16 v[58:61], v[154:157], v[190:193], v[58:61]
	v_mfma_f32_16x16x32_bf16 v[34:37], v[166:169], v[190:193], v[34:37]
	v_mfma_f32_16x16x32_bf16 v[2:5], v[166:169], v[206:209], v[2:5]
	v_mfma_f32_16x16x32_bf16 v[10:13], v[154:157], v[206:209], v[10:13]
	s_barrier
	s_setprio 0
	s_add_i32 s39, s39, 2
	s_add_u32 s22, s22, 0x100
	s_addc_u32 s23, s23, 0
	s_cmpk_gt_u32 s39, 0x55
	s_cbranch_scc0 .LBB0_1584
	s_and_b64 vcc, exec, s[36:37]
	s_cbranch_vccnz .LBB0_1572
	v_mov_b32_e32 v2, 0
	s_mov_b32 s10, s73
	s_mov_b32 s25, s74
	s_mov_b64 s[12:13], s[20:21]
	s_mov_b64 s[14:15], s[16:17]
	s_mov_b32 s72, s75
	v_mov_b32_e32 v3, v2
	v_mov_b32_e32 v4, v2
	v_mov_b32_e32 v5, v2
	v_mov_b32_e32 v10, v2
	v_mov_b32_e32 v11, v2
	v_mov_b32_e32 v12, v2
	v_mov_b32_e32 v13, v2
	v_mov_b32_e32 v34, v2
	v_mov_b32_e32 v35, v2
	v_mov_b32_e32 v36, v2
	v_mov_b32_e32 v37, v2
	v_mov_b32_e32 v58, v2
	v_mov_b32_e32 v59, v2
	v_mov_b32_e32 v60, v2
	v_mov_b32_e32 v61, v2
	v_mov_b32_e32 v86, v2
	v_mov_b32_e32 v87, v2
	v_mov_b32_e32 v88, v2
	v_mov_b32_e32 v89, v2
	v_mov_b32_e32 v66, v2
	v_mov_b32_e32 v67, v2
	v_mov_b32_e32 v68, v2
	v_mov_b32_e32 v69, v2
	v_mov_b32_e32 v30, v2
	v_mov_b32_e32 v31, v2
	v_mov_b32_e32 v32, v2
	v_mov_b32_e32 v33, v2
	v_mov_b32_e32 v42, v2
	v_mov_b32_e32 v43, v2
	v_mov_b32_e32 v44, v2
	v_mov_b32_e32 v45, v2
	v_mov_b32_e32 v26, v2
	v_mov_b32_e32 v27, v2
	v_mov_b32_e32 v28, v2
	v_mov_b32_e32 v29, v2
	v_mov_b32_e32 v38, v2
	v_mov_b32_e32 v39, v2
	v_mov_b32_e32 v40, v2
	v_mov_b32_e32 v41, v2
	v_mov_b32_e32 v90, v2
	v_mov_b32_e32 v91, v2
	v_mov_b32_e32 v92, v2
	v_mov_b32_e32 v93, v2
	v_mov_b32_e32 v94, v2
	v_mov_b32_e32 v95, v2
	v_mov_b32_e32 v96, v2
	v_mov_b32_e32 v97, v2
	v_mov_b32_e32 v70, v2
	v_mov_b32_e32 v71, v2
	v_mov_b32_e32 v72, v2
	v_mov_b32_e32 v73, v2
	v_mov_b32_e32 v82, v2
	v_mov_b32_e32 v83, v2
	v_mov_b32_e32 v84, v2
	v_mov_b32_e32 v85, v2
	v_mov_b32_e32 v46, v2
	v_mov_b32_e32 v47, v2
	v_mov_b32_e32 v48, v2
	v_mov_b32_e32 v49, v2
	v_mov_b32_e32 v62, v2
	v_mov_b32_e32 v63, v2
	v_mov_b32_e32 v64, v2
	v_mov_b32_e32 v65, v2
	v_mov_b32_e32 v126, v2
	v_mov_b32_e32 v127, v2
	v_mov_b32_e32 v128, v2
	v_mov_b32_e32 v129, v2
	v_mov_b32_e32 v114, v2
	v_mov_b32_e32 v115, v2
	v_mov_b32_e32 v116, v2
	v_mov_b32_e32 v117, v2
	v_mov_b32_e32 v110, v2
	v_mov_b32_e32 v111, v2
	v_mov_b32_e32 v112, v2
	v_mov_b32_e32 v113, v2
	v_mov_b32_e32 v98, v2
	v_mov_b32_e32 v99, v2
	v_mov_b32_e32 v100, v2
	v_mov_b32_e32 v101, v2
	v_mov_b32_e32 v78, v2
	v_mov_b32_e32 v79, v2
	v_mov_b32_e32 v80, v2
	v_mov_b32_e32 v81, v2
	v_mov_b32_e32 v50, v2
	v_mov_b32_e32 v51, v2
	v_mov_b32_e32 v52, v2
	v_mov_b32_e32 v53, v2
	v_mov_b32_e32 v18, v2
	v_mov_b32_e32 v19, v2
	v_mov_b32_e32 v20, v2
	v_mov_b32_e32 v21, v2
	v_mov_b32_e32 v6, v2
	v_mov_b32_e32 v7, v2
	v_mov_b32_e32 v8, v2
	v_mov_b32_e32 v9, v2
	v_mov_b32_e32 v118, v2
	v_mov_b32_e32 v119, v2
	v_mov_b32_e32 v120, v2
	v_mov_b32_e32 v121, v2
	v_mov_b32_e32 v122, v2
	v_mov_b32_e32 v123, v2
	v_mov_b32_e32 v124, v2
	v_mov_b32_e32 v125, v2
	v_mov_b32_e32 v102, v2
	v_mov_b32_e32 v103, v2
	v_mov_b32_e32 v104, v2
	v_mov_b32_e32 v105, v2
	v_mov_b32_e32 v106, v2
	v_mov_b32_e32 v107, v2
	v_mov_b32_e32 v108, v2
	v_mov_b32_e32 v109, v2
	v_mov_b32_e32 v54, v2
	v_mov_b32_e32 v55, v2
	v_mov_b32_e32 v56, v2
	v_mov_b32_e32 v57, v2
	v_mov_b32_e32 v74, v2
	v_mov_b32_e32 v75, v2
	v_mov_b32_e32 v76, v2
	v_mov_b32_e32 v77, v2
	v_mov_b32_e32 v14, v2
	v_mov_b32_e32 v15, v2
	v_mov_b32_e32 v16, v2
	v_mov_b32_e32 v17, v2
	v_mov_b32_e32 v22, v2
	v_mov_b32_e32 v23, v2
	v_mov_b32_e32 v24, v2
	v_mov_b32_e32 v25, v2
	s_branch .LBB0_1572
